# speedup vs baseline: 1.0211x; 1.0003x over previous
.LBB0_110:
	ds_read_b128 v[140:143], v138
	ds_read_b128 v[144:147], v138 offset:1024
	ds_read_b128 v[148:151], v138 offset:2048
	ds_read_b128 v[152:155], v138 offset:3072
	ds_read_b128 v[156:159], v192
	ds_read_b128 v[160:163], v192 offset:1024
	ds_read_b128 v[194:197], v191
	ds_read_b128 v[198:201], v191 offset:1024
	ds_read_b128 v[202:205], v190
	ds_read_b128 v[206:209], v190 offset:1024
	ds_read_b128 v[210:213], v189
	ds_read_b128 v[214:217], v189 offset:1024
	s_waitcnt lgkmcnt(8)
	s_waitcnt vmcnt(10)
	s_barrier
	s_waitcnt lgkmcnt(0)
	s_setprio 1
	s_waitcnt lgkmcnt(0)
	v_mfma_f32_16x16x32_bf16 v[124:127], v[140:143], v[156:159], v[124:127]
	v_mfma_f32_16x16x32_bf16 v[120:123], v[148:151], v[156:159], v[120:123]
	v_mfma_f32_16x16x32_bf16 v[116:119], v[140:143], v[194:197], v[116:119]
	v_mfma_f32_16x16x32_bf16 v[112:115], v[148:151], v[194:197], v[112:115]
	v_mfma_f32_16x16x32_bf16 v[108:111], v[140:143], v[202:205], v[108:111]
	v_mfma_f32_16x16x32_bf16 v[104:107], v[148:151], v[202:205], v[104:107]
	v_mfma_f32_16x16x32_bf16 v[100:103], v[140:143], v[210:213], v[100:103]
	v_mfma_f32_16x16x32_bf16 v[96:99], v[148:151], v[210:213], v[96:99]
	v_mfma_f32_16x16x32_bf16 v[124:127], v[144:147], v[160:163], v[124:127]
	v_mfma_f32_16x16x32_bf16 v[120:123], v[152:155], v[160:163], v[120:123]
	v_mfma_f32_16x16x32_bf16 v[116:119], v[144:147], v[198:201], v[116:119]
	v_mfma_f32_16x16x32_bf16 v[112:115], v[152:155], v[198:201], v[112:115]
	v_mfma_f32_16x16x32_bf16 v[108:111], v[144:147], v[206:209], v[108:111]
	v_mfma_f32_16x16x32_bf16 v[104:107], v[152:155], v[206:209], v[104:107]
	v_mfma_f32_16x16x32_bf16 v[100:103], v[144:147], v[214:217], v[100:103]
	v_mfma_f32_16x16x32_bf16 v[96:99], v[152:155], v[214:217], v[96:99]
	s_setprio 0
	s_barrier
	v_readfirstlane_b32 s63, v188
	v_lshl_add_u64 v[234:235], s[66:67], 0, v[164:165]
	s_mov_b32 m0, s63
	v_readfirstlane_b32 s63, v187
	ds_read_b128 v[218:221], v135
	ds_read_b128 v[222:225], v135 offset:1024
	ds_read_b128 v[226:229], v135 offset:2048
	ds_read_b128 v[230:233], v135 offset:3072
	global_load_lds_dwordx4 v[234:235], off
	v_lshl_add_u64 v[236:237], v[234:235], 0, s[10:11]
	s_mov_b32 m0, s63
	s_nop 0
	global_load_lds_dwordx4 v[236:237], off
	s_waitcnt vmcnt(10)
	s_barrier
	s_waitcnt lgkmcnt(0)
	s_setprio 1
	s_waitcnt lgkmcnt(0)
	v_mfma_f32_16x16x32_bf16 v[92:95], v[218:221], v[156:159], v[92:95]
	v_mfma_f32_16x16x32_bf16 v[88:91], v[226:229], v[156:159], v[88:91]
	v_mfma_f32_16x16x32_bf16 v[84:87], v[218:221], v[194:197], v[84:87]
	v_mfma_f32_16x16x32_bf16 v[80:83], v[226:229], v[194:197], v[80:83]
	v_mfma_f32_16x16x32_bf16 v[76:79], v[218:221], v[202:205], v[76:79]
	v_mfma_f32_16x16x32_bf16 v[72:75], v[226:229], v[202:205], v[72:75]
	v_mfma_f32_16x16x32_bf16 v[68:71], v[218:221], v[210:213], v[68:71]
	v_mfma_f32_16x16x32_bf16 v[64:67], v[226:229], v[210:213], v[64:67]
	v_mfma_f32_16x16x32_bf16 v[92:95], v[222:225], v[160:163], v[92:95]
	v_mfma_f32_16x16x32_bf16 v[88:91], v[230:233], v[160:163], v[88:91]
	v_mfma_f32_16x16x32_bf16 v[84:87], v[222:225], v[198:201], v[84:87]
	v_mfma_f32_16x16x32_bf16 v[80:83], v[230:233], v[198:201], v[80:83]
	v_mfma_f32_16x16x32_bf16 v[76:79], v[222:225], v[206:209], v[76:79]
	v_mfma_f32_16x16x32_bf16 v[72:75], v[230:233], v[206:209], v[72:75]
	v_mfma_f32_16x16x32_bf16 v[68:71], v[222:225], v[214:217], v[68:71]
	v_mfma_f32_16x16x32_bf16 v[64:67], v[230:233], v[214:217], v[64:67]
	s_setprio 0
	v_readfirstlane_b32 s63, v169
	v_lshl_add_u64 v[236:237], v[128:129], 0, s[26:27]
	s_mov_b32 m0, s63
	v_readfirstlane_b32 s63, v186
	s_barrier
	ds_read_b128 v[156:159], v192 offset:16384
	ds_read_b128 v[160:163], v192 offset:17408
	ds_read_b128 v[194:197], v191 offset:16384
	ds_read_b128 v[198:201], v191 offset:17408
	ds_read_b128 v[202:205], v190 offset:16384
	ds_read_b128 v[206:209], v190 offset:17408
	ds_read_b128 v[210:213], v189 offset:16384
	ds_read_b128 v[214:217], v189 offset:17408
	global_load_lds_dwordx4 v[236:237], off
	v_lshl_add_u64 v[236:237], v[128:129], 0, s[28:29]
	s_mov_b32 m0, s63
	s_nop 0
	global_load_lds_dwordx4 v[236:237], off
	s_barrier
	s_waitcnt lgkmcnt(0)
	s_setprio 1
	s_waitcnt lgkmcnt(0)
	v_mfma_f32_16x16x32_bf16 v[60:63], v[140:143], v[156:159], v[60:63]
	v_mfma_f32_16x16x32_bf16 v[56:59], v[148:151], v[156:159], v[56:59]
	v_mfma_f32_16x16x32_bf16 v[52:55], v[140:143], v[194:197], v[52:55]
	v_mfma_f32_16x16x32_bf16 v[48:51], v[148:151], v[194:197], v[48:51]
	v_mfma_f32_16x16x32_bf16 v[44:47], v[140:143], v[202:205], v[44:47]
	v_mfma_f32_16x16x32_bf16 v[40:43], v[148:151], v[202:205], v[40:43]
	v_mfma_f32_16x16x32_bf16 v[36:39], v[140:143], v[210:213], v[36:39]
	v_mfma_f32_16x16x32_bf16 v[32:35], v[148:151], v[210:213], v[32:35]
	v_mfma_f32_16x16x32_bf16 v[60:63], v[144:147], v[160:163], v[60:63]
	v_mfma_f32_16x16x32_bf16 v[56:59], v[152:155], v[160:163], v[56:59]
	v_mfma_f32_16x16x32_bf16 v[52:55], v[144:147], v[198:201], v[52:55]
	v_mfma_f32_16x16x32_bf16 v[48:51], v[152:155], v[198:201], v[48:51]
	v_mfma_f32_16x16x32_bf16 v[44:47], v[144:147], v[206:209], v[44:47]
	v_mfma_f32_16x16x32_bf16 v[40:43], v[152:155], v[206:209], v[40:43]
	v_mfma_f32_16x16x32_bf16 v[36:39], v[144:147], v[214:217], v[36:39]
	v_mfma_f32_16x16x32_bf16 v[32:35], v[152:155], v[214:217], v[32:35]
	s_setprio 0
	s_barrier
	v_readfirstlane_b32 s63, v185
	v_lshl_add_u64 v[140:141], v[234:235], 0, s[30:31]
	s_mov_b32 m0, s63
	v_readfirstlane_b32 s63, v184
	global_load_lds_dwordx4 v[140:141], off
	v_lshl_add_u64 v[140:141], v[234:235], 0, s[34:35]
	s_mov_b32 m0, s63
	s_nop 0
	global_load_lds_dwordx4 v[140:141], off
	v_readfirstlane_b32 s63, v183
	v_lshl_add_u64 v[142:143], v[128:129], 0, s[40:41]
	s_mov_b32 m0, s63
	v_readfirstlane_b32 s63, v182
	global_load_lds_dwordx4 v[142:143], off
	s_mov_b32 m0, s63
	s_nop 0
	global_load_lds_dwordx4 v[128:129], off
	s_waitcnt vmcnt(12)
	s_barrier
	s_setprio 1
	v_mfma_f32_16x16x32_bf16 v[28:31], v[218:221], v[156:159], v[28:31]
	v_mfma_f32_16x16x32_bf16 v[24:27], v[226:229], v[156:159], v[24:27]
	v_mfma_f32_16x16x32_bf16 v[20:23], v[218:221], v[194:197], v[20:23]
	v_mfma_f32_16x16x32_bf16 v[16:19], v[226:229], v[194:197], v[16:19]
	v_mfma_f32_16x16x32_bf16 v[12:15], v[218:221], v[202:205], v[12:15]
	v_mfma_f32_16x16x32_bf16 v[8:11], v[226:229], v[202:205], v[8:11]
	v_mfma_f32_16x16x32_bf16 v[4:7], v[218:221], v[210:213], v[4:7]
	v_mfma_f32_16x16x32_bf16 v[0:3], v[226:229], v[210:213], v[0:3]
	v_mfma_f32_16x16x32_bf16 v[28:31], v[222:225], v[160:163], v[28:31]
	v_mfma_f32_16x16x32_bf16 v[24:27], v[230:233], v[160:163], v[24:27]
	v_mfma_f32_16x16x32_bf16 v[20:23], v[222:225], v[198:201], v[20:23]
	v_mfma_f32_16x16x32_bf16 v[16:19], v[230:233], v[198:201], v[16:19]
	v_mfma_f32_16x16x32_bf16 v[12:15], v[222:225], v[206:209], v[12:15]
	v_mfma_f32_16x16x32_bf16 v[8:11], v[230:233], v[206:209], v[8:11]
	v_mfma_f32_16x16x32_bf16 v[4:7], v[222:225], v[214:217], v[4:7]
	v_mfma_f32_16x16x32_bf16 v[0:3], v[230:233], v[214:217], v[0:3]
	s_setprio 0
	s_barrier
	ds_read_b128 v[140:143], v130
	ds_read_b128 v[144:147], v130 offset:1024
	ds_read_b128 v[148:151], v130 offset:2048
	ds_read_b128 v[152:155], v130 offset:3072
	ds_read_b128 v[156:159], v192 offset:32768
	ds_read_b128 v[160:163], v192 offset:33792
	ds_read_b128 v[194:197], v191 offset:32768
	ds_read_b128 v[198:201], v191 offset:33792
	ds_read_b128 v[202:205], v190 offset:32768
	ds_read_b128 v[206:209], v190 offset:33792
	ds_read_b128 v[210:213], v189 offset:32768
	ds_read_b128 v[214:217], v189 offset:33792
	s_waitcnt lgkmcnt(8)
	s_waitcnt vmcnt(10)
	s_barrier
	s_waitcnt lgkmcnt(0)
	s_setprio 1
	s_waitcnt lgkmcnt(0)
	v_mfma_f32_16x16x32_bf16 v[124:127], v[140:143], v[156:159], v[124:127]
	v_mfma_f32_16x16x32_bf16 v[120:123], v[148:151], v[156:159], v[120:123]
	v_mfma_f32_16x16x32_bf16 v[116:119], v[140:143], v[194:197], v[116:119]
	v_mfma_f32_16x16x32_bf16 v[112:115], v[148:151], v[194:197], v[112:115]
	v_mfma_f32_16x16x32_bf16 v[108:111], v[140:143], v[202:205], v[108:111]
	v_mfma_f32_16x16x32_bf16 v[104:107], v[148:151], v[202:205], v[104:107]
	v_mfma_f32_16x16x32_bf16 v[100:103], v[140:143], v[210:213], v[100:103]
	v_mfma_f32_16x16x32_bf16 v[96:99], v[148:151], v[210:213], v[96:99]
	v_mfma_f32_16x16x32_bf16 v[124:127], v[144:147], v[160:163], v[124:127]
	v_mfma_f32_16x16x32_bf16 v[120:123], v[152:155], v[160:163], v[120:123]
	v_mfma_f32_16x16x32_bf16 v[116:119], v[144:147], v[198:201], v[116:119]
	v_mfma_f32_16x16x32_bf16 v[112:115], v[152:155], v[198:201], v[112:115]
	v_mfma_f32_16x16x32_bf16 v[108:111], v[144:147], v[206:209], v[108:111]
	v_mfma_f32_16x16x32_bf16 v[104:107], v[152:155], v[206:209], v[104:107]
	v_mfma_f32_16x16x32_bf16 v[100:103], v[144:147], v[214:217], v[100:103]
	v_mfma_f32_16x16x32_bf16 v[96:99], v[152:155], v[214:217], v[96:99]
	s_setprio 0
	s_barrier
	v_readfirstlane_b32 s63, v181
	v_lshl_add_u64 v[234:235], s[64:65], 0, v[164:165]
	s_mov_b32 m0, s63
	v_readfirstlane_b32 s63, v180
	ds_read_b128 v[218:221], v132
	ds_read_b128 v[222:225], v132 offset:1024
	ds_read_b128 v[226:229], v132 offset:2048
	ds_read_b128 v[230:233], v132 offset:3072
	global_load_lds_dwordx4 v[234:235], off
	v_lshl_add_u64 v[236:237], v[234:235], 0, s[10:11]
	s_mov_b32 m0, s63
	s_nop 0
	global_load_lds_dwordx4 v[236:237], off
	s_waitcnt vmcnt(10)
	s_barrier
	s_waitcnt lgkmcnt(0)
	s_setprio 1
	s_waitcnt lgkmcnt(0)
	v_mfma_f32_16x16x32_bf16 v[92:95], v[218:221], v[156:159], v[92:95]
	v_mfma_f32_16x16x32_bf16 v[88:91], v[226:229], v[156:159], v[88:91]
	v_mfma_f32_16x16x32_bf16 v[84:87], v[218:221], v[194:197], v[84:87]
	v_mfma_f32_16x16x32_bf16 v[80:83], v[226:229], v[194:197], v[80:83]
	v_mfma_f32_16x16x32_bf16 v[76:79], v[218:221], v[202:205], v[76:79]
	v_mfma_f32_16x16x32_bf16 v[72:75], v[226:229], v[202:205], v[72:75]
	v_mfma_f32_16x16x32_bf16 v[68:71], v[218:221], v[210:213], v[68:71]
	v_mfma_f32_16x16x32_bf16 v[64:67], v[226:229], v[210:213], v[64:67]
	v_mfma_f32_16x16x32_bf16 v[92:95], v[222:225], v[160:163], v[92:95]
	v_mfma_f32_16x16x32_bf16 v[88:91], v[230:233], v[160:163], v[88:91]
	v_mfma_f32_16x16x32_bf16 v[84:87], v[222:225], v[198:201], v[84:87]
	v_mfma_f32_16x16x32_bf16 v[80:83], v[230:233], v[198:201], v[80:83]
	v_mfma_f32_16x16x32_bf16 v[76:79], v[222:225], v[206:209], v[76:79]
	v_mfma_f32_16x16x32_bf16 v[72:75], v[230:233], v[206:209], v[72:75]
	v_mfma_f32_16x16x32_bf16 v[68:71], v[222:225], v[214:217], v[68:71]
	v_mfma_f32_16x16x32_bf16 v[64:67], v[230:233], v[214:217], v[64:67]
	s_setprio 0
	v_readfirstlane_b32 s63, v179
	v_lshl_add_u64 v[236:237], v[128:129], 0, s[44:45]
	s_mov_b32 m0, s63
	v_readfirstlane_b32 s63, v177
	s_barrier
	ds_read_b128 v[156:159], v192 offset:49152
	ds_read_b128 v[160:163], v192 offset:50176
	ds_read_b128 v[194:197], v191 offset:49152
	ds_read_b128 v[198:201], v191 offset:50176
	ds_read_b128 v[202:205], v190 offset:49152
	ds_read_b128 v[206:209], v190 offset:50176
	ds_read_b128 v[210:213], v189 offset:49152
	ds_read_b128 v[214:217], v189 offset:50176
	global_load_lds_dwordx4 v[236:237], off
	v_lshl_add_u64 v[236:237], v[128:129], 0, s[46:47]
	s_mov_b32 m0, s63
	s_nop 0
	global_load_lds_dwordx4 v[236:237], off
	s_barrier
	s_waitcnt lgkmcnt(0)
	s_setprio 1
	s_waitcnt lgkmcnt(0)
	v_mfma_f32_16x16x32_bf16 v[60:63], v[140:143], v[156:159], v[60:63]
	v_mfma_f32_16x16x32_bf16 v[56:59], v[148:151], v[156:159], v[56:59]
	v_mfma_f32_16x16x32_bf16 v[52:55], v[140:143], v[194:197], v[52:55]
	v_mfma_f32_16x16x32_bf16 v[48:51], v[148:151], v[194:197], v[48:51]
	v_mfma_f32_16x16x32_bf16 v[44:47], v[140:143], v[202:205], v[44:47]
	v_mfma_f32_16x16x32_bf16 v[40:43], v[148:151], v[202:205], v[40:43]
	v_mfma_f32_16x16x32_bf16 v[36:39], v[140:143], v[210:213], v[36:39]
	v_mfma_f32_16x16x32_bf16 v[32:35], v[148:151], v[210:213], v[32:35]
	v_mfma_f32_16x16x32_bf16 v[60:63], v[144:147], v[160:163], v[60:63]
	v_mfma_f32_16x16x32_bf16 v[56:59], v[152:155], v[160:163], v[56:59]
	v_mfma_f32_16x16x32_bf16 v[52:55], v[144:147], v[198:201], v[52:55]
	v_mfma_f32_16x16x32_bf16 v[48:51], v[152:155], v[198:201], v[48:51]
	v_mfma_f32_16x16x32_bf16 v[44:47], v[144:147], v[206:209], v[44:47]
	v_mfma_f32_16x16x32_bf16 v[40:43], v[152:155], v[206:209], v[40:43]
	v_mfma_f32_16x16x32_bf16 v[36:39], v[144:147], v[214:217], v[36:39]
	v_mfma_f32_16x16x32_bf16 v[32:35], v[152:155], v[214:217], v[32:35]
	s_setprio 0
	s_barrier
	v_readfirstlane_b32 s63, v175
	v_lshl_add_u64 v[140:141], v[234:235], 0, s[30:31]
	s_mov_b32 m0, s63
	v_readfirstlane_b32 s63, v173
	global_load_lds_dwordx4 v[140:141], off
	v_lshl_add_u64 v[140:141], v[234:235], 0, s[34:35]
	s_mov_b32 m0, s63
	s_nop 0
	global_load_lds_dwordx4 v[140:141], off
	v_lshl_add_u64 v[128:129], v[128:129], 0, s[56:57]
	v_readfirstlane_b32 s63, v137
	v_lshl_add_u64 v[142:143], v[128:129], 0, s[22:23]
	s_mov_b32 m0, s63
	v_readfirstlane_b32 s63, v136
	global_load_lds_dwordx4 v[142:143], off
	v_lshl_add_u64 v[142:143], v[128:129], 0, s[24:25]
	s_mov_b32 m0, s63
	s_nop 0
	global_load_lds_dwordx4 v[142:143], off
	s_waitcnt vmcnt(12)
	s_barrier
	s_setprio 1
	v_mfma_f32_16x16x32_bf16 v[28:31], v[218:221], v[156:159], v[28:31]
	v_mfma_f32_16x16x32_bf16 v[24:27], v[226:229], v[156:159], v[24:27]
	v_mfma_f32_16x16x32_bf16 v[20:23], v[218:221], v[194:197], v[20:23]
	v_mfma_f32_16x16x32_bf16 v[16:19], v[226:229], v[194:197], v[16:19]
	v_mfma_f32_16x16x32_bf16 v[12:15], v[218:221], v[202:205], v[12:15]
	v_mfma_f32_16x16x32_bf16 v[8:11], v[226:229], v[202:205], v[8:11]
	v_mfma_f32_16x16x32_bf16 v[4:7], v[218:221], v[210:213], v[4:7]
	v_mfma_f32_16x16x32_bf16 v[0:3], v[226:229], v[210:213], v[0:3]
	v_mfma_f32_16x16x32_bf16 v[28:31], v[222:225], v[160:163], v[28:31]
	v_mfma_f32_16x16x32_bf16 v[24:27], v[230:233], v[160:163], v[24:27]
	v_mfma_f32_16x16x32_bf16 v[20:23], v[222:225], v[198:201], v[20:23]
	v_mfma_f32_16x16x32_bf16 v[16:19], v[230:233], v[198:201], v[16:19]
	v_mfma_f32_16x16x32_bf16 v[12:15], v[222:225], v[206:209], v[12:15]
	v_mfma_f32_16x16x32_bf16 v[8:11], v[230:233], v[206:209], v[8:11]
	v_mfma_f32_16x16x32_bf16 v[4:7], v[222:225], v[214:217], v[4:7]
	v_mfma_f32_16x16x32_bf16 v[0:3], v[230:233], v[214:217], v[0:3]
	s_setprio 0
	s_add_i32 s4, s4, 2
	s_add_u32 s64, s64, s68
	s_addc_u32 s65, s65, s69
	s_add_u32 s66, s66, s68
	s_addc_u32 s67, s67, s69
	s_cmp_lt_u32 s4, 28
	s_barrier
	s_cbranch_scc1 .LBB0_110
	s_lshl_b32 s4, s70, 11
	s_or_b32 s64, s71, s4
	s_or_b32 s66, s64, 0x80
	v_lshlrev_b32_e32 v128, 3, v131
	v_lshlrev_b32_e32 v129, 5, v131
	s_ashr_i32 s67, s66, 31
	v_and_b32_e32 v128, 0xffff0, v128
	v_and_b32_e32 v129, 32, v129
	s_lshl_b64 s[66:67], s[66:67], 12
	v_add_u32_e32 v129, v129, v134
	v_add_lshl_u32 v128, v133, v128, 12
	s_add_u32 s66, s54, s66
	v_lshl_add_u32 v164, v129, 1, v128
	s_addc_u32 s67, s55, s67
	v_lshl_add_u64 v[128:129], s[66:67], 0, v[164:165]
	v_readfirstlane_b32 s4, v137
	ds_read_b128 v[140:143], v138
	ds_read_b128 v[144:147], v138 offset:1024
	ds_read_b128 v[148:151], v138 offset:2048
	ds_read_b128 v[152:155], v138 offset:3072
	ds_read_b128 v[156:159], v192
	ds_read_b128 v[160:163], v192 offset:1024
	ds_read_b128 v[194:197], v191
	ds_read_b128 v[198:201], v191 offset:1024
	ds_read_b128 v[202:205], v190
	ds_read_b128 v[206:209], v190 offset:1024
	ds_read_b128 v[210:213], v189
	ds_read_b128 v[214:217], v189 offset:1024
	v_lshl_add_u64 v[138:139], v[128:129], 0, s[58:59]
	s_mov_b32 m0, s4
	v_readfirstlane_b32 s4, v136
	global_load_lds_dwordx4 v[138:139], off
	v_lshl_add_u64 v[128:129], v[128:129], 0, s[60:61]
	s_mov_b32 m0, s4
	s_ashr_i32 s65, s64, 31
	global_load_lds_dwordx4 v[128:129], off
	s_waitcnt vmcnt(10)
	s_barrier
	s_waitcnt lgkmcnt(0)
	s_setprio 1
	s_waitcnt lgkmcnt(0)
	v_mfma_f32_16x16x32_bf16 v[124:127], v[140:143], v[156:159], v[124:127]
	v_mfma_f32_16x16x32_bf16 v[120:123], v[148:151], v[156:159], v[120:123]
	v_mfma_f32_16x16x32_bf16 v[116:119], v[140:143], v[194:197], v[116:119]
	v_mfma_f32_16x16x32_bf16 v[112:115], v[148:151], v[194:197], v[112:115]
	v_mfma_f32_16x16x32_bf16 v[108:111], v[140:143], v[202:205], v[108:111]
	v_mfma_f32_16x16x32_bf16 v[104:107], v[148:151], v[202:205], v[104:107]
	v_mfma_f32_16x16x32_bf16 v[100:103], v[140:143], v[210:213], v[100:103]
	v_mfma_f32_16x16x32_bf16 v[96:99], v[148:151], v[210:213], v[96:99]
	v_mfma_f32_16x16x32_bf16 v[124:127], v[144:147], v[160:163], v[124:127]
	v_mfma_f32_16x16x32_bf16 v[120:123], v[152:155], v[160:163], v[120:123]
	v_mfma_f32_16x16x32_bf16 v[116:119], v[144:147], v[198:201], v[116:119]
	v_mfma_f32_16x16x32_bf16 v[112:115], v[152:155], v[198:201], v[112:115]
	v_mfma_f32_16x16x32_bf16 v[108:111], v[144:147], v[206:209], v[108:111]
	v_mfma_f32_16x16x32_bf16 v[104:107], v[152:155], v[206:209], v[104:107]
	v_mfma_f32_16x16x32_bf16 v[100:103], v[144:147], v[214:217], v[100:103]
	v_mfma_f32_16x16x32_bf16 v[96:99], v[152:155], v[214:217], v[96:99]
	s_setprio 0
	s_barrier
	ds_read_b128 v[136:139], v135
	ds_read_b128 v[218:221], v135 offset:1024
	ds_read_b128 v[222:225], v135 offset:2048
	ds_read_b128 v[226:229], v135 offset:3072
	s_barrier
	s_waitcnt lgkmcnt(0)
	s_setprio 1
	s_waitcnt lgkmcnt(0)
	v_mfma_f32_16x16x32_bf16 v[92:95], v[136:139], v[156:159], v[92:95]
	v_mfma_f32_16x16x32_bf16 v[88:91], v[222:225], v[156:159], v[88:91]
	v_mfma_f32_16x16x32_bf16 v[84:87], v[136:139], v[194:197], v[84:87]
	v_mfma_f32_16x16x32_bf16 v[80:83], v[222:225], v[194:197], v[80:83]
	v_mfma_f32_16x16x32_bf16 v[76:79], v[136:139], v[202:205], v[76:79]
	v_mfma_f32_16x16x32_bf16 v[72:75], v[222:225], v[202:205], v[72:75]
	v_mfma_f32_16x16x32_bf16 v[68:71], v[136:139], v[210:213], v[68:71]
	v_mfma_f32_16x16x32_bf16 v[64:67], v[222:225], v[210:213], v[64:67]
	v_mfma_f32_16x16x32_bf16 v[156:159], v[218:221], v[160:163], v[92:95]
	v_mfma_f32_16x16x32_bf16 v[160:163], v[226:229], v[160:163], v[88:91]
	v_mfma_f32_16x16x32_bf16 v[194:197], v[218:221], v[198:201], v[84:87]
	v_mfma_f32_16x16x32_bf16 v[198:201], v[226:229], v[198:201], v[80:83]
	v_mfma_f32_16x16x32_bf16 v[202:205], v[218:221], v[206:209], v[76:79]
	v_mfma_f32_16x16x32_bf16 v[206:209], v[226:229], v[206:209], v[72:75]
	v_mfma_f32_16x16x32_bf16 v[210:213], v[218:221], v[214:217], v[68:71]
	v_mfma_f32_16x16x32_bf16 v[214:217], v[226:229], v[214:217], v[64:67]
	s_setprio 0
	s_barrier
	s_nop 0
	ds_read_b128 v[64:67], v192 offset:16384
	ds_read_b128 v[68:71], v192 offset:17408
	ds_read_b128 v[72:75], v191 offset:16384
	ds_read_b128 v[76:79], v191 offset:17408
	ds_read_b128 v[80:83], v190 offset:16384
	ds_read_b128 v[84:87], v190 offset:17408
	ds_read_b128 v[88:91], v189 offset:16384
	ds_read_b128 v[92:95], v189 offset:17408
	s_waitcnt vmcnt(4)
	s_barrier
	s_waitcnt lgkmcnt(0)
	s_setprio 1
	s_waitcnt lgkmcnt(0)
	v_mfma_f32_16x16x32_bf16 v[60:63], v[140:143], v[64:67], v[60:63]
	v_mfma_f32_16x16x32_bf16 v[56:59], v[148:151], v[64:67], v[56:59]
	v_mfma_f32_16x16x32_bf16 v[52:55], v[140:143], v[72:75], v[52:55]
	v_mfma_f32_16x16x32_bf16 v[48:51], v[148:151], v[72:75], v[48:51]
	v_mfma_f32_16x16x32_bf16 v[230:233], v[140:143], v[80:83], v[44:47]
	v_mfma_f32_16x16x32_bf16 v[234:237], v[148:151], v[80:83], v[40:43]
	v_mfma_f32_16x16x32_bf16 v[140:143], v[140:143], v[88:91], v[36:39]
	v_mfma_f32_16x16x32_bf16 v[148:151], v[148:151], v[88:91], v[32:35]
	v_mfma_f32_16x16x32_bf16 v[32:35], v[144:147], v[68:71], v[60:63]
	v_mfma_f32_16x16x32_bf16 v[36:39], v[152:155], v[68:71], v[56:59]
	v_mfma_f32_16x16x32_bf16 v[40:43], v[144:147], v[76:79], v[52:55]
	v_mfma_f32_16x16x32_bf16 v[44:47], v[152:155], v[76:79], v[48:51]
	v_mfma_f32_16x16x32_bf16 v[48:51], v[144:147], v[84:87], v[230:233]
	v_mfma_f32_16x16x32_bf16 v[52:55], v[152:155], v[84:87], v[234:237]
	v_mfma_f32_16x16x32_bf16 v[56:59], v[144:147], v[92:95], v[140:143]
	v_mfma_f32_16x16x32_bf16 v[60:63], v[152:155], v[92:95], v[148:151]
	s_setprio 0
	s_setprio 1
	v_mfma_f32_16x16x32_bf16 v[28:31], v[136:139], v[64:67], v[28:31]
	v_mfma_f32_16x16x32_bf16 v[24:27], v[222:225], v[64:67], v[24:27]
	v_mfma_f32_16x16x32_bf16 v[20:23], v[136:139], v[72:75], v[20:23]
	v_mfma_f32_16x16x32_bf16 v[64:67], v[222:225], v[72:75], v[16:19]
	v_mfma_f32_16x16x32_bf16 v[12:15], v[136:139], v[80:83], v[12:15]
	v_mfma_f32_16x16x32_bf16 v[8:11], v[222:225], v[80:83], v[8:11]
	v_mfma_f32_16x16x32_bf16 v[72:75], v[136:139], v[88:91], v[4:7]
	v_mfma_f32_16x16x32_bf16 v[80:83], v[222:225], v[88:91], v[0:3]
	v_mfma_f32_16x16x32_bf16 v[0:3], v[218:221], v[68:71], v[28:31]
	v_mfma_f32_16x16x32_bf16 v[4:7], v[226:229], v[68:71], v[24:27]
	v_mfma_f32_16x16x32_bf16 v[16:19], v[218:221], v[76:79], v[20:23]
	v_mfma_f32_16x16x32_bf16 v[20:23], v[226:229], v[76:79], v[64:67]
	v_mfma_f32_16x16x32_bf16 v[64:67], v[218:221], v[84:87], v[12:15]
	v_mfma_f32_16x16x32_bf16 v[68:71], v[226:229], v[84:87], v[8:11]
	v_mfma_f32_16x16x32_bf16 v[72:75], v[218:221], v[92:95], v[72:75]
	v_mfma_f32_16x16x32_bf16 v[76:79], v[226:229], v[92:95], v[80:83]
	s_setprio 0
	s_barrier
	ds_read_b128 v[12:15], v130
	ds_read_b128 v[8:11], v130 offset:1024
	ds_read_b128 v[24:27], v130 offset:2048
	ds_read_b128 v[80:83], v130 offset:3072
	ds_read_b128 v[140:143], v192 offset:32768
	ds_read_b128 v[148:151], v192 offset:33792
	ds_read_b128 v[218:221], v191 offset:32768
	ds_read_b128 v[222:225], v191 offset:33792
	ds_read_b128 v[226:229], v190 offset:32768
	ds_read_b128 v[230:233], v190 offset:33792
	ds_read_b128 v[234:237], v189 offset:32768
	ds_read_b128 v[238:241], v189 offset:33792
	s_waitcnt vmcnt(2)
	s_barrier
	s_waitcnt lgkmcnt(0)
	s_setprio 1
	s_waitcnt lgkmcnt(0)
	v_mfma_f32_16x16x32_bf16 v[28:31], v[12:15], v[140:143], v[124:127]
	v_mfma_f32_16x16x32_bf16 v[84:87], v[24:27], v[140:143], v[120:123]
	v_mfma_f32_16x16x32_bf16 v[88:91], v[12:15], v[218:221], v[116:119]
	v_mfma_f32_16x16x32_bf16 v[92:95], v[24:27], v[218:221], v[112:115]
	v_mfma_f32_16x16x32_bf16 v[108:111], v[12:15], v[226:229], v[108:111]
	v_mfma_f32_16x16x32_bf16 v[104:107], v[24:27], v[226:229], v[104:107]
	v_mfma_f32_16x16x32_bf16 v[100:103], v[12:15], v[234:237], v[100:103]
	v_mfma_f32_16x16x32_bf16 v[96:99], v[24:27], v[234:237], v[96:99]
	v_mfma_f32_16x16x32_bf16 v[152:155], v[8:11], v[148:151], v[28:31]
	v_mfma_f32_16x16x32_bf16 v[144:147], v[80:83], v[148:151], v[84:87]
	v_mfma_f32_16x16x32_bf16 v[136:139], v[8:11], v[222:225], v[88:91]
	v_mfma_f32_16x16x32_bf16 v[128:131], v[80:83], v[222:225], v[92:95]
	v_mfma_f32_16x16x32_bf16 v[120:123], v[8:11], v[230:233], v[108:111]
	v_mfma_f32_16x16x32_bf16 v[112:115], v[80:83], v[230:233], v[104:107]
	v_mfma_f32_16x16x32_bf16 v[104:107], v[8:11], v[238:241], v[100:103]
	v_mfma_f32_16x16x32_bf16 v[28:31], v[80:83], v[238:241], v[96:99]
	s_setprio 0
	s_barrier
	ds_read_b128 v[92:95], v132
	ds_read_b128 v[84:87], v132 offset:1024
	ds_read_b128 v[96:99], v132 offset:2048
	ds_read_b128 v[88:91], v132 offset:3072
	s_waitcnt vmcnt(0)
	s_barrier
	s_waitcnt lgkmcnt(0)
	s_setprio 1
	s_waitcnt lgkmcnt(0)
	v_mfma_f32_16x16x32_bf16 v[100:103], v[92:95], v[140:143], v[156:159]
	v_mfma_f32_16x16x32_bf16 v[108:111], v[96:99], v[140:143], v[160:163]
	v_mfma_f32_16x16x32_bf16 v[116:119], v[92:95], v[218:221], v[194:197]
	v_mfma_f32_16x16x32_bf16 v[124:127], v[96:99], v[218:221], v[198:201]
	v_mfma_f32_16x16x32_bf16 v[160:163], v[92:95], v[226:229], v[202:205]
	v_mfma_f32_16x16x32_bf16 v[194:197], v[96:99], v[226:229], v[206:209]
	v_mfma_f32_16x16x32_bf16 v[198:201], v[92:95], v[234:237], v[210:213]
	v_mfma_f32_16x16x32_bf16 v[202:205], v[96:99], v[234:237], v[214:217]
	v_mfma_f32_16x16x32_bf16 v[156:159], v[84:87], v[148:151], v[100:103]
	v_mfma_f32_16x16x32_bf16 v[148:151], v[88:91], v[148:151], v[108:111]
	v_mfma_f32_16x16x32_bf16 v[140:143], v[84:87], v[222:225], v[116:119]
	v_mfma_f32_16x16x32_bf16 v[132:135], v[88:91], v[222:225], v[124:127]
	v_mfma_f32_16x16x32_bf16 v[124:127], v[84:87], v[230:233], v[160:163]
	v_mfma_f32_16x16x32_bf16 v[116:119], v[88:91], v[230:233], v[194:197]
	v_mfma_f32_16x16x32_bf16 v[108:111], v[84:87], v[238:241], v[198:201]
	v_mfma_f32_16x16x32_bf16 v[100:103], v[88:91], v[238:241], v[202:205]
	s_setprio 0
	s_lshl_b64 s[66:67], s[64:65], 2
	s_barrier
	v_mbcnt_lo_u32_b32 v162, -1, 0
	v_mbcnt_hi_u32_b32 v162, -1, v162
	s_add_u32 s66, s87, s66
	v_add_u32_e32 v160, s76, v162
	s_addc_u32 s67, s88, s67
	v_and_b32_e32 v164, 0x100, v160
	v_and_b32_e32 v162, 15, v162
	v_lshl_add_u64 v[160:161], s[66:67], 0, v[164:165]
	v_lshlrev_b32_e32 v164, 2, v162
	v_lshl_add_u64 v[160:161], v[160:161], 0, v[164:165]
	global_load_dword v178, v[160:161], off
	global_load_dword v176, v[160:161], off offset:64
	global_load_dword v174, v[160:161], off offset:128
	global_load_dword v164, v[160:161], off offset:192
	global_load_dword v172, v[160:161], off offset:512
	global_load_dword v170, v[160:161], off offset:576
	global_load_dword v168, v[160:161], off offset:640
	global_load_dword v166, v[160:161], off offset:704
	v_mbcnt_lo_u32_b32 v194, -1, 0
	v_mbcnt_hi_u32_b32 v194, -1, v194
	s_mov_b64 s[66:67], -1
	v_add_u32_e32 v160, s76, v194
	v_bfe_u32 v161, v160, 8, 1
	v_ashrrev_i32_e32 v196, 6, v160
	v_bfe_u32 v160, v194, 4, 2
	v_and_b32_e32 v198, 3, v196
	v_and_b32_e32 v195, 15, v194
	s_cmp_gt_i32 s74, 1
	v_lshlrev_b32_e32 v193, 6, v161
	v_lshlrev_b32_e32 v197, 4, v160
	s_cbranch_scc0 .LBB0_113
	v_lshlrev_b32_e32 v161, 6, v198
	v_or3_b32 v160, v193, v195, s64
	v_or3_b32 v161, v161, v197, s62
	v_lshl_add_u32 v199, v160, 12, v161
	s_waitcnt vmcnt(0)
	v_mul_f32_e32 v160, v178, v178
	v_pk_mul_f32 v[200:201], v[152:153], v[160:161] op_sel_hi:[1,0]
	v_pk_mul_f32 v[162:163], v[154:155], v[160:161] op_sel_hi:[1,0]
	v_pk_mul_f32 v[202:203], v[158:159], v[160:161] op_sel_hi:[1,0]
	v_pk_mul_f32 v[204:205], v[156:157], v[160:161] op_sel_hi:[1,0]
	v_mul_f32_e32 v160, v144, v200
	v_mul_f32_e32 v161, v145, v201
	v_cvt_pk_bf16_f32 v160, v160, v161
	v_mul_f32_e32 v161, v146, v162
	v_mul_f32_e32 v162, v147, v163
	v_cvt_pk_bf16_f32 v161, v161, v162
	v_mul_f32_e32 v162, v148, v204
	v_mul_f32_e32 v163, v149, v205
	v_cvt_pk_bf16_f32 v162, v162, v163
	v_mul_f32_e32 v163, v150, v202
	v_mul_f32_e32 v200, v151, v203
	v_cvt_pk_bf16_f32 v163, v163, v200
	global_store_dwordx4 v199, v[160:163], s[6:7]
	v_add_u32_e32 v206, 0x10000, v199
	s_mov_b64 s[66:67], 0
	v_mul_f32_e32 v160, v176, v176
	v_pk_mul_f32 v[200:201], v[136:137], v[160:161] op_sel_hi:[1,0]
	v_pk_mul_f32 v[162:163], v[138:139], v[160:161] op_sel_hi:[1,0]
	v_pk_mul_f32 v[202:203], v[142:143], v[160:161] op_sel_hi:[1,0]
	v_pk_mul_f32 v[204:205], v[140:141], v[160:161] op_sel_hi:[1,0]
	v_mul_f32_e32 v160, v128, v200
	v_mul_f32_e32 v161, v129, v201
	v_cvt_pk_bf16_f32 v160, v160, v161
	v_mul_f32_e32 v161, v130, v162
	v_mul_f32_e32 v162, v131, v163
	v_cvt_pk_bf16_f32 v161, v161, v162
	v_mul_f32_e32 v162, v132, v204
	v_mul_f32_e32 v163, v133, v205
	v_cvt_pk_bf16_f32 v162, v162, v163
	v_mul_f32_e32 v163, v134, v202
	v_mul_f32_e32 v200, v135, v203
	v_cvt_pk_bf16_f32 v163, v163, v200
	global_store_dwordx4 v206, v[160:163], s[6:7]
	v_add_u32_e32 v206, 0x20000, v199
	v_add_u32_e32 v199, 0x30000, v199
	v_mul_f32_e32 v160, v174, v174
	v_pk_mul_f32 v[200:201], v[120:121], v[160:161] op_sel_hi:[1,0]
	v_pk_mul_f32 v[162:163], v[122:123], v[160:161] op_sel_hi:[1,0]
	v_pk_mul_f32 v[202:203], v[126:127], v[160:161] op_sel_hi:[1,0]
	v_pk_mul_f32 v[204:205], v[124:125], v[160:161] op_sel_hi:[1,0]
	v_mul_f32_e32 v160, v112, v200
	v_mul_f32_e32 v161, v113, v201
	v_cvt_pk_bf16_f32 v160, v160, v161
	v_mul_f32_e32 v161, v114, v162
	v_mul_f32_e32 v162, v115, v163
	v_cvt_pk_bf16_f32 v161, v161, v162
	v_mul_f32_e32 v162, v116, v204
	v_mul_f32_e32 v163, v117, v205
	v_cvt_pk_bf16_f32 v162, v162, v163
	v_mul_f32_e32 v163, v118, v202
	v_mul_f32_e32 v200, v119, v203
	v_cvt_pk_bf16_f32 v163, v163, v200
	global_store_dwordx4 v206, v[160:163], s[6:7]
	s_nop 1
	v_mul_f32_e32 v160, v164, v164
	v_pk_mul_f32 v[200:201], v[104:105], v[160:161] op_sel_hi:[1,0]
	v_pk_mul_f32 v[162:163], v[106:107], v[160:161] op_sel_hi:[1,0]
	v_pk_mul_f32 v[202:203], v[110:111], v[160:161] op_sel_hi:[1,0]
	v_pk_mul_f32 v[204:205], v[108:109], v[160:161] op_sel_hi:[1,0]
	v_mul_f32_e32 v160, v28, v200
	v_mul_f32_e32 v161, v29, v201
	v_cvt_pk_bf16_f32 v160, v160, v161
	v_mul_f32_e32 v161, v30, v162
	v_mul_f32_e32 v162, v31, v163
	v_cvt_pk_bf16_f32 v161, v161, v162
	v_mul_f32_e32 v162, v100, v204
	v_mul_f32_e32 v163, v101, v205
	v_cvt_pk_bf16_f32 v162, v162, v163
	v_mul_f32_e32 v163, v102, v202
	v_mul_f32_e32 v200, v103, v203
	v_cvt_pk_bf16_f32 v163, v163, v200

.LBB0_178:
	ds_read_b128 v[164:167], v162
	ds_read_b128 v[168:171], v162 offset:1024
	ds_read_b128 v[172:175], v162 offset:2048
	ds_read_b128 v[176:179], v162 offset:3072
	ds_read_b128 v[180:183], v153
	ds_read_b128 v[184:187], v153 offset:1024
	ds_read_b128 v[188:191], v152
	ds_read_b128 v[192:195], v152 offset:1024
	ds_read_b128 v[196:199], v151
	ds_read_b128 v[200:203], v151 offset:1024
	ds_read_b128 v[204:207], v150
	ds_read_b128 v[208:211], v150 offset:1024
	s_waitcnt lgkmcnt(8)
	s_waitcnt vmcnt(10)
	s_barrier
	s_waitcnt lgkmcnt(0)
	s_setprio 1
	s_waitcnt lgkmcnt(0)
	v_mfma_f32_16x16x32_bf16 v[124:127], v[164:167], v[180:183], v[124:127]
	v_mfma_f32_16x16x32_bf16 v[120:123], v[172:175], v[180:183], v[120:123]
	v_mfma_f32_16x16x32_bf16 v[116:119], v[164:167], v[188:191], v[116:119]
	v_mfma_f32_16x16x32_bf16 v[112:115], v[172:175], v[188:191], v[112:115]
	v_mfma_f32_16x16x32_bf16 v[108:111], v[164:167], v[196:199], v[108:111]
	v_mfma_f32_16x16x32_bf16 v[104:107], v[172:175], v[196:199], v[104:107]
	v_mfma_f32_16x16x32_bf16 v[100:103], v[164:167], v[204:207], v[100:103]
	v_mfma_f32_16x16x32_bf16 v[96:99], v[172:175], v[204:207], v[96:99]
	v_mfma_f32_16x16x32_bf16 v[124:127], v[168:171], v[184:187], v[124:127]
	v_mfma_f32_16x16x32_bf16 v[120:123], v[176:179], v[184:187], v[120:123]
	v_mfma_f32_16x16x32_bf16 v[116:119], v[168:171], v[192:195], v[116:119]
	v_mfma_f32_16x16x32_bf16 v[112:115], v[176:179], v[192:195], v[112:115]
	v_mfma_f32_16x16x32_bf16 v[108:111], v[168:171], v[200:203], v[108:111]
	v_mfma_f32_16x16x32_bf16 v[104:107], v[176:179], v[200:203], v[104:107]
	v_mfma_f32_16x16x32_bf16 v[100:103], v[168:171], v[208:211], v[100:103]
	v_mfma_f32_16x16x32_bf16 v[96:99], v[176:179], v[208:211], v[96:99]
	s_setprio 0
	s_barrier
	v_lshl_add_u64 v[230:231], s[50:51], 0, v[130:131]
	s_mov_b64 s[66:67], 0x1880000
	v_readfirstlane_b32 s65, v149
	v_lshl_add_u64 v[232:233], v[230:231], 0, s[66:67]
	s_mov_b32 m0, s65
	s_mov_b64 s[66:67], 0x1881000
	v_readfirstlane_b32 s65, v148
	ds_read_b128 v[212:215], v159
	ds_read_b128 v[216:219], v159 offset:1024
	ds_read_b128 v[220:223], v159 offset:2048
	ds_read_b128 v[224:227], v159 offset:3072
	global_load_lds_dwordx4 v[232:233], off
	v_lshl_add_u64 v[232:233], v[230:231], 0, s[66:67]
	s_mov_b32 m0, s65
	s_nop 0
	global_load_lds_dwordx4 v[232:233], off
	s_waitcnt vmcnt(10)
	s_barrier
	s_waitcnt lgkmcnt(0)
	s_setprio 1
	s_waitcnt lgkmcnt(0)
	v_mfma_f32_16x16x32_bf16 v[92:95], v[212:215], v[180:183], v[92:95]
	v_mfma_f32_16x16x32_bf16 v[88:91], v[220:223], v[180:183], v[88:91]
	v_mfma_f32_16x16x32_bf16 v[84:87], v[212:215], v[188:191], v[84:87]
	v_mfma_f32_16x16x32_bf16 v[80:83], v[220:223], v[188:191], v[80:83]
	v_mfma_f32_16x16x32_bf16 v[76:79], v[212:215], v[196:199], v[76:79]
	v_mfma_f32_16x16x32_bf16 v[72:75], v[220:223], v[196:199], v[72:75]
	v_mfma_f32_16x16x32_bf16 v[68:71], v[212:215], v[204:207], v[68:71]
	v_mfma_f32_16x16x32_bf16 v[64:67], v[220:223], v[204:207], v[64:67]
	v_mfma_f32_16x16x32_bf16 v[92:95], v[216:219], v[184:187], v[92:95]
	v_mfma_f32_16x16x32_bf16 v[88:91], v[224:227], v[184:187], v[88:91]
	v_mfma_f32_16x16x32_bf16 v[84:87], v[216:219], v[192:195], v[84:87]
	v_mfma_f32_16x16x32_bf16 v[80:83], v[224:227], v[192:195], v[80:83]
	v_mfma_f32_16x16x32_bf16 v[76:79], v[216:219], v[200:203], v[76:79]
	v_mfma_f32_16x16x32_bf16 v[72:75], v[224:227], v[200:203], v[72:75]
	v_mfma_f32_16x16x32_bf16 v[68:71], v[216:219], v[208:211], v[68:71]
	v_mfma_f32_16x16x32_bf16 v[64:67], v[224:227], v[208:211], v[64:67]
	s_setprio 0
	s_mov_b64 s[66:67], 0xe000100
	v_readfirstlane_b32 s65, v135
	v_lshl_add_u64 v[232:233], v[228:229], 0, s[66:67]
	s_mov_b32 m0, s65
	s_mov_b64 s[66:67], 0xe040100
	v_readfirstlane_b32 s65, v147
	s_barrier
	ds_read_b128 v[180:183], v153 offset:16384
	ds_read_b128 v[184:187], v153 offset:17408
	ds_read_b128 v[188:191], v152 offset:16384
	ds_read_b128 v[192:195], v152 offset:17408
	ds_read_b128 v[196:199], v151 offset:16384
	ds_read_b128 v[200:203], v151 offset:17408
	ds_read_b128 v[204:207], v150 offset:16384
	ds_read_b128 v[208:211], v150 offset:17408
	global_load_lds_dwordx4 v[232:233], off
	v_lshl_add_u64 v[232:233], v[228:229], 0, s[66:67]
	s_mov_b32 m0, s65
	s_nop 0
	global_load_lds_dwordx4 v[232:233], off
	s_barrier
	s_waitcnt lgkmcnt(0)
	s_setprio 1
	s_waitcnt lgkmcnt(0)
	v_mfma_f32_16x16x32_bf16 v[60:63], v[164:167], v[180:183], v[60:63]
	v_mfma_f32_16x16x32_bf16 v[56:59], v[172:175], v[180:183], v[56:59]
	v_mfma_f32_16x16x32_bf16 v[52:55], v[164:167], v[188:191], v[52:55]
	v_mfma_f32_16x16x32_bf16 v[48:51], v[172:175], v[188:191], v[48:51]
	v_mfma_f32_16x16x32_bf16 v[44:47], v[164:167], v[196:199], v[44:47]
	v_mfma_f32_16x16x32_bf16 v[40:43], v[172:175], v[196:199], v[40:43]
	v_mfma_f32_16x16x32_bf16 v[36:39], v[164:167], v[204:207], v[36:39]
	v_mfma_f32_16x16x32_bf16 v[32:35], v[172:175], v[204:207], v[32:35]
	v_mfma_f32_16x16x32_bf16 v[60:63], v[168:171], v[184:187], v[60:63]
	v_mfma_f32_16x16x32_bf16 v[56:59], v[176:179], v[184:187], v[56:59]
	v_mfma_f32_16x16x32_bf16 v[52:55], v[168:171], v[192:195], v[52:55]
	v_mfma_f32_16x16x32_bf16 v[48:51], v[176:179], v[192:195], v[48:51]
	v_mfma_f32_16x16x32_bf16 v[44:47], v[168:171], v[200:203], v[44:47]
	v_mfma_f32_16x16x32_bf16 v[40:43], v[176:179], v[200:203], v[40:43]
	v_mfma_f32_16x16x32_bf16 v[36:39], v[168:171], v[208:211], v[36:39]
	v_mfma_f32_16x16x32_bf16 v[32:35], v[176:179], v[208:211], v[32:35]
	s_setprio 0
	s_barrier
	s_mov_b64 s[66:67], 0x1882000
	v_readfirstlane_b32 s65, v146
	v_lshl_add_u64 v[164:165], v[230:231], 0, s[66:67]
	s_mov_b32 m0, s65
	s_mov_b64 s[66:67], 0x1883000
	v_readfirstlane_b32 s65, v145
	global_load_lds_dwordx4 v[164:165], off
	v_lshl_add_u64 v[164:165], v[230:231], 0, s[66:67]
	s_mov_b32 m0, s65
	s_nop 0
	global_load_lds_dwordx4 v[164:165], off
	v_readfirstlane_b32 s65, v144
	v_lshl_add_u64 v[166:167], v[228:229], 0, s[26:27]
	s_mov_b32 m0, s65
	v_readfirstlane_b32 s65, v143
	global_load_lds_dwordx4 v[166:167], off
	v_lshl_add_u64 v[166:167], v[228:229], 0, s[28:29]
	s_mov_b32 m0, s65
	s_nop 0
	global_load_lds_dwordx4 v[166:167], off
	s_waitcnt vmcnt(12)
	s_barrier
	s_setprio 1
	v_mfma_f32_16x16x32_bf16 v[28:31], v[212:215], v[180:183], v[28:31]
	v_mfma_f32_16x16x32_bf16 v[24:27], v[220:223], v[180:183], v[24:27]
	v_mfma_f32_16x16x32_bf16 v[20:23], v[212:215], v[188:191], v[20:23]
	v_mfma_f32_16x16x32_bf16 v[16:19], v[220:223], v[188:191], v[16:19]
	v_mfma_f32_16x16x32_bf16 v[12:15], v[212:215], v[196:199], v[12:15]
	v_mfma_f32_16x16x32_bf16 v[8:11], v[220:223], v[196:199], v[8:11]
	v_mfma_f32_16x16x32_bf16 v[4:7], v[212:215], v[204:207], v[4:7]
	v_mfma_f32_16x16x32_bf16 v[0:3], v[220:223], v[204:207], v[0:3]
	v_mfma_f32_16x16x32_bf16 v[28:31], v[216:219], v[184:187], v[28:31]
	v_mfma_f32_16x16x32_bf16 v[24:27], v[224:227], v[184:187], v[24:27]
	v_mfma_f32_16x16x32_bf16 v[20:23], v[216:219], v[192:195], v[20:23]
	v_mfma_f32_16x16x32_bf16 v[16:19], v[224:227], v[192:195], v[16:19]
	v_mfma_f32_16x16x32_bf16 v[12:15], v[216:219], v[200:203], v[12:15]
	v_mfma_f32_16x16x32_bf16 v[8:11], v[224:227], v[200:203], v[8:11]
	v_mfma_f32_16x16x32_bf16 v[4:7], v[216:219], v[208:211], v[4:7]
	v_mfma_f32_16x16x32_bf16 v[0:3], v[224:227], v[208:211], v[0:3]
	s_setprio 0
	s_barrier
	ds_read_b128 v[164:167], v155
	ds_read_b128 v[168:171], v155 offset:1024
	ds_read_b128 v[172:175], v155 offset:2048
	ds_read_b128 v[176:179], v155 offset:3072
	ds_read_b128 v[180:183], v153 offset:32768
	ds_read_b128 v[184:187], v153 offset:33792
	ds_read_b128 v[188:191], v152 offset:32768
	ds_read_b128 v[192:195], v152 offset:33792
	ds_read_b128 v[196:199], v151 offset:32768
	ds_read_b128 v[200:203], v151 offset:33792
	ds_read_b128 v[204:207], v150 offset:32768
	ds_read_b128 v[208:211], v150 offset:33792
	s_waitcnt lgkmcnt(8)
	s_waitcnt vmcnt(10)
	s_barrier
	s_waitcnt lgkmcnt(0)
	s_setprio 1
	s_waitcnt lgkmcnt(0)
	v_mfma_f32_16x16x32_bf16 v[124:127], v[164:167], v[180:183], v[124:127]
	v_mfma_f32_16x16x32_bf16 v[120:123], v[172:175], v[180:183], v[120:123]
	v_mfma_f32_16x16x32_bf16 v[116:119], v[164:167], v[188:191], v[116:119]
	v_mfma_f32_16x16x32_bf16 v[112:115], v[172:175], v[188:191], v[112:115]
	v_mfma_f32_16x16x32_bf16 v[108:111], v[164:167], v[196:199], v[108:111]
	v_mfma_f32_16x16x32_bf16 v[104:107], v[172:175], v[196:199], v[104:107]
	v_mfma_f32_16x16x32_bf16 v[100:103], v[164:167], v[204:207], v[100:103]
	v_mfma_f32_16x16x32_bf16 v[96:99], v[172:175], v[204:207], v[96:99]
	v_mfma_f32_16x16x32_bf16 v[124:127], v[168:171], v[184:187], v[124:127]
	v_mfma_f32_16x16x32_bf16 v[120:123], v[176:179], v[184:187], v[120:123]
	v_mfma_f32_16x16x32_bf16 v[116:119], v[168:171], v[192:195], v[116:119]
	v_mfma_f32_16x16x32_bf16 v[112:115], v[176:179], v[192:195], v[112:115]
	v_mfma_f32_16x16x32_bf16 v[108:111], v[168:171], v[200:203], v[108:111]
	v_mfma_f32_16x16x32_bf16 v[104:107], v[176:179], v[200:203], v[104:107]
	v_mfma_f32_16x16x32_bf16 v[100:103], v[168:171], v[208:211], v[100:103]
	v_mfma_f32_16x16x32_bf16 v[96:99], v[176:179], v[208:211], v[96:99]
	s_setprio 0
	s_barrier
	v_readfirstlane_b32 s65, v142
	v_lshl_add_u64 v[232:233], v[230:231], 0, s[30:31]
	s_mov_b32 m0, s65
	v_readfirstlane_b32 s65, v141
	ds_read_b128 v[212:215], v154
	ds_read_b128 v[216:219], v154 offset:1024
	ds_read_b128 v[220:223], v154 offset:2048
	ds_read_b128 v[224:227], v154 offset:3072
	global_load_lds_dwordx4 v[232:233], off
	v_lshl_add_u64 v[232:233], v[230:231], 0, s[34:35]
	s_mov_b32 m0, s65
	s_nop 0
	global_load_lds_dwordx4 v[232:233], off
	s_waitcnt vmcnt(10)
	s_barrier
	s_waitcnt lgkmcnt(0)
	s_setprio 1
	s_waitcnt lgkmcnt(0)
	v_mfma_f32_16x16x32_bf16 v[92:95], v[212:215], v[180:183], v[92:95]
	v_mfma_f32_16x16x32_bf16 v[88:91], v[220:223], v[180:183], v[88:91]
	v_mfma_f32_16x16x32_bf16 v[84:87], v[212:215], v[188:191], v[84:87]
	v_mfma_f32_16x16x32_bf16 v[80:83], v[220:223], v[188:191], v[80:83]
	v_mfma_f32_16x16x32_bf16 v[76:79], v[212:215], v[196:199], v[76:79]
	v_mfma_f32_16x16x32_bf16 v[72:75], v[220:223], v[196:199], v[72:75]
	v_mfma_f32_16x16x32_bf16 v[68:71], v[212:215], v[204:207], v[68:71]
	v_mfma_f32_16x16x32_bf16 v[64:67], v[220:223], v[204:207], v[64:67]
	v_mfma_f32_16x16x32_bf16 v[92:95], v[216:219], v[184:187], v[92:95]
	v_mfma_f32_16x16x32_bf16 v[88:91], v[224:227], v[184:187], v[88:91]
	v_mfma_f32_16x16x32_bf16 v[84:87], v[216:219], v[192:195], v[84:87]
	v_mfma_f32_16x16x32_bf16 v[80:83], v[224:227], v[192:195], v[80:83]
	v_mfma_f32_16x16x32_bf16 v[76:79], v[216:219], v[200:203], v[76:79]
	v_mfma_f32_16x16x32_bf16 v[72:75], v[224:227], v[200:203], v[72:75]
	v_mfma_f32_16x16x32_bf16 v[68:71], v[216:219], v[208:211], v[68:71]
	v_mfma_f32_16x16x32_bf16 v[64:67], v[224:227], v[208:211], v[64:67]
	s_setprio 0
	v_readfirstlane_b32 s65, v140
	v_lshl_add_u64 v[232:233], v[228:229], 0, s[40:41]
	s_mov_b32 m0, s65
	v_readfirstlane_b32 s65, v139
	s_barrier
	ds_read_b128 v[180:183], v153 offset:49152
	ds_read_b128 v[184:187], v153 offset:50176
	ds_read_b128 v[188:191], v152 offset:49152
	ds_read_b128 v[192:195], v152 offset:50176
	ds_read_b128 v[196:199], v151 offset:49152
	ds_read_b128 v[200:203], v151 offset:50176
	ds_read_b128 v[204:207], v150 offset:49152
	ds_read_b128 v[208:211], v150 offset:50176
	global_load_lds_dwordx4 v[232:233], off
	v_lshl_add_u64 v[228:229], v[228:229], 0, s[44:45]
	s_mov_b32 m0, s65
	s_nop 0
	global_load_lds_dwordx4 v[228:229], off
	s_barrier
	s_waitcnt lgkmcnt(0)
	s_setprio 1
	s_waitcnt lgkmcnt(0)
	v_mfma_f32_16x16x32_bf16 v[60:63], v[164:167], v[180:183], v[60:63]
	v_mfma_f32_16x16x32_bf16 v[56:59], v[172:175], v[180:183], v[56:59]
	v_mfma_f32_16x16x32_bf16 v[52:55], v[164:167], v[188:191], v[52:55]
	v_mfma_f32_16x16x32_bf16 v[48:51], v[172:175], v[188:191], v[48:51]
	v_mfma_f32_16x16x32_bf16 v[44:47], v[164:167], v[196:199], v[44:47]
	v_mfma_f32_16x16x32_bf16 v[40:43], v[172:175], v[196:199], v[40:43]
	v_mfma_f32_16x16x32_bf16 v[36:39], v[164:167], v[204:207], v[36:39]
	v_mfma_f32_16x16x32_bf16 v[32:35], v[172:175], v[204:207], v[32:35]
	v_mfma_f32_16x16x32_bf16 v[60:63], v[168:171], v[184:187], v[60:63]
	v_mfma_f32_16x16x32_bf16 v[56:59], v[176:179], v[184:187], v[56:59]
	v_mfma_f32_16x16x32_bf16 v[52:55], v[168:171], v[192:195], v[52:55]
	v_mfma_f32_16x16x32_bf16 v[48:51], v[176:179], v[192:195], v[48:51]
	v_mfma_f32_16x16x32_bf16 v[44:47], v[168:171], v[200:203], v[44:47]
	v_mfma_f32_16x16x32_bf16 v[40:43], v[176:179], v[200:203], v[40:43]
	v_mfma_f32_16x16x32_bf16 v[36:39], v[168:171], v[208:211], v[36:39]
	v_mfma_f32_16x16x32_bf16 v[32:35], v[176:179], v[208:211], v[32:35]
	s_setprio 0
	s_barrier
	v_readfirstlane_b32 s65, v138
	v_lshl_add_u64 v[164:165], v[230:231], 0, s[46:47]
	s_mov_b32 m0, s65
	v_readfirstlane_b32 s65, v137
	global_load_lds_dwordx4 v[164:165], off
	v_lshl_add_u64 v[164:165], v[230:231], 0, s[56:57]
	s_mov_b32 m0, s65
	s_nop 0
	global_load_lds_dwordx4 v[164:165], off
	v_lshl_add_u64 v[132:133], v[132:133], 0, s[58:59]
	v_lshl_add_u64 v[228:229], s[50:51], 0, v[132:133]
	s_mov_b64 s[66:67], 0xe080080
	v_readfirstlane_b32 s65, v161
	v_lshl_add_u64 v[166:167], v[228:229], 0, s[66:67]
	s_mov_b32 m0, s65
	s_mov_b64 s[66:67], 0xe0c0080
	v_readfirstlane_b32 s65, v160
	global_load_lds_dwordx4 v[166:167], off
	v_lshl_add_u64 v[166:167], v[228:229], 0, s[66:67]
	s_mov_b32 m0, s65
	s_nop 0
	global_load_lds_dwordx4 v[166:167], off
	s_waitcnt vmcnt(12)
	s_barrier
	s_setprio 1
	v_mfma_f32_16x16x32_bf16 v[28:31], v[212:215], v[180:183], v[28:31]
	v_mfma_f32_16x16x32_bf16 v[24:27], v[220:223], v[180:183], v[24:27]
	v_mfma_f32_16x16x32_bf16 v[20:23], v[212:215], v[188:191], v[20:23]
	v_mfma_f32_16x16x32_bf16 v[16:19], v[220:223], v[188:191], v[16:19]
	v_mfma_f32_16x16x32_bf16 v[12:15], v[212:215], v[196:199], v[12:15]
	v_mfma_f32_16x16x32_bf16 v[8:11], v[220:223], v[196:199], v[8:11]
	v_mfma_f32_16x16x32_bf16 v[4:7], v[212:215], v[204:207], v[4:7]
	v_mfma_f32_16x16x32_bf16 v[0:3], v[220:223], v[204:207], v[0:3]
	v_mfma_f32_16x16x32_bf16 v[28:31], v[216:219], v[184:187], v[28:31]
	v_mfma_f32_16x16x32_bf16 v[24:27], v[224:227], v[184:187], v[24:27]
	v_mfma_f32_16x16x32_bf16 v[20:23], v[216:219], v[192:195], v[20:23]
	v_mfma_f32_16x16x32_bf16 v[16:19], v[224:227], v[192:195], v[16:19]
	v_mfma_f32_16x16x32_bf16 v[12:15], v[216:219], v[200:203], v[12:15]
	v_mfma_f32_16x16x32_bf16 v[8:11], v[224:227], v[200:203], v[8:11]
	v_mfma_f32_16x16x32_bf16 v[4:7], v[216:219], v[208:211], v[4:7]
	v_mfma_f32_16x16x32_bf16 v[0:3], v[224:227], v[208:211], v[0:3]
	s_setprio 0
	s_add_i32 s24, s24, 2
	v_lshl_add_u64 v[130:131], v[130:131], 0, s[10:11]
	s_cmp_lt_u32 s24, 28
	s_barrier
	s_cbranch_scc1 .LBB0_178
	s_lshl_b32 s24, s85, 5
	s_lshl_b32 s65, s85, 8
	s_and_b32 s24, s24, 0x1800
	s_and_b32 s65, s65, 0x700
	s_or_b32 s24, s65, s24
	v_lshlrev_b32_e32 v128, 3, v156
	v_lshlrev_b32_e32 v130, 5, v156
	v_and_b32_e32 v128, 0xffff0, v128
	v_and_b32_e32 v130, 32, v130
	s_lshl_b32 s65, s24, 12
	v_add_u32_e32 v130, v130, v158
	v_add_lshl_u32 v128, v157, v128, 12
	s_add_u32 s66, s68, s65
	v_lshl_add_u32 v128, v130, 1, v128
	s_addc_u32 s67, s69, 0
	v_lshl_add_u64 v[156:157], s[66:67], 0, v[128:129]
	v_readfirstlane_b32 s65, v161
	ds_read_b128 v[130:133], v162
	ds_read_b128 v[164:167], v162 offset:1024
	ds_read_b128 v[168:171], v162 offset:2048
	ds_read_b128 v[172:175], v162 offset:3072
	ds_read_b128 v[176:179], v153
	ds_read_b128 v[180:183], v153 offset:1024
	ds_read_b128 v[184:187], v152
	ds_read_b128 v[188:191], v152 offset:1024
	ds_read_b128 v[192:195], v151
	ds_read_b128 v[196:199], v151 offset:1024
	ds_read_b128 v[200:203], v150
	ds_read_b128 v[204:207], v150 offset:1024
	v_lshl_add_u64 v[162:163], v[156:157], 0, s[60:61]
	s_mov_b32 m0, s65
	v_readfirstlane_b32 s65, v160
	global_load_lds_dwordx4 v[162:163], off
	v_lshl_add_u64 v[156:157], v[156:157], 0, s[62:63]
	s_mov_b32 m0, s65
	s_nop 0
	global_load_lds_dwordx4 v[156:157], off
	s_waitcnt vmcnt(10)
	s_barrier
	s_waitcnt lgkmcnt(0)
	s_setprio 1
	s_waitcnt lgkmcnt(0)
	v_mfma_f32_16x16x32_bf16 v[124:127], v[130:133], v[176:179], v[124:127]
	v_mfma_f32_16x16x32_bf16 v[120:123], v[168:171], v[176:179], v[120:123]
	v_mfma_f32_16x16x32_bf16 v[116:119], v[130:133], v[184:187], v[116:119]
	v_mfma_f32_16x16x32_bf16 v[112:115], v[168:171], v[184:187], v[112:115]
	v_mfma_f32_16x16x32_bf16 v[108:111], v[130:133], v[192:195], v[108:111]
	v_mfma_f32_16x16x32_bf16 v[104:107], v[168:171], v[192:195], v[104:107]
	v_mfma_f32_16x16x32_bf16 v[100:103], v[130:133], v[200:203], v[100:103]
	v_mfma_f32_16x16x32_bf16 v[96:99], v[168:171], v[200:203], v[96:99]
	v_mfma_f32_16x16x32_bf16 v[124:127], v[164:167], v[180:183], v[124:127]
	v_mfma_f32_16x16x32_bf16 v[120:123], v[172:175], v[180:183], v[120:123]
	v_mfma_f32_16x16x32_bf16 v[116:119], v[164:167], v[188:191], v[116:119]
	v_mfma_f32_16x16x32_bf16 v[112:115], v[172:175], v[188:191], v[112:115]
	v_mfma_f32_16x16x32_bf16 v[108:111], v[164:167], v[196:199], v[108:111]
	v_mfma_f32_16x16x32_bf16 v[104:107], v[172:175], v[196:199], v[104:107]
	v_mfma_f32_16x16x32_bf16 v[100:103], v[164:167], v[204:207], v[100:103]
	v_mfma_f32_16x16x32_bf16 v[96:99], v[172:175], v[204:207], v[96:99]
	s_setprio 0
	s_barrier
	ds_read_b128 v[160:163], v159
	ds_read_b128 v[208:211], v159 offset:1024
	ds_read_b128 v[212:215], v159 offset:2048
	ds_read_b128 v[156:159], v159 offset:3072
	s_barrier
	s_waitcnt lgkmcnt(0)
	s_setprio 1
	s_waitcnt lgkmcnt(0)
	v_mfma_f32_16x16x32_bf16 v[92:95], v[160:163], v[176:179], v[92:95]
	v_mfma_f32_16x16x32_bf16 v[88:91], v[212:215], v[176:179], v[88:91]
	v_mfma_f32_16x16x32_bf16 v[84:87], v[160:163], v[184:187], v[84:87]
	v_mfma_f32_16x16x32_bf16 v[80:83], v[212:215], v[184:187], v[80:83]
	v_mfma_f32_16x16x32_bf16 v[76:79], v[160:163], v[192:195], v[76:79]
	v_mfma_f32_16x16x32_bf16 v[72:75], v[212:215], v[192:195], v[72:75]
	v_mfma_f32_16x16x32_bf16 v[68:71], v[160:163], v[200:203], v[68:71]
	v_mfma_f32_16x16x32_bf16 v[64:67], v[212:215], v[200:203], v[64:67]
	v_mfma_f32_16x16x32_bf16 v[176:179], v[208:211], v[180:183], v[92:95]
	v_mfma_f32_16x16x32_bf16 v[180:183], v[156:159], v[180:183], v[88:91]
	v_mfma_f32_16x16x32_bf16 v[184:187], v[208:211], v[188:191], v[84:87]
	v_mfma_f32_16x16x32_bf16 v[188:191], v[156:159], v[188:191], v[80:83]
	v_mfma_f32_16x16x32_bf16 v[192:195], v[208:211], v[196:199], v[76:79]
	v_mfma_f32_16x16x32_bf16 v[196:199], v[156:159], v[196:199], v[72:75]
	v_mfma_f32_16x16x32_bf16 v[200:203], v[208:211], v[204:207], v[68:71]
	v_mfma_f32_16x16x32_bf16 v[204:207], v[156:159], v[204:207], v[64:67]
	s_setprio 0
	s_barrier
	s_nop 0
	ds_read_b128 v[64:67], v153 offset:16384
	ds_read_b128 v[68:71], v153 offset:17408
	ds_read_b128 v[72:75], v152 offset:16384
	ds_read_b128 v[76:79], v152 offset:17408
	ds_read_b128 v[80:83], v151 offset:16384
	ds_read_b128 v[84:87], v151 offset:17408
	ds_read_b128 v[88:91], v150 offset:16384
	ds_read_b128 v[92:95], v150 offset:17408
	s_waitcnt vmcnt(4)
	s_barrier
	s_waitcnt lgkmcnt(0)
	s_setprio 1
	s_waitcnt lgkmcnt(0)
	v_mfma_f32_16x16x32_bf16 v[60:63], v[130:133], v[64:67], v[60:63]
	v_mfma_f32_16x16x32_bf16 v[56:59], v[168:171], v[64:67], v[56:59]
	v_mfma_f32_16x16x32_bf16 v[52:55], v[130:133], v[72:75], v[52:55]
	v_mfma_f32_16x16x32_bf16 v[48:51], v[168:171], v[72:75], v[48:51]
	v_mfma_f32_16x16x32_bf16 v[216:219], v[130:133], v[80:83], v[44:47]
	v_mfma_f32_16x16x32_bf16 v[220:223], v[168:171], v[80:83], v[40:43]
	v_mfma_f32_16x16x32_bf16 v[130:133], v[130:133], v[88:91], v[36:39]
	v_mfma_f32_16x16x32_bf16 v[168:171], v[168:171], v[88:91], v[32:35]
	v_mfma_f32_16x16x32_bf16 v[32:35], v[164:167], v[68:71], v[60:63]
	v_mfma_f32_16x16x32_bf16 v[36:39], v[172:175], v[68:71], v[56:59]
	v_mfma_f32_16x16x32_bf16 v[40:43], v[164:167], v[76:79], v[52:55]
	v_mfma_f32_16x16x32_bf16 v[44:47], v[172:175], v[76:79], v[48:51]
	v_mfma_f32_16x16x32_bf16 v[48:51], v[164:167], v[84:87], v[216:219]
	v_mfma_f32_16x16x32_bf16 v[52:55], v[172:175], v[84:87], v[220:223]
	v_mfma_f32_16x16x32_bf16 v[56:59], v[164:167], v[92:95], v[130:133]
	v_mfma_f32_16x16x32_bf16 v[60:63], v[172:175], v[92:95], v[168:171]
	s_setprio 0
	s_setprio 1
	v_mfma_f32_16x16x32_bf16 v[28:31], v[160:163], v[64:67], v[28:31]
	v_mfma_f32_16x16x32_bf16 v[24:27], v[212:215], v[64:67], v[24:27]
	v_mfma_f32_16x16x32_bf16 v[20:23], v[160:163], v[72:75], v[20:23]
	v_mfma_f32_16x16x32_bf16 v[64:67], v[212:215], v[72:75], v[16:19]
	v_mfma_f32_16x16x32_bf16 v[72:75], v[160:163], v[80:83], v[12:15]
	v_mfma_f32_16x16x32_bf16 v[8:11], v[212:215], v[80:83], v[8:11]
	v_mfma_f32_16x16x32_bf16 v[80:83], v[160:163], v[88:91], v[4:7]
	v_mfma_f32_16x16x32_bf16 v[0:3], v[212:215], v[88:91], v[0:3]
	v_mfma_f32_16x16x32_bf16 v[4:7], v[208:211], v[68:71], v[28:31]
	v_mfma_f32_16x16x32_bf16 v[12:15], v[156:159], v[68:71], v[24:27]
	v_mfma_f32_16x16x32_bf16 v[16:19], v[208:211], v[76:79], v[20:23]
	v_mfma_f32_16x16x32_bf16 v[20:23], v[156:159], v[76:79], v[64:67]
	v_mfma_f32_16x16x32_bf16 v[24:27], v[208:211], v[84:87], v[72:75]
	v_mfma_f32_16x16x32_bf16 v[28:31], v[156:159], v[84:87], v[8:11]
	v_mfma_f32_16x16x32_bf16 v[64:67], v[208:211], v[92:95], v[80:83]
	v_mfma_f32_16x16x32_bf16 v[68:71], v[156:159], v[92:95], v[0:3]
	s_setprio 0
	s_barrier
	ds_read_b128 v[8:11], v155
	ds_read_b128 v[0:3], v155 offset:1024
	ds_read_b128 v[76:79], v155 offset:2048
	ds_read_b128 v[72:75], v155 offset:3072
	ds_read_b128 v[130:133], v153 offset:32768
	ds_read_b128 v[156:159], v153 offset:33792
	ds_read_b128 v[160:163], v152 offset:32768
	ds_read_b128 v[164:167], v152 offset:33792
	ds_read_b128 v[168:171], v151 offset:32768
	ds_read_b128 v[172:175], v151 offset:33792
	ds_read_b128 v[208:211], v150 offset:32768
	ds_read_b128 v[212:215], v150 offset:33792
	s_waitcnt vmcnt(2)
	s_barrier
	s_waitcnt lgkmcnt(0)
	s_setprio 1
	s_waitcnt lgkmcnt(0)
	v_mfma_f32_16x16x32_bf16 v[80:83], v[8:11], v[130:133], v[124:127]
	v_mfma_f32_16x16x32_bf16 v[84:87], v[76:79], v[130:133], v[120:123]
	v_mfma_f32_16x16x32_bf16 v[88:91], v[8:11], v[160:163], v[116:119]
	v_mfma_f32_16x16x32_bf16 v[92:95], v[76:79], v[160:163], v[112:115]
	v_mfma_f32_16x16x32_bf16 v[108:111], v[8:11], v[168:171], v[108:111]
	v_mfma_f32_16x16x32_bf16 v[104:107], v[76:79], v[168:171], v[104:107]
	v_mfma_f32_16x16x32_bf16 v[100:103], v[8:11], v[208:211], v[100:103]
	v_mfma_f32_16x16x32_bf16 v[96:99], v[76:79], v[208:211], v[96:99]
	v_mfma_f32_16x16x32_bf16 v[112:115], v[0:3], v[156:159], v[80:83]
	v_mfma_f32_16x16x32_bf16 v[116:119], v[72:75], v[156:159], v[84:87]
	v_mfma_f32_16x16x32_bf16 v[120:123], v[0:3], v[164:167], v[88:91]
	v_mfma_f32_16x16x32_bf16 v[124:127], v[72:75], v[164:167], v[92:95]
	v_mfma_f32_16x16x32_bf16 v[108:111], v[0:3], v[172:175], v[108:111]
	v_mfma_f32_16x16x32_bf16 v[104:107], v[72:75], v[172:175], v[104:107]
	v_mfma_f32_16x16x32_bf16 v[100:103], v[0:3], v[212:215], v[100:103]
	v_mfma_f32_16x16x32_bf16 v[96:99], v[72:75], v[212:215], v[96:99]
	s_setprio 0
	s_barrier
	ds_read_b128 v[88:91], v154
	ds_read_b128 v[80:83], v154 offset:1024
	ds_read_b128 v[92:95], v154 offset:2048
	ds_read_b128 v[84:87], v154 offset:3072
	s_waitcnt vmcnt(0)
	s_barrier
	s_waitcnt lgkmcnt(0)
	s_setprio 1
	s_waitcnt lgkmcnt(0)
	v_mfma_f32_16x16x32_bf16 v[176:179], v[88:91], v[130:133], v[176:179]
	v_mfma_f32_16x16x32_bf16 v[130:133], v[92:95], v[130:133], v[180:183]
	v_mfma_f32_16x16x32_bf16 v[180:183], v[88:91], v[160:163], v[184:187]
	v_mfma_f32_16x16x32_bf16 v[160:163], v[92:95], v[160:163], v[188:191]
	v_mfma_f32_16x16x32_bf16 v[184:187], v[88:91], v[168:171], v[192:195]
	v_mfma_f32_16x16x32_bf16 v[168:171], v[92:95], v[168:171], v[196:199]
	v_mfma_f32_16x16x32_bf16 v[188:191], v[88:91], v[208:211], v[200:203]
	v_mfma_f32_16x16x32_bf16 v[192:195], v[92:95], v[208:211], v[204:207]
	v_mfma_f32_16x16x32_bf16 v[176:179], v[80:83], v[156:159], v[176:179]
	v_mfma_f32_16x16x32_bf16 v[130:133], v[84:87], v[156:159], v[130:133]
	v_mfma_f32_16x16x32_bf16 v[154:157], v[80:83], v[164:167], v[180:183]
	v_mfma_f32_16x16x32_bf16 v[158:161], v[84:87], v[164:167], v[160:163]
	v_mfma_f32_16x16x32_bf16 v[162:165], v[80:83], v[172:175], v[184:187]
	v_mfma_f32_16x16x32_bf16 v[166:169], v[84:87], v[172:175], v[168:171]
	v_mfma_f32_16x16x32_bf16 v[170:173], v[80:83], v[212:215], v[188:191]
	v_mfma_f32_16x16x32_bf16 v[180:183], v[84:87], v[212:215], v[192:195]
	s_setprio 0
	s_barrier
	v_mbcnt_lo_u32_b32 v128, -1, 0
	v_mbcnt_hi_u32_b32 v128, -1, v128
	v_cvt_pk_bf16_f32 v112, v112, v113
	v_cvt_pk_bf16_f32 v113, v114, v115
	v_cvt_pk_bf16_f32 v114, v116, v117
	v_cvt_pk_bf16_f32 v115, v118, v119
	s_lshl_b32 s66, s64, 9
	v_add_u32_e32 v174, s72, v128
	v_ashrrev_i32_e32 v175, 6, v174
	v_and_b32_e32 v184, 15, v128
	v_and_b32_e32 v185, 48, v128
	v_mul_lo_u32 v186, v175, s77
	v_bfe_u32 v187, v128, 3, 3
	v_lshlrev_b32_e32 v128, 4, v128
	v_add_u32_e32 v186, 0x20000, v186
	v_lshrrev_b32_e32 v174, 2, v174
	v_and_b32_e32 v128, 0x70, v128
	v_mul_u32_u24_e32 v184, 0x90, v184
	v_and_b32_e32 v174, 64, v174
	v_add3_u32 v184, v186, v184, v185
	v_or_b32_e32 v185, v186, v128
	v_or3_b32 v174, s24, v174, v187
	v_mad_u32_u24 v185, v187, s78, v185
	ds_write_b128 v184, v[112:115]
	v_cvt_pk_bf16_f32 v112, v176, v177
	v_cvt_pk_bf16_f32 v113, v178, v179
	v_cvt_pk_bf16_f32 v114, v130, v131
	v_cvt_pk_bf16_f32 v115, v132, v133
	ds_write_b128 v184, v[112:115] offset:64
	v_lshlrev_b32_e32 v175, 7, v175
	ds_read_b128 v[112:115], v185
	v_lshlrev_b32_e32 v116, 12, v174
	v_and_or_b32 v116, v175, s79, v116
	v_or3_b32 v128, v116, s66, v128
	ds_read_b128 v[116:119], v185 offset:1152
	v_lshl_add_u64 v[130:131], s[0:1], 0, v[128:129]
	s_mov_b32 s64, 0x8000
	s_waitcnt lgkmcnt(0)
	global_store_dwordx4 v128, v[112:115], s[0:1]
	v_cvt_pk_bf16_f32 v108, v108, v109
	v_cvt_pk_bf16_f32 v109, v110, v111
	v_cvt_pk_bf16_f32 v110, v104, v105
	v_cvt_pk_bf16_f32 v111, v106, v107
	v_cvt_pk_bf16_f32 v104, v162, v163
	s_nop 1
	v_add_co_u32_e32 v112, vcc, s64, v130
	v_cvt_pk_bf16_f32 v114, v124, v125
	v_cvt_pk_bf16_f32 v115, v126, v127
	v_cvt_pk_bf16_f32 v105, v164, v165
	v_cvt_pk_bf16_f32 v106, v166, v167
	s_nop 1
	v_addc_co_u32_e32 v113, vcc, 0, v131, vcc
	global_store_dwordx4 v[112:113], v[116:119], off
	v_cvt_pk_bf16_f32 v112, v120, v121
	v_cvt_pk_bf16_f32 v113, v122, v123
	ds_write_b128 v184, v[112:115]
	v_cvt_pk_bf16_f32 v112, v154, v155
	v_cvt_pk_bf16_f32 v113, v156, v157
	v_cvt_pk_bf16_f32 v114, v158, v159
	v_cvt_pk_bf16_f32 v115, v160, v161
	ds_write_b128 v184, v[112:115] offset:64
	ds_read_b128 v[112:115], v185
	ds_read_b128 v[116:119], v185 offset:1152
	v_add_co_u32_e32 v120, vcc, s74, v130
	ds_write_b128 v184, v[108:111]
	v_cvt_pk_bf16_f32 v107, v168, v169
	ds_write_b128 v184, v[104:107] offset:64
	v_addc_co_u32_e32 v121, vcc, 0, v131, vcc
	ds_read_b128 v[104:107], v185
	ds_read_b128 v[108:111], v185 offset:1152
	s_waitcnt lgkmcnt(0)
	global_store_dwordx4 v[120:121], v[112:115], off
	v_cvt_pk_bf16_f32 v100, v100, v101
	v_cvt_pk_bf16_f32 v101, v102, v103
	v_cvt_pk_bf16_f32 v102, v96, v97
	v_cvt_pk_bf16_f32 v103, v98, v99
	ds_write_b128 v184, v[100:103]
	s_nop 0
	v_add_co_u32_e32 v112, vcc, s75, v130
	v_cvt_pk_bf16_f32 v96, v170, v171
	v_cvt_pk_bf16_f32 v97, v172, v173
	v_cvt_pk_bf16_f32 v98, v180, v181
	v_cvt_pk_bf16_f32 v99, v182, v183
	s_nop 1
	v_addc_co_u32_e32 v113, vcc, 0, v131, vcc
	global_store_dwordx4 v[112:113], v[116:119], off
	v_add_co_u32_e32 v112, vcc, s76, v130
	ds_write_b128 v184, v[96:99] offset:64
	s_nop 0
	v_addc_co_u32_e32 v113, vcc, 0, v131, vcc
	ds_read_b128 v[96:99], v185
	ds_read_b128 v[100:103], v185 offset:1152
	global_store_dwordx4 v[112:113], v[104:107], off
	s_nop 1
	v_add_co_u32_e32 v104, vcc, s80, v130
	s_nop 1
	v_addc_co_u32_e32 v105, vcc, 0, v131, vcc
	global_store_dwordx4 v[104:105], v[108:111], off
	v_add_co_u32_e32 v104, vcc, s81, v130
	s_nop 1
	v_addc_co_u32_e32 v105, vcc, 0, v131, vcc
	s_waitcnt lgkmcnt(0)
	global_store_dwordx4 v[104:105], v[96:99], off
	s_nop 1
	v_add_co_u32_e32 v96, vcc, s82, v130
	s_nop 1
	v_addc_co_u32_e32 v97, vcc, 0, v131, vcc
	global_store_dwordx4 v[96:97], v[100:103], off
	ds_read_b128 v[96:99], v153 offset:49152
	ds_read_b128 v[100:103], v153 offset:50176
	ds_read_b128 v[104:107], v152 offset:49152
	ds_read_b128 v[108:111], v152 offset:50176
	ds_read_b128 v[112:115], v151 offset:49152
	ds_read_b128 v[116:119], v151 offset:50176
	ds_read_b128 v[120:123], v150 offset:49152
	ds_read_b128 v[124:127], v150 offset:50176
	s_barrier
	s_waitcnt lgkmcnt(0)
	s_setprio 1
	s_waitcnt lgkmcnt(0)
	v_mfma_f32_16x16x32_bf16 v[32:35], v[8:11], v[96:99], v[32:35]
	v_mfma_f32_16x16x32_bf16 v[36:39], v[76:79], v[96:99], v[36:39]
	v_mfma_f32_16x16x32_bf16 v[40:43], v[8:11], v[104:107], v[40:43]
	v_mfma_f32_16x16x32_bf16 v[130:133], v[76:79], v[104:107], v[44:47]
	v_mfma_f32_16x16x32_bf16 v[150:153], v[8:11], v[112:115], v[48:51]
	v_mfma_f32_16x16x32_bf16 v[52:55], v[76:79], v[112:115], v[52:55]
	v_mfma_f32_16x16x32_bf16 v[8:11], v[8:11], v[120:123], v[56:59]
	v_mfma_f32_16x16x32_bf16 v[60:63], v[76:79], v[120:123], v[60:63]
	v_mfma_f32_16x16x32_bf16 v[56:59], v[0:3], v[100:103], v[32:35]
	v_mfma_f32_16x16x32_bf16 v[48:51], v[72:75], v[100:103], v[36:39]
	v_mfma_f32_16x16x32_bf16 v[44:47], v[0:3], v[108:111], v[40:43]
	v_mfma_f32_16x16x32_bf16 v[40:43], v[72:75], v[108:111], v[130:133]
	v_mfma_f32_16x16x32_bf16 v[36:39], v[0:3], v[116:119], v[150:153]
	v_mfma_f32_16x16x32_bf16 v[32:35], v[72:75], v[116:119], v[52:55]
	v_mfma_f32_16x16x32_bf16 v[8:11], v[0:3], v[124:127], v[8:11]
	v_mfma_f32_16x16x32_bf16 v[0:3], v[72:75], v[124:127], v[60:63]
	s_setprio 0
	s_setprio 1
	v_mfma_f32_16x16x32_bf16 v[4:7], v[88:91], v[96:99], v[4:7]
	v_mfma_f32_16x16x32_bf16 v[12:15], v[92:95], v[96:99], v[12:15]
	v_mfma_f32_16x16x32_bf16 v[16:19], v[88:91], v[104:107], v[16:19]
	v_mfma_f32_16x16x32_bf16 v[20:23], v[92:95], v[104:107], v[20:23]
	v_mfma_f32_16x16x32_bf16 v[72:75], v[88:91], v[112:115], v[24:27]
	v_mfma_f32_16x16x32_bf16 v[76:79], v[92:95], v[112:115], v[28:31]
	v_mfma_f32_16x16x32_bf16 v[64:67], v[88:91], v[120:123], v[64:67]
	v_mfma_f32_16x16x32_bf16 v[68:71], v[92:95], v[120:123], v[68:71]
	v_mfma_f32_16x16x32_bf16 v[60:63], v[80:83], v[100:103], v[4:7]
	v_mfma_f32_16x16x32_bf16 v[52:55], v[84:87], v[100:103], v[12:15]
	v_mfma_f32_16x16x32_bf16 v[28:31], v[80:83], v[108:111], v[16:19]
	v_mfma_f32_16x16x32_bf16 v[24:27], v[84:87], v[108:111], v[20:23]
	v_mfma_f32_16x16x32_bf16 v[20:23], v[80:83], v[116:119], v[72:75]
	v_mfma_f32_16x16x32_bf16 v[16:19], v[84:87], v[116:119], v[76:79]
	v_mfma_f32_16x16x32_bf16 v[12:15], v[80:83], v[124:127], v[64:67]
	v_mfma_f32_16x16x32_bf16 v[4:7], v[84:87], v[124:127], v[68:71]
	s_setprio 0
	v_cmp_gt_u32_e32 vcc, s83, v136
	s_barrier
	s_and_saveexec_b64 s[64:65], vcc
	s_cbranch_execz .LBB0_181
	s_barrier

.LBB0_234:
	ds_read_b128 v[140:143], v138
	ds_read_b128 v[144:147], v138 offset:1024
	ds_read_b128 v[148:151], v138 offset:2048
	ds_read_b128 v[152:155], v138 offset:3072
	ds_read_b128 v[156:159], v193
	ds_read_b128 v[160:163], v193 offset:1024
	ds_read_b128 v[194:197], v192
	ds_read_b128 v[198:201], v192 offset:1024
	ds_read_b128 v[202:205], v191
	ds_read_b128 v[206:209], v191 offset:1024
	ds_read_b128 v[210:213], v190
	ds_read_b128 v[214:217], v190 offset:1024
	s_waitcnt lgkmcnt(8)
	s_waitcnt vmcnt(10)
	s_barrier
	s_waitcnt lgkmcnt(0)
	s_setprio 1
	s_waitcnt lgkmcnt(0)
	v_mfma_f32_16x16x32_bf16 v[124:127], v[140:143], v[156:159], v[124:127]
	v_mfma_f32_16x16x32_bf16 v[120:123], v[148:151], v[156:159], v[120:123]
	v_mfma_f32_16x16x32_bf16 v[116:119], v[140:143], v[194:197], v[116:119]
	v_mfma_f32_16x16x32_bf16 v[112:115], v[148:151], v[194:197], v[112:115]
	v_mfma_f32_16x16x32_bf16 v[108:111], v[140:143], v[202:205], v[108:111]
	v_mfma_f32_16x16x32_bf16 v[104:107], v[148:151], v[202:205], v[104:107]
	v_mfma_f32_16x16x32_bf16 v[100:103], v[140:143], v[210:213], v[100:103]
	v_mfma_f32_16x16x32_bf16 v[96:99], v[148:151], v[210:213], v[96:99]
	v_mfma_f32_16x16x32_bf16 v[124:127], v[144:147], v[160:163], v[124:127]
	v_mfma_f32_16x16x32_bf16 v[120:123], v[152:155], v[160:163], v[120:123]
	v_mfma_f32_16x16x32_bf16 v[116:119], v[144:147], v[198:201], v[116:119]
	v_mfma_f32_16x16x32_bf16 v[112:115], v[152:155], v[198:201], v[112:115]
	v_mfma_f32_16x16x32_bf16 v[108:111], v[144:147], v[206:209], v[108:111]
	v_mfma_f32_16x16x32_bf16 v[104:107], v[152:155], v[206:209], v[104:107]
	v_mfma_f32_16x16x32_bf16 v[100:103], v[144:147], v[214:217], v[100:103]
	v_mfma_f32_16x16x32_bf16 v[96:99], v[152:155], v[214:217], v[96:99]
	s_setprio 0
	s_barrier
	v_readfirstlane_b32 s82, v189
	v_lshl_add_u64 v[234:235], s[60:61], 0, v[164:165]
	s_mov_b32 m0, s82
	v_readfirstlane_b32 s82, v188
	ds_read_b128 v[218:221], v135
	ds_read_b128 v[222:225], v135 offset:1024
	ds_read_b128 v[226:229], v135 offset:2048
	ds_read_b128 v[230:233], v135 offset:3072
	global_load_lds_dwordx4 v[234:235], off
	v_lshl_add_u64 v[236:237], v[234:235], 0, s[2:3]
	s_mov_b32 m0, s82
	s_nop 0
	global_load_lds_dwordx4 v[236:237], off
	s_waitcnt vmcnt(10)
	s_barrier
	s_waitcnt lgkmcnt(0)
	s_setprio 1
	s_waitcnt lgkmcnt(0)
	v_mfma_f32_16x16x32_bf16 v[92:95], v[218:221], v[156:159], v[92:95]
	v_mfma_f32_16x16x32_bf16 v[88:91], v[226:229], v[156:159], v[88:91]
	v_mfma_f32_16x16x32_bf16 v[84:87], v[218:221], v[194:197], v[84:87]
	v_mfma_f32_16x16x32_bf16 v[80:83], v[226:229], v[194:197], v[80:83]
	v_mfma_f32_16x16x32_bf16 v[76:79], v[218:221], v[202:205], v[76:79]
	v_mfma_f32_16x16x32_bf16 v[72:75], v[226:229], v[202:205], v[72:75]
	v_mfma_f32_16x16x32_bf16 v[68:71], v[218:221], v[210:213], v[68:71]
	v_mfma_f32_16x16x32_bf16 v[64:67], v[226:229], v[210:213], v[64:67]
	v_mfma_f32_16x16x32_bf16 v[92:95], v[222:225], v[160:163], v[92:95]
	v_mfma_f32_16x16x32_bf16 v[88:91], v[230:233], v[160:163], v[88:91]
	v_mfma_f32_16x16x32_bf16 v[84:87], v[222:225], v[198:201], v[84:87]
	v_mfma_f32_16x16x32_bf16 v[80:83], v[230:233], v[198:201], v[80:83]
	v_mfma_f32_16x16x32_bf16 v[76:79], v[222:225], v[206:209], v[76:79]
	v_mfma_f32_16x16x32_bf16 v[72:75], v[230:233], v[206:209], v[72:75]
	v_mfma_f32_16x16x32_bf16 v[68:71], v[222:225], v[214:217], v[68:71]
	v_mfma_f32_16x16x32_bf16 v[64:67], v[230:233], v[214:217], v[64:67]
	s_setprio 0
	v_readfirstlane_b32 s82, v169
	v_lshl_add_u64 v[236:237], v[128:129], 0, s[22:23]
	s_mov_b32 m0, s82
	v_readfirstlane_b32 s82, v187
	s_barrier
	ds_read_b128 v[156:159], v193 offset:16384
	ds_read_b128 v[160:163], v193 offset:17408
	ds_read_b128 v[194:197], v192 offset:16384
	ds_read_b128 v[198:201], v192 offset:17408
	ds_read_b128 v[202:205], v191 offset:16384
	ds_read_b128 v[206:209], v191 offset:17408
	ds_read_b128 v[210:213], v190 offset:16384
	ds_read_b128 v[214:217], v190 offset:17408
	global_load_lds_dwordx4 v[236:237], off
	v_lshl_add_u64 v[236:237], v[128:129], 0, s[24:25]
	s_mov_b32 m0, s82
	s_nop 0
	global_load_lds_dwordx4 v[236:237], off
	s_barrier
	s_waitcnt lgkmcnt(0)
	s_setprio 1
	s_waitcnt lgkmcnt(0)
	v_mfma_f32_16x16x32_bf16 v[60:63], v[140:143], v[156:159], v[60:63]
	v_mfma_f32_16x16x32_bf16 v[56:59], v[148:151], v[156:159], v[56:59]
	v_mfma_f32_16x16x32_bf16 v[52:55], v[140:143], v[194:197], v[52:55]
	v_mfma_f32_16x16x32_bf16 v[48:51], v[148:151], v[194:197], v[48:51]
	v_mfma_f32_16x16x32_bf16 v[44:47], v[140:143], v[202:205], v[44:47]
	v_mfma_f32_16x16x32_bf16 v[40:43], v[148:151], v[202:205], v[40:43]
	v_mfma_f32_16x16x32_bf16 v[36:39], v[140:143], v[210:213], v[36:39]
	v_mfma_f32_16x16x32_bf16 v[32:35], v[148:151], v[210:213], v[32:35]
	v_mfma_f32_16x16x32_bf16 v[60:63], v[144:147], v[160:163], v[60:63]
	v_mfma_f32_16x16x32_bf16 v[56:59], v[152:155], v[160:163], v[56:59]
	v_mfma_f32_16x16x32_bf16 v[52:55], v[144:147], v[198:201], v[52:55]
	v_mfma_f32_16x16x32_bf16 v[48:51], v[152:155], v[198:201], v[48:51]
	v_mfma_f32_16x16x32_bf16 v[44:47], v[144:147], v[206:209], v[44:47]
	v_mfma_f32_16x16x32_bf16 v[40:43], v[152:155], v[206:209], v[40:43]
	v_mfma_f32_16x16x32_bf16 v[36:39], v[144:147], v[214:217], v[36:39]
	v_mfma_f32_16x16x32_bf16 v[32:35], v[152:155], v[214:217], v[32:35]
	s_setprio 0
	s_barrier
	v_readfirstlane_b32 s82, v186
	v_lshl_add_u64 v[140:141], v[234:235], 0, s[6:7]
	s_mov_b32 m0, s82
	v_readfirstlane_b32 s82, v185
	global_load_lds_dwordx4 v[140:141], off
	v_lshl_add_u64 v[140:141], v[234:235], 0, s[8:9]
	s_mov_b32 m0, s82
	s_nop 0
	global_load_lds_dwordx4 v[140:141], off
	v_readfirstlane_b32 s82, v184
	v_lshl_add_u64 v[142:143], v[128:129], 0, s[26:27]
	s_mov_b32 m0, s82
	v_readfirstlane_b32 s82, v183
	global_load_lds_dwordx4 v[142:143], off
	s_mov_b32 m0, s82
	s_nop 0
	global_load_lds_dwordx4 v[128:129], off
	s_waitcnt vmcnt(12)
	s_barrier
	s_setprio 1
	v_mfma_f32_16x16x32_bf16 v[28:31], v[218:221], v[156:159], v[28:31]
	v_mfma_f32_16x16x32_bf16 v[24:27], v[226:229], v[156:159], v[24:27]
	v_mfma_f32_16x16x32_bf16 v[20:23], v[218:221], v[194:197], v[20:23]
	v_mfma_f32_16x16x32_bf16 v[16:19], v[226:229], v[194:197], v[16:19]
	v_mfma_f32_16x16x32_bf16 v[12:15], v[218:221], v[202:205], v[12:15]
	v_mfma_f32_16x16x32_bf16 v[8:11], v[226:229], v[202:205], v[8:11]
	v_mfma_f32_16x16x32_bf16 v[4:7], v[218:221], v[210:213], v[4:7]
	v_mfma_f32_16x16x32_bf16 v[0:3], v[226:229], v[210:213], v[0:3]
	v_mfma_f32_16x16x32_bf16 v[28:31], v[222:225], v[160:163], v[28:31]
	v_mfma_f32_16x16x32_bf16 v[24:27], v[230:233], v[160:163], v[24:27]
	v_mfma_f32_16x16x32_bf16 v[20:23], v[222:225], v[198:201], v[20:23]
	v_mfma_f32_16x16x32_bf16 v[16:19], v[230:233], v[198:201], v[16:19]
	v_mfma_f32_16x16x32_bf16 v[12:15], v[222:225], v[206:209], v[12:15]
	v_mfma_f32_16x16x32_bf16 v[8:11], v[230:233], v[206:209], v[8:11]
	v_mfma_f32_16x16x32_bf16 v[4:7], v[222:225], v[214:217], v[4:7]
	v_mfma_f32_16x16x32_bf16 v[0:3], v[230:233], v[214:217], v[0:3]
	s_setprio 0
	s_barrier
	ds_read_b128 v[140:143], v130
	ds_read_b128 v[144:147], v130 offset:1024
	ds_read_b128 v[148:151], v130 offset:2048
	ds_read_b128 v[152:155], v130 offset:3072
	ds_read_b128 v[156:159], v193 offset:32768
	ds_read_b128 v[160:163], v193 offset:33792
	ds_read_b128 v[194:197], v192 offset:32768
	ds_read_b128 v[198:201], v192 offset:33792
	ds_read_b128 v[202:205], v191 offset:32768
	ds_read_b128 v[206:209], v191 offset:33792
	ds_read_b128 v[210:213], v190 offset:32768
	ds_read_b128 v[214:217], v190 offset:33792
	s_waitcnt lgkmcnt(8)
	s_waitcnt vmcnt(10)
	s_barrier
	s_waitcnt lgkmcnt(0)
	s_setprio 1
	s_waitcnt lgkmcnt(0)
	v_mfma_f32_16x16x32_bf16 v[124:127], v[140:143], v[156:159], v[124:127]
	v_mfma_f32_16x16x32_bf16 v[120:123], v[148:151], v[156:159], v[120:123]
	v_mfma_f32_16x16x32_bf16 v[116:119], v[140:143], v[194:197], v[116:119]
	v_mfma_f32_16x16x32_bf16 v[112:115], v[148:151], v[194:197], v[112:115]
	v_mfma_f32_16x16x32_bf16 v[108:111], v[140:143], v[202:205], v[108:111]
	v_mfma_f32_16x16x32_bf16 v[104:107], v[148:151], v[202:205], v[104:107]
	v_mfma_f32_16x16x32_bf16 v[100:103], v[140:143], v[210:213], v[100:103]
	v_mfma_f32_16x16x32_bf16 v[96:99], v[148:151], v[210:213], v[96:99]
	v_mfma_f32_16x16x32_bf16 v[124:127], v[144:147], v[160:163], v[124:127]
	v_mfma_f32_16x16x32_bf16 v[120:123], v[152:155], v[160:163], v[120:123]
	v_mfma_f32_16x16x32_bf16 v[116:119], v[144:147], v[198:201], v[116:119]
	v_mfma_f32_16x16x32_bf16 v[112:115], v[152:155], v[198:201], v[112:115]
	v_mfma_f32_16x16x32_bf16 v[108:111], v[144:147], v[206:209], v[108:111]
	v_mfma_f32_16x16x32_bf16 v[104:107], v[152:155], v[206:209], v[104:107]
	v_mfma_f32_16x16x32_bf16 v[100:103], v[144:147], v[214:217], v[100:103]
	v_mfma_f32_16x16x32_bf16 v[96:99], v[152:155], v[214:217], v[96:99]
	s_setprio 0
	s_barrier
	v_readfirstlane_b32 s82, v182
	v_lshl_add_u64 v[234:235], s[56:57], 0, v[164:165]
	s_mov_b32 m0, s82
	v_readfirstlane_b32 s82, v181
	ds_read_b128 v[218:221], v132
	ds_read_b128 v[222:225], v132 offset:1024
	ds_read_b128 v[226:229], v132 offset:2048
	ds_read_b128 v[230:233], v132 offset:3072
	global_load_lds_dwordx4 v[234:235], off
	v_lshl_add_u64 v[236:237], v[234:235], 0, s[2:3]
	s_mov_b32 m0, s82
	s_nop 0
	global_load_lds_dwordx4 v[236:237], off
	s_waitcnt vmcnt(10)
	s_barrier
	s_waitcnt lgkmcnt(0)
	s_setprio 1
	s_waitcnt lgkmcnt(0)
	v_mfma_f32_16x16x32_bf16 v[92:95], v[218:221], v[156:159], v[92:95]
	v_mfma_f32_16x16x32_bf16 v[88:91], v[226:229], v[156:159], v[88:91]
	v_mfma_f32_16x16x32_bf16 v[84:87], v[218:221], v[194:197], v[84:87]
	v_mfma_f32_16x16x32_bf16 v[80:83], v[226:229], v[194:197], v[80:83]
	v_mfma_f32_16x16x32_bf16 v[76:79], v[218:221], v[202:205], v[76:79]
	v_mfma_f32_16x16x32_bf16 v[72:75], v[226:229], v[202:205], v[72:75]
	v_mfma_f32_16x16x32_bf16 v[68:71], v[218:221], v[210:213], v[68:71]
	v_mfma_f32_16x16x32_bf16 v[64:67], v[226:229], v[210:213], v[64:67]
	v_mfma_f32_16x16x32_bf16 v[92:95], v[222:225], v[160:163], v[92:95]
	v_mfma_f32_16x16x32_bf16 v[88:91], v[230:233], v[160:163], v[88:91]
	v_mfma_f32_16x16x32_bf16 v[84:87], v[222:225], v[198:201], v[84:87]
	v_mfma_f32_16x16x32_bf16 v[80:83], v[230:233], v[198:201], v[80:83]
	v_mfma_f32_16x16x32_bf16 v[76:79], v[222:225], v[206:209], v[76:79]
	v_mfma_f32_16x16x32_bf16 v[72:75], v[230:233], v[206:209], v[72:75]
	v_mfma_f32_16x16x32_bf16 v[68:71], v[222:225], v[214:217], v[68:71]
	v_mfma_f32_16x16x32_bf16 v[64:67], v[230:233], v[214:217], v[64:67]
	s_setprio 0
	v_readfirstlane_b32 s82, v177
	v_lshl_add_u64 v[236:237], v[128:129], 0, s[28:29]
	s_mov_b32 m0, s82
	v_readfirstlane_b32 s82, v175
	s_barrier
	ds_read_b128 v[156:159], v193 offset:49152
	ds_read_b128 v[160:163], v193 offset:50176
	ds_read_b128 v[194:197], v192 offset:49152
	ds_read_b128 v[198:201], v192 offset:50176
	ds_read_b128 v[202:205], v191 offset:49152
	ds_read_b128 v[206:209], v191 offset:50176
	ds_read_b128 v[210:213], v190 offset:49152
	ds_read_b128 v[214:217], v190 offset:50176
	global_load_lds_dwordx4 v[236:237], off
	v_lshl_add_u64 v[236:237], v[128:129], 0, s[30:31]
	s_mov_b32 m0, s82
	s_nop 0
	global_load_lds_dwordx4 v[236:237], off
	s_barrier
	s_waitcnt lgkmcnt(0)
	s_setprio 1
	s_waitcnt lgkmcnt(0)
	v_mfma_f32_16x16x32_bf16 v[60:63], v[140:143], v[156:159], v[60:63]
	v_mfma_f32_16x16x32_bf16 v[56:59], v[148:151], v[156:159], v[56:59]
	v_mfma_f32_16x16x32_bf16 v[52:55], v[140:143], v[194:197], v[52:55]
	v_mfma_f32_16x16x32_bf16 v[48:51], v[148:151], v[194:197], v[48:51]
	v_mfma_f32_16x16x32_bf16 v[44:47], v[140:143], v[202:205], v[44:47]
	v_mfma_f32_16x16x32_bf16 v[40:43], v[148:151], v[202:205], v[40:43]
	v_mfma_f32_16x16x32_bf16 v[36:39], v[140:143], v[210:213], v[36:39]
	v_mfma_f32_16x16x32_bf16 v[32:35], v[148:151], v[210:213], v[32:35]
	v_mfma_f32_16x16x32_bf16 v[60:63], v[144:147], v[160:163], v[60:63]
	v_mfma_f32_16x16x32_bf16 v[56:59], v[152:155], v[160:163], v[56:59]
	v_mfma_f32_16x16x32_bf16 v[52:55], v[144:147], v[198:201], v[52:55]
	v_mfma_f32_16x16x32_bf16 v[48:51], v[152:155], v[198:201], v[48:51]
	v_mfma_f32_16x16x32_bf16 v[44:47], v[144:147], v[206:209], v[44:47]
	v_mfma_f32_16x16x32_bf16 v[40:43], v[152:155], v[206:209], v[40:43]
	v_mfma_f32_16x16x32_bf16 v[36:39], v[144:147], v[214:217], v[36:39]
	v_mfma_f32_16x16x32_bf16 v[32:35], v[152:155], v[214:217], v[32:35]
	s_setprio 0
	s_barrier
	v_readfirstlane_b32 s82, v173
	v_lshl_add_u64 v[140:141], v[234:235], 0, s[6:7]
	s_mov_b32 m0, s82
	v_readfirstlane_b32 s82, v171
	global_load_lds_dwordx4 v[140:141], off
	v_lshl_add_u64 v[140:141], v[234:235], 0, s[8:9]
	s_mov_b32 m0, s82
	s_nop 0
	global_load_lds_dwordx4 v[140:141], off
	v_lshl_add_u64 v[128:129], v[128:129], 0, s[34:35]
	v_readfirstlane_b32 s82, v137
	v_lshl_add_u64 v[142:143], v[128:129], 0, s[18:19]
	s_mov_b32 m0, s82
	v_readfirstlane_b32 s82, v136
	global_load_lds_dwordx4 v[142:143], off
	v_lshl_add_u64 v[142:143], v[128:129], 0, s[20:21]
	s_mov_b32 m0, s82
	s_nop 0
	global_load_lds_dwordx4 v[142:143], off
	s_waitcnt vmcnt(12)
	s_barrier
	s_setprio 1
	v_mfma_f32_16x16x32_bf16 v[28:31], v[218:221], v[156:159], v[28:31]
	v_mfma_f32_16x16x32_bf16 v[24:27], v[226:229], v[156:159], v[24:27]
	v_mfma_f32_16x16x32_bf16 v[20:23], v[218:221], v[194:197], v[20:23]
	v_mfma_f32_16x16x32_bf16 v[16:19], v[226:229], v[194:197], v[16:19]
	v_mfma_f32_16x16x32_bf16 v[12:15], v[218:221], v[202:205], v[12:15]
	v_mfma_f32_16x16x32_bf16 v[8:11], v[226:229], v[202:205], v[8:11]
	v_mfma_f32_16x16x32_bf16 v[4:7], v[218:221], v[210:213], v[4:7]
	v_mfma_f32_16x16x32_bf16 v[0:3], v[226:229], v[210:213], v[0:3]
	v_mfma_f32_16x16x32_bf16 v[28:31], v[222:225], v[160:163], v[28:31]
	v_mfma_f32_16x16x32_bf16 v[24:27], v[230:233], v[160:163], v[24:27]
	v_mfma_f32_16x16x32_bf16 v[20:23], v[222:225], v[198:201], v[20:23]
	v_mfma_f32_16x16x32_bf16 v[16:19], v[230:233], v[198:201], v[16:19]
	v_mfma_f32_16x16x32_bf16 v[12:15], v[222:225], v[206:209], v[12:15]
	v_mfma_f32_16x16x32_bf16 v[8:11], v[230:233], v[206:209], v[8:11]
	v_mfma_f32_16x16x32_bf16 v[4:7], v[222:225], v[214:217], v[4:7]
	v_mfma_f32_16x16x32_bf16 v[0:3], v[230:233], v[214:217], v[0:3]
	s_setprio 0
	s_add_i32 s14, s14, 2
	s_add_u32 s56, s56, s58
	s_addc_u32 s57, s57, s59
	s_add_u32 s60, s60, s58
	s_addc_u32 s61, s61, s59
	s_cmp_lt_u32 s14, 28
	s_barrier
	s_cbranch_scc1 .LBB0_234
	s_lshl_b32 s14, s62, 3
	s_or_b32 s82, s63, s14
	s_lshl_b32 s56, s82, 8
	v_lshlrev_b32_e32 v128, 3, v131
	v_lshlrev_b32_e32 v129, 5, v131
	s_or_b32 s14, s56, 0x80
	v_and_b32_e32 v128, 0x7fff0, v128
	v_and_b32_e32 v129, 32, v129
	s_lshl_b64 s[58:59], s[14:15], 13
	v_add_u32_e32 v129, v129, v134
	v_add_lshl_u32 v128, v133, v128, 13
	s_add_u32 s58, s40, s58
	v_lshl_add_u32 v164, v129, 1, v128
	s_addc_u32 s59, s41, s59
	v_lshl_add_u64 v[128:129], s[58:59], 0, v[164:165]
	v_readfirstlane_b32 s14, v137
	ds_read_b128 v[140:143], v138
	ds_read_b128 v[144:147], v138 offset:1024
	ds_read_b128 v[148:151], v138 offset:2048
	ds_read_b128 v[152:155], v138 offset:3072
	ds_read_b128 v[156:159], v193
	ds_read_b128 v[160:163], v193 offset:1024
	ds_read_b128 v[194:197], v192
	ds_read_b128 v[198:201], v192 offset:1024
	ds_read_b128 v[202:205], v191
	ds_read_b128 v[206:209], v191 offset:1024
	ds_read_b128 v[210:213], v190
	ds_read_b128 v[214:217], v190 offset:1024
	v_lshl_add_u64 v[138:139], v[128:129], 0, s[44:45]
	s_mov_b32 m0, s14
	v_readfirstlane_b32 s14, v136
	global_load_lds_dwordx4 v[138:139], off
	v_lshl_add_u64 v[128:129], v[128:129], 0, s[46:47]
	s_mov_b32 m0, s14
	s_mov_b32 s57, s15
	global_load_lds_dwordx4 v[128:129], off
	s_waitcnt vmcnt(10)
	s_barrier
	s_waitcnt lgkmcnt(0)
	s_setprio 1
	s_waitcnt lgkmcnt(0)
	v_mfma_f32_16x16x32_bf16 v[124:127], v[140:143], v[156:159], v[124:127]
	v_mfma_f32_16x16x32_bf16 v[120:123], v[148:151], v[156:159], v[120:123]
	v_mfma_f32_16x16x32_bf16 v[116:119], v[140:143], v[194:197], v[116:119]
	v_mfma_f32_16x16x32_bf16 v[112:115], v[148:151], v[194:197], v[112:115]
	v_mfma_f32_16x16x32_bf16 v[108:111], v[140:143], v[202:205], v[108:111]
	v_mfma_f32_16x16x32_bf16 v[104:107], v[148:151], v[202:205], v[104:107]
	v_mfma_f32_16x16x32_bf16 v[100:103], v[140:143], v[210:213], v[100:103]
	v_mfma_f32_16x16x32_bf16 v[96:99], v[148:151], v[210:213], v[96:99]
	v_mfma_f32_16x16x32_bf16 v[124:127], v[144:147], v[160:163], v[124:127]
	v_mfma_f32_16x16x32_bf16 v[120:123], v[152:155], v[160:163], v[120:123]
	v_mfma_f32_16x16x32_bf16 v[116:119], v[144:147], v[198:201], v[116:119]
	v_mfma_f32_16x16x32_bf16 v[112:115], v[152:155], v[198:201], v[112:115]
	v_mfma_f32_16x16x32_bf16 v[108:111], v[144:147], v[206:209], v[108:111]
	v_mfma_f32_16x16x32_bf16 v[104:107], v[152:155], v[206:209], v[104:107]
	v_mfma_f32_16x16x32_bf16 v[100:103], v[144:147], v[214:217], v[100:103]
	v_mfma_f32_16x16x32_bf16 v[96:99], v[152:155], v[214:217], v[96:99]
	s_setprio 0
	s_barrier
	ds_read_b128 v[136:139], v135
	ds_read_b128 v[218:221], v135 offset:1024
	ds_read_b128 v[222:225], v135 offset:2048
	ds_read_b128 v[226:229], v135 offset:3072
	s_barrier
	s_waitcnt lgkmcnt(0)
	s_setprio 1
	s_waitcnt lgkmcnt(0)
	v_mfma_f32_16x16x32_bf16 v[92:95], v[136:139], v[156:159], v[92:95]
	v_mfma_f32_16x16x32_bf16 v[84:87], v[136:139], v[194:197], v[84:87]
	v_mfma_f32_16x16x32_bf16 v[80:83], v[222:225], v[194:197], v[80:83]
	v_mfma_f32_16x16x32_bf16 v[88:91], v[222:225], v[156:159], v[88:91]
	v_mfma_f32_16x16x32_bf16 v[76:79], v[136:139], v[202:205], v[76:79]
	v_mfma_f32_16x16x32_bf16 v[72:75], v[222:225], v[202:205], v[72:75]
	v_mfma_f32_16x16x32_bf16 v[68:71], v[136:139], v[210:213], v[68:71]
	v_mfma_f32_16x16x32_bf16 v[64:67], v[222:225], v[210:213], v[64:67]
	v_mfma_f32_16x16x32_bf16 v[156:159], v[218:221], v[160:163], v[92:95]
	v_mfma_f32_16x16x32_bf16 v[194:197], v[218:221], v[198:201], v[84:87]
	v_mfma_f32_16x16x32_bf16 v[198:201], v[226:229], v[198:201], v[80:83]
	v_mfma_f32_16x16x32_bf16 v[160:163], v[226:229], v[160:163], v[88:91]
	v_mfma_f32_16x16x32_bf16 v[202:205], v[218:221], v[206:209], v[76:79]
	v_mfma_f32_16x16x32_bf16 v[206:209], v[226:229], v[206:209], v[72:75]
	v_mfma_f32_16x16x32_bf16 v[210:213], v[218:221], v[214:217], v[68:71]
	v_mfma_f32_16x16x32_bf16 v[214:217], v[226:229], v[214:217], v[64:67]
	s_setprio 0
	s_barrier
	s_nop 0
	ds_read_b128 v[64:67], v193 offset:16384
	ds_read_b128 v[68:71], v193 offset:17408
	ds_read_b128 v[72:75], v192 offset:16384
	ds_read_b128 v[76:79], v192 offset:17408
	ds_read_b128 v[80:83], v191 offset:16384
	ds_read_b128 v[84:87], v191 offset:17408
	ds_read_b128 v[88:91], v190 offset:16384
	ds_read_b128 v[92:95], v190 offset:17408
	s_waitcnt vmcnt(4)
	s_barrier
	s_waitcnt lgkmcnt(0)
	s_setprio 1
	s_waitcnt lgkmcnt(0)
	v_mfma_f32_16x16x32_bf16 v[60:63], v[140:143], v[64:67], v[60:63]
	v_mfma_f32_16x16x32_bf16 v[56:59], v[148:151], v[64:67], v[56:59]
	v_mfma_f32_16x16x32_bf16 v[52:55], v[140:143], v[72:75], v[52:55]
	v_mfma_f32_16x16x32_bf16 v[48:51], v[148:151], v[72:75], v[48:51]
	v_mfma_f32_16x16x32_bf16 v[230:233], v[140:143], v[80:83], v[44:47]
	v_mfma_f32_16x16x32_bf16 v[234:237], v[148:151], v[80:83], v[40:43]
	v_mfma_f32_16x16x32_bf16 v[140:143], v[140:143], v[88:91], v[36:39]
	v_mfma_f32_16x16x32_bf16 v[148:151], v[148:151], v[88:91], v[32:35]
	v_mfma_f32_16x16x32_bf16 v[32:35], v[144:147], v[68:71], v[60:63]
	v_mfma_f32_16x16x32_bf16 v[36:39], v[152:155], v[68:71], v[56:59]
	v_mfma_f32_16x16x32_bf16 v[40:43], v[144:147], v[76:79], v[52:55]
	v_mfma_f32_16x16x32_bf16 v[44:47], v[152:155], v[76:79], v[48:51]
	v_mfma_f32_16x16x32_bf16 v[48:51], v[144:147], v[84:87], v[230:233]
	v_mfma_f32_16x16x32_bf16 v[52:55], v[152:155], v[84:87], v[234:237]
	v_mfma_f32_16x16x32_bf16 v[56:59], v[144:147], v[92:95], v[140:143]
	v_mfma_f32_16x16x32_bf16 v[60:63], v[152:155], v[92:95], v[148:151]
	s_setprio 0
	s_setprio 1
	v_mfma_f32_16x16x32_bf16 v[28:31], v[136:139], v[64:67], v[28:31]
	v_mfma_f32_16x16x32_bf16 v[24:27], v[222:225], v[64:67], v[24:27]
	v_mfma_f32_16x16x32_bf16 v[20:23], v[136:139], v[72:75], v[20:23]
	v_mfma_f32_16x16x32_bf16 v[64:67], v[222:225], v[72:75], v[16:19]
	v_mfma_f32_16x16x32_bf16 v[12:15], v[136:139], v[80:83], v[12:15]
	v_mfma_f32_16x16x32_bf16 v[8:11], v[222:225], v[80:83], v[8:11]
	v_mfma_f32_16x16x32_bf16 v[72:75], v[136:139], v[88:91], v[4:7]
	v_mfma_f32_16x16x32_bf16 v[80:83], v[222:225], v[88:91], v[0:3]
	v_mfma_f32_16x16x32_bf16 v[0:3], v[218:221], v[68:71], v[28:31]
	v_mfma_f32_16x16x32_bf16 v[4:7], v[226:229], v[68:71], v[24:27]
	v_mfma_f32_16x16x32_bf16 v[16:19], v[218:221], v[76:79], v[20:23]
	v_mfma_f32_16x16x32_bf16 v[20:23], v[226:229], v[76:79], v[64:67]
	v_mfma_f32_16x16x32_bf16 v[24:27], v[218:221], v[84:87], v[12:15]
	v_mfma_f32_16x16x32_bf16 v[28:31], v[226:229], v[84:87], v[8:11]
	v_mfma_f32_16x16x32_bf16 v[64:67], v[218:221], v[92:95], v[72:75]
	v_mfma_f32_16x16x32_bf16 v[68:71], v[226:229], v[92:95], v[80:83]
	s_setprio 0
	s_barrier
	ds_read_b128 v[12:15], v130
	ds_read_b128 v[8:11], v130 offset:1024
	ds_read_b128 v[76:79], v130 offset:2048
	ds_read_b128 v[72:75], v130 offset:3072
	ds_read_b128 v[140:143], v193 offset:32768
	ds_read_b128 v[148:151], v193 offset:33792
	ds_read_b128 v[218:221], v192 offset:32768
	ds_read_b128 v[222:225], v192 offset:33792
	ds_read_b128 v[226:229], v191 offset:32768
	ds_read_b128 v[230:233], v191 offset:33792
	ds_read_b128 v[234:237], v190 offset:32768
	ds_read_b128 v[238:241], v190 offset:33792
	s_waitcnt vmcnt(2)
	s_barrier
	s_waitcnt lgkmcnt(0)
	s_setprio 1
	s_waitcnt lgkmcnt(0)
	v_mfma_f32_16x16x32_bf16 v[80:83], v[12:15], v[140:143], v[124:127]
	v_mfma_f32_16x16x32_bf16 v[84:87], v[76:79], v[140:143], v[120:123]
	v_mfma_f32_16x16x32_bf16 v[88:91], v[12:15], v[218:221], v[116:119]
	v_mfma_f32_16x16x32_bf16 v[92:95], v[76:79], v[218:221], v[112:115]
	v_mfma_f32_16x16x32_bf16 v[108:111], v[12:15], v[226:229], v[108:111]
	v_mfma_f32_16x16x32_bf16 v[104:107], v[76:79], v[226:229], v[104:107]
	v_mfma_f32_16x16x32_bf16 v[100:103], v[12:15], v[234:237], v[100:103]
	v_mfma_f32_16x16x32_bf16 v[96:99], v[76:79], v[234:237], v[96:99]
	v_mfma_f32_16x16x32_bf16 v[152:155], v[8:11], v[148:151], v[80:83]
	v_mfma_f32_16x16x32_bf16 v[144:147], v[72:75], v[148:151], v[84:87]
	v_mfma_f32_16x16x32_bf16 v[136:139], v[8:11], v[222:225], v[88:91]
	v_mfma_f32_16x16x32_bf16 v[128:131], v[72:75], v[222:225], v[92:95]
	v_mfma_f32_16x16x32_bf16 v[120:123], v[8:11], v[230:233], v[108:111]
	v_mfma_f32_16x16x32_bf16 v[112:115], v[72:75], v[230:233], v[104:107]
	v_mfma_f32_16x16x32_bf16 v[104:107], v[8:11], v[238:241], v[100:103]
	v_mfma_f32_16x16x32_bf16 v[96:99], v[72:75], v[238:241], v[96:99]
	s_setprio 0
	s_barrier
	ds_read_b128 v[88:91], v132
	ds_read_b128 v[80:83], v132 offset:1024
	ds_read_b128 v[92:95], v132 offset:2048
	ds_read_b128 v[84:87], v132 offset:3072
	s_waitcnt vmcnt(0)
	s_barrier
	s_waitcnt lgkmcnt(0)
	s_setprio 1
	s_waitcnt lgkmcnt(0)
	v_mfma_f32_16x16x32_bf16 v[100:103], v[88:91], v[140:143], v[156:159]
	v_mfma_f32_16x16x32_bf16 v[108:111], v[92:95], v[140:143], v[160:163]
	v_mfma_f32_16x16x32_bf16 v[116:119], v[88:91], v[218:221], v[194:197]
	v_mfma_f32_16x16x32_bf16 v[124:127], v[92:95], v[218:221], v[198:201]
	v_mfma_f32_16x16x32_bf16 v[160:163], v[88:91], v[226:229], v[202:205]
	v_mfma_f32_16x16x32_bf16 v[194:197], v[92:95], v[226:229], v[206:209]
	v_mfma_f32_16x16x32_bf16 v[198:201], v[88:91], v[234:237], v[210:213]
	v_mfma_f32_16x16x32_bf16 v[202:205], v[92:95], v[234:237], v[214:217]
	v_mfma_f32_16x16x32_bf16 v[156:159], v[80:83], v[148:151], v[100:103]
	v_mfma_f32_16x16x32_bf16 v[148:151], v[84:87], v[148:151], v[108:111]
	v_mfma_f32_16x16x32_bf16 v[140:143], v[80:83], v[222:225], v[116:119]
	v_mfma_f32_16x16x32_bf16 v[132:135], v[84:87], v[222:225], v[124:127]
	v_mfma_f32_16x16x32_bf16 v[124:127], v[80:83], v[230:233], v[160:163]
	v_mfma_f32_16x16x32_bf16 v[116:119], v[84:87], v[230:233], v[194:197]
	v_mfma_f32_16x16x32_bf16 v[108:111], v[80:83], v[238:241], v[198:201]
	v_mfma_f32_16x16x32_bf16 v[100:103], v[84:87], v[238:241], v[202:205]
	s_setprio 0
	s_lshl_b64 s[58:59], s[56:57], 2
	s_barrier
	v_mbcnt_lo_u32_b32 v162, -1, 0
	v_mbcnt_hi_u32_b32 v162, -1, v162
	s_add_u32 s58, s87, s58
	v_add_u32_e32 v160, s64, v162
	s_addc_u32 s59, s88, s59
	v_and_b32_e32 v164, 0x100, v160
	v_and_b32_e32 v162, 15, v162
	v_lshl_add_u64 v[160:161], s[58:59], 0, v[164:165]
	v_lshlrev_b32_e32 v164, 2, v162
	v_lshl_add_u64 v[160:161], v[160:161], 0, v[164:165]
	global_load_dword v180, v[160:161], off
	global_load_dword v178, v[160:161], off offset:64
	global_load_dword v176, v[160:161], off offset:128
	global_load_dword v174, v[160:161], off offset:192
	global_load_dword v172, v[160:161], off offset:512
	global_load_dword v170, v[160:161], off offset:576
	global_load_dword v168, v[160:161], off offset:640
	global_load_dword v166, v[160:161], off offset:704
	v_mbcnt_lo_u32_b32 v194, -1, 0
	v_mbcnt_hi_u32_b32 v194, -1, v194
	s_cmp_lg_u32 s81, 0
	v_add_u32_e32 v160, s64, v194
	v_bfe_u32 v196, v160, 8, 1
	v_ashrrev_i32_e32 v199, 6, v160
	v_bfe_u32 v160, v194, 4, 2
	s_cselect_b64 s[58:59], -1, 0
	v_and_b32_e32 v197, 3, v199
	v_and_b32_e32 v195, 15, v194
	s_and_b64 vcc, exec, s[58:59]
	v_lshlrev_b32_e32 v198, 4, v160
	s_cbranch_vccz .LBB0_246
	s_lshl_b32 s14, s80, 22
	s_lshl_b32 s57, s82, 14
	s_add_i32 s57, s57, s14
	v_lshlrev_b32_e32 v160, 6, v195
	v_or3_b32 v160, s57, v160, v198
	v_lshl_add_u32 v160, v197, 20, v160
	v_lshl_or_b32 v164, v196, 12, v160
	s_waitcnt vmcnt(0)
	v_pk_mul_f32 v[160:161], v[154:155], v[180:181] op_sel_hi:[1,0]
	v_pk_mul_f32 v[200:201], v[146:147], v[180:181] op_sel_hi:[1,0]
	v_max_f32_e32 v160, 0, v160
	v_mul_f32_e32 v204, v160, v160
	v_max_f32_e32 v160, 0, v200
	v_pk_mul_f32 v[162:163], v[152:153], v[180:181] op_sel_hi:[1,0]
	v_mul_f32_e32 v200, v160, v160
	v_max_f32_e32 v160, 0, v161
	v_pk_mul_f32 v[202:203], v[144:145], v[180:181] op_sel_hi:[1,0]
	v_max_f32_e32 v162, 0, v162
	v_max_f32_e32 v163, 0, v163
	v_mul_f32_e32 v161, v160, v160
	v_max_f32_e32 v160, 0, v201
	v_mul_f32_e32 v162, v162, v162
	v_max_f32_e32 v202, 0, v202
	v_mul_f32_e32 v163, v163, v163
	v_max_f32_e32 v203, 0, v203
	v_mul_f32_e32 v201, v160, v160
	v_cvt_pk_bf16_f32 v160, v162, v163
	v_cvt_pk_bf16_f32 v161, v204, v161
	v_mul_f32_e32 v202, v202, v202
	v_mul_f32_e32 v203, v203, v203
	v_cvt_pk_bf16_f32 v162, v202, v203
	v_cvt_pk_bf16_f32 v163, v200, v201
	global_store_dwordx4 v164, v[160:163], s[0:1]
	v_pk_mul_f32 v[202:203], v[150:151], v[180:181] op_sel_hi:[1,0]
	v_lshl_add_u64 v[200:201], s[0:1], 0, v[164:165]
	v_pk_mul_f32 v[160:161], v[158:159], v[180:181] op_sel_hi:[1,0]
	v_pk_mul_f32 v[162:163], v[156:157], v[180:181] op_sel_hi:[1,0]
	v_max_f32_e32 v160, 0, v160
	v_mul_f32_e32 v206, v160, v160
	v_max_f32_e32 v160, 0, v202
	v_mul_f32_e32 v202, v160, v160
	v_max_f32_e32 v160, 0, v161
	v_pk_mul_f32 v[204:205], v[148:149], v[180:181] op_sel_hi:[1,0]
	v_max_f32_e32 v162, 0, v162
	v_max_f32_e32 v163, 0, v163
	v_mul_f32_e32 v161, v160, v160
	v_max_f32_e32 v160, 0, v203
	v_add_co_u32_e32 v200, vcc, s74, v200
	v_mul_f32_e32 v162, v162, v162
	v_max_f32_e32 v204, 0, v204
	v_mul_f32_e32 v163, v163, v163
	v_max_f32_e32 v205, 0, v205
	v_mul_f32_e32 v203, v160, v160
	v_cvt_pk_bf16_f32 v160, v162, v163
	v_cvt_pk_bf16_f32 v161, v206, v161
	v_addc_co_u32_e32 v201, vcc, 0, v201, vcc
	v_mul_f32_e32 v204, v204, v204
	v_mul_f32_e32 v205, v205, v205
	v_cvt_pk_bf16_f32 v162, v204, v205
	v_cvt_pk_bf16_f32 v163, v202, v203
	global_store_dwordx4 v[200:201], v[160:163], off
	v_pk_mul_f32 v[202:203], v[130:131], v[178:179] op_sel_hi:[1,0]
	v_pk_mul_f32 v[204:205], v[128:129], v[178:179] op_sel_hi:[1,0]
	v_pk_mul_f32 v[160:161], v[138:139], v[178:179] op_sel_hi:[1,0]
	v_pk_mul_f32 v[162:163], v[136:137], v[178:179] op_sel_hi:[1,0]
	v_max_f32_e32 v160, 0, v160
	v_mul_f32_e32 v206, v160, v160
	v_max_f32_e32 v160, 0, v202
	v_mul_f32_e32 v202, v160, v160
	v_max_f32_e32 v160, 0, v161
	v_max_f32_e32 v162, 0, v162
	v_max_f32_e32 v163, 0, v163
	v_mul_f32_e32 v161, v160, v160
	v_max_f32_e32 v160, 0, v203
	v_mul_f32_e32 v162, v162, v162
	v_max_f32_e32 v204, 0, v204
	v_mul_f32_e32 v163, v163, v163
	v_max_f32_e32 v205, 0, v205
	v_mul_f32_e32 v203, v160, v160
	v_cvt_pk_bf16_f32 v160, v162, v163
	v_cvt_pk_bf16_f32 v161, v206, v161
	v_mul_f32_e32 v204, v204, v204
	v_mul_f32_e32 v205, v205, v205
	v_cvt_pk_bf16_f32 v162, v204, v205
	v_cvt_pk_bf16_f32 v163, v202, v203
	global_store_dwordx4 v164, v[160:163], s[0:1] offset:1024
	v_pk_mul_f32 v[202:203], v[134:135], v[178:179] op_sel_hi:[1,0]
	v_pk_mul_f32 v[204:205], v[132:133], v[178:179] op_sel_hi:[1,0]
	v_pk_mul_f32 v[160:161], v[142:143], v[178:179] op_sel_hi:[1,0]
	v_pk_mul_f32 v[162:163], v[140:141], v[178:179] op_sel_hi:[1,0]
	v_max_f32_e32 v160, 0, v160
	v_mul_f32_e32 v206, v160, v160
	v_max_f32_e32 v160, 0, v202
	v_mul_f32_e32 v202, v160, v160
	v_max_f32_e32 v160, 0, v161
	v_max_f32_e32 v162, 0, v162
	v_max_f32_e32 v163, 0, v163
	v_mul_f32_e32 v161, v160, v160
	v_max_f32_e32 v160, 0, v203
	v_mul_f32_e32 v162, v162, v162
	v_max_f32_e32 v204, 0, v204
	v_mul_f32_e32 v163, v163, v163
	v_max_f32_e32 v205, 0, v205
	v_mul_f32_e32 v203, v160, v160
	v_cvt_pk_bf16_f32 v160, v162, v163
	v_cvt_pk_bf16_f32 v161, v206, v161
	v_mul_f32_e32 v204, v204, v204
	v_mul_f32_e32 v205, v205, v205
	v_cvt_pk_bf16_f32 v162, v204, v205
	v_cvt_pk_bf16_f32 v163, v202, v203
	global_store_dwordx4 v[200:201], v[160:163], off offset:1024
	v_pk_mul_f32 v[202:203], v[114:115], v[176:177] op_sel_hi:[1,0]
	v_pk_mul_f32 v[204:205], v[112:113], v[176:177] op_sel_hi:[1,0]
	v_pk_mul_f32 v[160:161], v[122:123], v[176:177] op_sel_hi:[1,0]
	v_pk_mul_f32 v[162:163], v[120:121], v[176:177] op_sel_hi:[1,0]
	v_max_f32_e32 v160, 0, v160
	v_mul_f32_e32 v206, v160, v160
	v_max_f32_e32 v160, 0, v202
	v_mul_f32_e32 v202, v160, v160
	v_max_f32_e32 v160, 0, v161
	v_max_f32_e32 v162, 0, v162
	v_max_f32_e32 v163, 0, v163
	v_mul_f32_e32 v161, v160, v160
	v_max_f32_e32 v160, 0, v203
	v_mul_f32_e32 v162, v162, v162
	v_max_f32_e32 v204, 0, v204
	v_mul_f32_e32 v163, v163, v163
	v_max_f32_e32 v205, 0, v205
	v_mul_f32_e32 v203, v160, v160
	v_cvt_pk_bf16_f32 v160, v162, v163
	v_cvt_pk_bf16_f32 v161, v206, v161
	v_mul_f32_e32 v204, v204, v204
	v_mul_f32_e32 v205, v205, v205
	v_cvt_pk_bf16_f32 v162, v204, v205
	v_cvt_pk_bf16_f32 v163, v202, v203
	global_store_dwordx4 v164, v[160:163], s[0:1] offset:2048
	v_pk_mul_f32 v[202:203], v[118:119], v[176:177] op_sel_hi:[1,0]
	v_pk_mul_f32 v[204:205], v[116:117], v[176:177] op_sel_hi:[1,0]
	v_pk_mul_f32 v[160:161], v[126:127], v[176:177] op_sel_hi:[1,0]
	v_pk_mul_f32 v[162:163], v[124:125], v[176:177] op_sel_hi:[1,0]
	v_max_f32_e32 v160, 0, v160
	v_mul_f32_e32 v206, v160, v160
	v_max_f32_e32 v160, 0, v202
	v_mul_f32_e32 v202, v160, v160
	v_max_f32_e32 v160, 0, v161
	v_max_f32_e32 v162, 0, v162
	v_max_f32_e32 v163, 0, v163
	v_mul_f32_e32 v161, v160, v160
	v_max_f32_e32 v160, 0, v203
	v_mul_f32_e32 v162, v162, v162
	v_max_f32_e32 v204, 0, v204
	v_mul_f32_e32 v163, v163, v163
	v_max_f32_e32 v205, 0, v205
	v_mul_f32_e32 v203, v160, v160
	v_cvt_pk_bf16_f32 v160, v162, v163
	v_cvt_pk_bf16_f32 v161, v206, v161
	v_mul_f32_e32 v204, v204, v204
	v_mul_f32_e32 v205, v205, v205
	v_cvt_pk_bf16_f32 v162, v204, v205
	v_cvt_pk_bf16_f32 v163, v202, v203
	global_store_dwordx4 v[200:201], v[160:163], off offset:2048
	v_pk_mul_f32 v[200:201], v[98:99], v[174:175] op_sel_hi:[1,0]
	v_pk_mul_f32 v[202:203], v[96:97], v[174:175] op_sel_hi:[1,0]
	v_pk_mul_f32 v[160:161], v[106:107], v[174:175] op_sel_hi:[1,0]
	v_pk_mul_f32 v[162:163], v[104:105], v[174:175] op_sel_hi:[1,0]
	v_max_f32_e32 v160, 0, v160
	v_mul_f32_e32 v204, v160, v160
	v_max_f32_e32 v160, 0, v200
	v_mul_f32_e32 v200, v160, v160
	v_max_f32_e32 v160, 0, v161
	v_max_f32_e32 v162, 0, v162
	v_max_f32_e32 v163, 0, v163
	v_mul_f32_e32 v161, v160, v160
	v_max_f32_e32 v160, 0, v201
	v_mul_f32_e32 v162, v162, v162
	v_max_f32_e32 v202, 0, v202
	v_mul_f32_e32 v163, v163, v163
	v_max_f32_e32 v203, 0, v203
	v_mul_f32_e32 v201, v160, v160
	v_cvt_pk_bf16_f32 v160, v162, v163
	v_cvt_pk_bf16_f32 v161, v204, v161
	v_mul_f32_e32 v202, v202, v202
	v_mul_f32_e32 v203, v203, v203
	v_cvt_pk_bf16_f32 v162, v202, v203
	v_cvt_pk_bf16_f32 v163, v200, v201
	global_store_dwordx4 v164, v[160:163], s[0:1] offset:3072
	v_pk_mul_f32 v[200:201], v[102:103], v[174:175] op_sel_hi:[1,0]
	v_pk_mul_f32 v[202:203], v[100:101], v[174:175] op_sel_hi:[1,0]
	v_pk_mul_f32 v[160:161], v[110:111], v[174:175] op_sel_hi:[1,0]
	v_pk_mul_f32 v[162:163], v[108:109], v[174:175] op_sel_hi:[1,0]
	v_max_f32_e32 v160, 0, v160
	v_mul_f32_e32 v204, v160, v160
	v_max_f32_e32 v160, 0, v200
	v_max_f32_e32 v162, 0, v162
	v_max_f32_e32 v163, 0, v163
	v_mul_f32_e32 v200, v160, v160
	v_max_f32_e32 v160, 0, v161
	v_mul_f32_e32 v162, v162, v162
	v_max_f32_e32 v202, 0, v202
	v_mul_f32_e32 v163, v163, v163
	v_max_f32_e32 v203, 0, v203
	v_mul_f32_e32 v161, v160, v160
	v_max_f32_e32 v160, 0, v201
	v_mul_f32_e32 v202, v202, v202
	v_mul_f32_e32 v203, v203, v203
	v_mul_f32_e32 v201, v160, v160
	v_cvt_pk_bf16_f32 v160, v162, v163
	v_cvt_pk_bf16_f32 v161, v204, v161
	v_cvt_pk_bf16_f32 v162, v202, v203
	v_cvt_pk_bf16_f32 v163, v200, v201
	v_add_u32_e32 v164, 0x80c00, v164
	s_cbranch_execnz .LBB0_238

.LBB0_274:
	ds_read_b128 v[162:165], v161
	ds_read_b128 v[166:169], v161 offset:1024
	ds_read_b128 v[170:173], v161 offset:2048
	ds_read_b128 v[174:177], v161 offset:3072
	ds_read_b128 v[178:181], v152
	ds_read_b128 v[182:185], v152 offset:1024
	ds_read_b128 v[186:189], v151
	ds_read_b128 v[190:193], v151 offset:1024
	ds_read_b128 v[194:197], v150
	ds_read_b128 v[198:201], v150 offset:1024
	ds_read_b128 v[202:205], v149
	ds_read_b128 v[206:209], v149 offset:1024
	s_waitcnt lgkmcnt(8)
	s_waitcnt vmcnt(10)
	s_barrier
	s_waitcnt lgkmcnt(0)
	s_setprio 1
	s_waitcnt lgkmcnt(0)
	v_mfma_f32_16x16x32_bf16 v[124:127], v[162:165], v[178:181], v[124:127]
	v_mfma_f32_16x16x32_bf16 v[120:123], v[170:173], v[178:181], v[120:123]
	v_mfma_f32_16x16x32_bf16 v[116:119], v[162:165], v[186:189], v[116:119]
	v_mfma_f32_16x16x32_bf16 v[112:115], v[170:173], v[186:189], v[112:115]
	v_mfma_f32_16x16x32_bf16 v[108:111], v[162:165], v[194:197], v[108:111]
	v_mfma_f32_16x16x32_bf16 v[104:107], v[170:173], v[194:197], v[104:107]
	v_mfma_f32_16x16x32_bf16 v[100:103], v[162:165], v[202:205], v[100:103]
	v_mfma_f32_16x16x32_bf16 v[96:99], v[170:173], v[202:205], v[96:99]
	v_mfma_f32_16x16x32_bf16 v[124:127], v[166:169], v[182:185], v[124:127]
	v_mfma_f32_16x16x32_bf16 v[120:123], v[174:177], v[182:185], v[120:123]
	v_mfma_f32_16x16x32_bf16 v[116:119], v[166:169], v[190:193], v[116:119]
	v_mfma_f32_16x16x32_bf16 v[112:115], v[174:177], v[190:193], v[112:115]
	v_mfma_f32_16x16x32_bf16 v[108:111], v[166:169], v[198:201], v[108:111]
	v_mfma_f32_16x16x32_bf16 v[104:107], v[174:177], v[198:201], v[104:107]
	v_mfma_f32_16x16x32_bf16 v[100:103], v[166:169], v[206:209], v[100:103]
	v_mfma_f32_16x16x32_bf16 v[96:99], v[174:177], v[206:209], v[96:99]
	s_setprio 0
	s_barrier
	s_mov_b32 vcc_lo, 0xfffbd000
	s_mov_b32 vcc_hi, -1
	v_readfirstlane_b32 s67, v148
	v_lshl_add_u64 v[226:227], v[130:131], 0, vcc
	s_mov_b32 m0, s67
	v_readfirstlane_b32 s67, v147
	ds_read_b128 v[210:213], v158
	ds_read_b128 v[214:217], v158 offset:1024
	ds_read_b128 v[218:221], v158 offset:2048
	ds_read_b128 v[222:225], v158 offset:3072
	global_load_lds_dwordx4 v[226:227], off
	v_lshl_add_u64 v[226:227], v[130:131], 0, s[22:23]
	s_mov_b32 m0, s67
	s_add_i32 s66, s66, 2
	global_load_lds_dwordx4 v[226:227], off
	s_waitcnt vmcnt(10)
	s_barrier
	s_waitcnt lgkmcnt(0)
	s_setprio 1
	s_waitcnt lgkmcnt(0)
	v_mfma_f32_16x16x32_bf16 v[92:95], v[210:213], v[178:181], v[92:95]
	v_mfma_f32_16x16x32_bf16 v[88:91], v[218:221], v[178:181], v[88:91]
	v_mfma_f32_16x16x32_bf16 v[84:87], v[210:213], v[186:189], v[84:87]
	v_mfma_f32_16x16x32_bf16 v[80:83], v[218:221], v[186:189], v[80:83]
	v_mfma_f32_16x16x32_bf16 v[76:79], v[210:213], v[194:197], v[76:79]
	v_mfma_f32_16x16x32_bf16 v[72:75], v[218:221], v[194:197], v[72:75]
	v_mfma_f32_16x16x32_bf16 v[68:71], v[210:213], v[202:205], v[68:71]
	v_mfma_f32_16x16x32_bf16 v[64:67], v[218:221], v[202:205], v[64:67]
	v_mfma_f32_16x16x32_bf16 v[92:95], v[214:217], v[182:185], v[92:95]
	v_mfma_f32_16x16x32_bf16 v[88:91], v[222:225], v[182:185], v[88:91]
	v_mfma_f32_16x16x32_bf16 v[84:87], v[214:217], v[190:193], v[84:87]
	v_mfma_f32_16x16x32_bf16 v[80:83], v[222:225], v[190:193], v[80:83]
	v_mfma_f32_16x16x32_bf16 v[76:79], v[214:217], v[198:201], v[76:79]
	v_mfma_f32_16x16x32_bf16 v[72:75], v[222:225], v[198:201], v[72:75]
	v_mfma_f32_16x16x32_bf16 v[68:71], v[214:217], v[206:209], v[68:71]
	v_mfma_f32_16x16x32_bf16 v[64:67], v[222:225], v[206:209], v[64:67]
	s_setprio 0
	v_readfirstlane_b32 s67, v134
	v_lshl_add_u64 v[226:227], v[132:133], 0, s[24:25]
	s_mov_b32 m0, s67
	v_readfirstlane_b32 s67, v146
	s_barrier
	ds_read_b128 v[178:181], v152 offset:16384
	ds_read_b128 v[182:185], v152 offset:17408
	ds_read_b128 v[186:189], v151 offset:16384
	ds_read_b128 v[190:193], v151 offset:17408
	ds_read_b128 v[194:197], v150 offset:16384
	ds_read_b128 v[198:201], v150 offset:17408
	ds_read_b128 v[202:205], v149 offset:16384
	ds_read_b128 v[206:209], v149 offset:17408
	global_load_lds_dwordx4 v[226:227], off
	v_lshl_add_u64 v[226:227], v[132:133], 0, s[26:27]
	s_mov_b32 m0, s67
	s_nop 0
	global_load_lds_dwordx4 v[226:227], off
	s_barrier
	s_waitcnt lgkmcnt(0)
	s_setprio 1
	s_waitcnt lgkmcnt(0)
	v_mfma_f32_16x16x32_bf16 v[60:63], v[162:165], v[178:181], v[60:63]
	v_mfma_f32_16x16x32_bf16 v[56:59], v[170:173], v[178:181], v[56:59]
	v_mfma_f32_16x16x32_bf16 v[52:55], v[162:165], v[186:189], v[52:55]
	v_mfma_f32_16x16x32_bf16 v[48:51], v[170:173], v[186:189], v[48:51]
	v_mfma_f32_16x16x32_bf16 v[44:47], v[162:165], v[194:197], v[44:47]
	v_mfma_f32_16x16x32_bf16 v[40:43], v[170:173], v[194:197], v[40:43]
	v_mfma_f32_16x16x32_bf16 v[36:39], v[162:165], v[202:205], v[36:39]
	v_mfma_f32_16x16x32_bf16 v[32:35], v[170:173], v[202:205], v[32:35]
	v_mfma_f32_16x16x32_bf16 v[60:63], v[166:169], v[182:185], v[60:63]
	v_mfma_f32_16x16x32_bf16 v[56:59], v[174:177], v[182:185], v[56:59]
	v_mfma_f32_16x16x32_bf16 v[52:55], v[166:169], v[190:193], v[52:55]
	v_mfma_f32_16x16x32_bf16 v[48:51], v[174:177], v[190:193], v[48:51]
	v_mfma_f32_16x16x32_bf16 v[44:47], v[166:169], v[198:201], v[44:47]
	v_mfma_f32_16x16x32_bf16 v[40:43], v[174:177], v[198:201], v[40:43]
	v_mfma_f32_16x16x32_bf16 v[36:39], v[166:169], v[206:209], v[36:39]
	v_mfma_f32_16x16x32_bf16 v[32:35], v[174:177], v[206:209], v[32:35]
	s_setprio 0
	s_barrier
	v_readfirstlane_b32 s67, v145
	v_lshl_add_u64 v[162:163], v[130:131], 0, s[28:29]
	s_mov_b32 m0, s67
	v_readfirstlane_b32 s67, v144
	global_load_lds_dwordx4 v[162:163], off
	v_lshl_add_u64 v[162:163], v[130:131], 0, s[30:31]
	s_mov_b32 m0, s67
	s_nop 0
	global_load_lds_dwordx4 v[162:163], off
	v_readfirstlane_b32 s67, v143
	v_lshl_add_u64 v[164:165], v[132:133], 0, s[34:35]
	s_mov_b32 m0, s67
	v_readfirstlane_b32 s67, v142
	global_load_lds_dwordx4 v[164:165], off
	v_lshl_add_u64 v[164:165], v[132:133], 0, s[44:45]
	s_mov_b32 m0, s67
	s_nop 0
	global_load_lds_dwordx4 v[164:165], off
	s_waitcnt vmcnt(12)
	s_barrier
	s_setprio 1
	v_mfma_f32_16x16x32_bf16 v[28:31], v[210:213], v[178:181], v[28:31]
	v_mfma_f32_16x16x32_bf16 v[24:27], v[218:221], v[178:181], v[24:27]
	v_mfma_f32_16x16x32_bf16 v[20:23], v[210:213], v[186:189], v[20:23]
	v_mfma_f32_16x16x32_bf16 v[16:19], v[218:221], v[186:189], v[16:19]
	v_mfma_f32_16x16x32_bf16 v[12:15], v[210:213], v[194:197], v[12:15]
	v_mfma_f32_16x16x32_bf16 v[8:11], v[218:221], v[194:197], v[8:11]
	v_mfma_f32_16x16x32_bf16 v[4:7], v[210:213], v[202:205], v[4:7]
	v_mfma_f32_16x16x32_bf16 v[0:3], v[218:221], v[202:205], v[0:3]
	v_mfma_f32_16x16x32_bf16 v[28:31], v[214:217], v[182:185], v[28:31]
	v_mfma_f32_16x16x32_bf16 v[24:27], v[222:225], v[182:185], v[24:27]
	v_mfma_f32_16x16x32_bf16 v[20:23], v[214:217], v[190:193], v[20:23]
	v_mfma_f32_16x16x32_bf16 v[16:19], v[222:225], v[190:193], v[16:19]
	v_mfma_f32_16x16x32_bf16 v[12:15], v[214:217], v[198:201], v[12:15]
	v_mfma_f32_16x16x32_bf16 v[8:11], v[222:225], v[198:201], v[8:11]
	v_mfma_f32_16x16x32_bf16 v[4:7], v[214:217], v[206:209], v[4:7]
	v_mfma_f32_16x16x32_bf16 v[0:3], v[222:225], v[206:209], v[0:3]
	s_setprio 0
	s_barrier
	ds_read_b128 v[162:165], v154
	ds_read_b128 v[166:169], v154 offset:1024
	ds_read_b128 v[170:173], v154 offset:2048
	ds_read_b128 v[174:177], v154 offset:3072
	ds_read_b128 v[178:181], v152 offset:32768
	ds_read_b128 v[182:185], v152 offset:33792
	ds_read_b128 v[186:189], v151 offset:32768
	ds_read_b128 v[190:193], v151 offset:33792
	ds_read_b128 v[194:197], v150 offset:32768
	ds_read_b128 v[198:201], v150 offset:33792
	ds_read_b128 v[202:205], v149 offset:32768
	ds_read_b128 v[206:209], v149 offset:33792
	s_waitcnt lgkmcnt(8)
	s_waitcnt vmcnt(10)
	s_barrier
	s_waitcnt lgkmcnt(0)
	s_setprio 1
	s_waitcnt lgkmcnt(0)
	v_mfma_f32_16x16x32_bf16 v[124:127], v[162:165], v[178:181], v[124:127]
	v_mfma_f32_16x16x32_bf16 v[120:123], v[170:173], v[178:181], v[120:123]
	v_mfma_f32_16x16x32_bf16 v[116:119], v[162:165], v[186:189], v[116:119]
	v_mfma_f32_16x16x32_bf16 v[112:115], v[170:173], v[186:189], v[112:115]
	v_mfma_f32_16x16x32_bf16 v[108:111], v[162:165], v[194:197], v[108:111]
	v_mfma_f32_16x16x32_bf16 v[104:107], v[170:173], v[194:197], v[104:107]
	v_mfma_f32_16x16x32_bf16 v[100:103], v[162:165], v[202:205], v[100:103]
	v_mfma_f32_16x16x32_bf16 v[96:99], v[170:173], v[202:205], v[96:99]
	v_mfma_f32_16x16x32_bf16 v[124:127], v[166:169], v[182:185], v[124:127]
	v_mfma_f32_16x16x32_bf16 v[120:123], v[174:177], v[182:185], v[120:123]
	v_mfma_f32_16x16x32_bf16 v[116:119], v[166:169], v[190:193], v[116:119]
	v_mfma_f32_16x16x32_bf16 v[112:115], v[174:177], v[190:193], v[112:115]
	v_mfma_f32_16x16x32_bf16 v[108:111], v[166:169], v[198:201], v[108:111]
	v_mfma_f32_16x16x32_bf16 v[104:107], v[174:177], v[198:201], v[104:107]
	v_mfma_f32_16x16x32_bf16 v[100:103], v[166:169], v[206:209], v[100:103]
	v_mfma_f32_16x16x32_bf16 v[96:99], v[174:177], v[206:209], v[96:99]
	s_setprio 0
	s_barrier
	v_readfirstlane_b32 s67, v141
	v_lshl_add_u64 v[226:227], v[130:131], 0, s[46:47]
	s_mov_b32 m0, s67
	v_readfirstlane_b32 s67, v140
	ds_read_b128 v[210:213], v153
	ds_read_b128 v[214:217], v153 offset:1024
	ds_read_b128 v[218:221], v153 offset:2048
	ds_read_b128 v[222:225], v153 offset:3072
	global_load_lds_dwordx4 v[226:227], off
	v_lshl_add_u64 v[226:227], v[130:131], 0, s[56:57]
	s_mov_b32 m0, s67
	s_nop 0
	global_load_lds_dwordx4 v[226:227], off
	s_waitcnt vmcnt(10)
	s_barrier
	s_waitcnt lgkmcnt(0)
	s_setprio 1
	s_waitcnt lgkmcnt(0)
	v_mfma_f32_16x16x32_bf16 v[92:95], v[210:213], v[178:181], v[92:95]
	v_mfma_f32_16x16x32_bf16 v[88:91], v[218:221], v[178:181], v[88:91]
	v_mfma_f32_16x16x32_bf16 v[84:87], v[210:213], v[186:189], v[84:87]
	v_mfma_f32_16x16x32_bf16 v[80:83], v[218:221], v[186:189], v[80:83]
	v_mfma_f32_16x16x32_bf16 v[76:79], v[210:213], v[194:197], v[76:79]
	v_mfma_f32_16x16x32_bf16 v[72:75], v[218:221], v[194:197], v[72:75]
	v_mfma_f32_16x16x32_bf16 v[68:71], v[210:213], v[202:205], v[68:71]
	v_mfma_f32_16x16x32_bf16 v[64:67], v[218:221], v[202:205], v[64:67]
	v_mfma_f32_16x16x32_bf16 v[92:95], v[214:217], v[182:185], v[92:95]
	v_mfma_f32_16x16x32_bf16 v[88:91], v[222:225], v[182:185], v[88:91]
	v_mfma_f32_16x16x32_bf16 v[84:87], v[214:217], v[190:193], v[84:87]
	v_mfma_f32_16x16x32_bf16 v[80:83], v[222:225], v[190:193], v[80:83]
	v_mfma_f32_16x16x32_bf16 v[76:79], v[214:217], v[198:201], v[76:79]
	v_mfma_f32_16x16x32_bf16 v[72:75], v[222:225], v[198:201], v[72:75]
	v_mfma_f32_16x16x32_bf16 v[68:71], v[214:217], v[206:209], v[68:71]
	v_mfma_f32_16x16x32_bf16 v[64:67], v[222:225], v[206:209], v[64:67]
	s_setprio 0
	v_readfirstlane_b32 s67, v139
	v_lshl_add_u64 v[226:227], v[132:133], 0, s[58:59]
	s_mov_b32 m0, s67
	v_readfirstlane_b32 s67, v138
	s_barrier
	ds_read_b128 v[178:181], v152 offset:49152
	ds_read_b128 v[182:185], v152 offset:50176
	ds_read_b128 v[186:189], v151 offset:49152
	ds_read_b128 v[190:193], v151 offset:50176
	ds_read_b128 v[194:197], v150 offset:49152
	ds_read_b128 v[198:201], v150 offset:50176
	ds_read_b128 v[202:205], v149 offset:49152
	ds_read_b128 v[206:209], v149 offset:50176
	global_load_lds_dwordx4 v[226:227], off
	s_mov_b32 m0, s67
	s_nop 0
	global_load_lds_dwordx4 v[132:133], off
	s_barrier
	s_waitcnt lgkmcnt(0)
	s_setprio 1
	s_waitcnt lgkmcnt(0)
	v_mfma_f32_16x16x32_bf16 v[60:63], v[162:165], v[178:181], v[60:63]
	v_mfma_f32_16x16x32_bf16 v[56:59], v[170:173], v[178:181], v[56:59]
	v_mfma_f32_16x16x32_bf16 v[52:55], v[162:165], v[186:189], v[52:55]
	v_mfma_f32_16x16x32_bf16 v[48:51], v[170:173], v[186:189], v[48:51]
	v_mfma_f32_16x16x32_bf16 v[44:47], v[162:165], v[194:197], v[44:47]
	v_mfma_f32_16x16x32_bf16 v[40:43], v[170:173], v[194:197], v[40:43]
	v_mfma_f32_16x16x32_bf16 v[36:39], v[162:165], v[202:205], v[36:39]
	v_mfma_f32_16x16x32_bf16 v[32:35], v[170:173], v[202:205], v[32:35]
	v_mfma_f32_16x16x32_bf16 v[60:63], v[166:169], v[182:185], v[60:63]
	v_mfma_f32_16x16x32_bf16 v[56:59], v[174:177], v[182:185], v[56:59]
	v_mfma_f32_16x16x32_bf16 v[52:55], v[166:169], v[190:193], v[52:55]
	v_mfma_f32_16x16x32_bf16 v[48:51], v[174:177], v[190:193], v[48:51]
	v_mfma_f32_16x16x32_bf16 v[44:47], v[166:169], v[198:201], v[44:47]
	v_mfma_f32_16x16x32_bf16 v[40:43], v[174:177], v[198:201], v[40:43]
	v_mfma_f32_16x16x32_bf16 v[36:39], v[166:169], v[206:209], v[36:39]
	v_mfma_f32_16x16x32_bf16 v[32:35], v[174:177], v[206:209], v[32:35]
	s_setprio 0
	s_barrier
	v_readfirstlane_b32 s67, v137
	v_lshl_add_u64 v[162:163], v[130:131], 0, s[58:59]
	s_mov_b32 m0, s67
	v_readfirstlane_b32 s67, v136
	global_load_lds_dwordx4 v[162:163], off
	s_mov_b32 m0, s67
	s_nop 0
	global_load_lds_dwordx4 v[130:131], off
	v_lshl_add_u64 v[132:133], v[132:133], 0, s[62:63]
	s_mov_b32 vcc_lo, 0xffe01000
	s_mov_b32 vcc_hi, -1
	v_lshl_add_u64 v[164:165], v[132:133], 0, vcc
	v_readfirstlane_b32 s67, v160
	s_mov_b32 vcc_lo, 0xffe02000
	s_mov_b32 m0, s67
	s_mov_b32 vcc_hi, -1
	v_readfirstlane_b32 s67, v159
	global_load_lds_dwordx4 v[164:165], off
	v_lshl_add_u64 v[164:165], v[132:133], 0, vcc
	s_mov_b32 m0, s67
	s_nop 0
	global_load_lds_dwordx4 v[164:165], off
	s_waitcnt vmcnt(12)
	s_barrier
	s_setprio 1
	v_mfma_f32_16x16x32_bf16 v[28:31], v[210:213], v[178:181], v[28:31]
	v_mfma_f32_16x16x32_bf16 v[24:27], v[218:221], v[178:181], v[24:27]
	v_mfma_f32_16x16x32_bf16 v[20:23], v[210:213], v[186:189], v[20:23]
	v_mfma_f32_16x16x32_bf16 v[16:19], v[218:221], v[186:189], v[16:19]
	v_mfma_f32_16x16x32_bf16 v[12:15], v[210:213], v[194:197], v[12:15]
	v_mfma_f32_16x16x32_bf16 v[8:11], v[218:221], v[194:197], v[8:11]
	v_mfma_f32_16x16x32_bf16 v[4:7], v[210:213], v[202:205], v[4:7]
	v_mfma_f32_16x16x32_bf16 v[0:3], v[218:221], v[202:205], v[0:3]
	v_mfma_f32_16x16x32_bf16 v[28:31], v[214:217], v[182:185], v[28:31]
	v_mfma_f32_16x16x32_bf16 v[24:27], v[222:225], v[182:185], v[24:27]
	v_mfma_f32_16x16x32_bf16 v[20:23], v[214:217], v[190:193], v[20:23]
	v_mfma_f32_16x16x32_bf16 v[16:19], v[222:225], v[190:193], v[16:19]
	v_mfma_f32_16x16x32_bf16 v[12:15], v[214:217], v[198:201], v[12:15]
	v_mfma_f32_16x16x32_bf16 v[8:11], v[222:225], v[198:201], v[8:11]
	v_mfma_f32_16x16x32_bf16 v[4:7], v[214:217], v[206:209], v[4:7]
	v_mfma_f32_16x16x32_bf16 v[0:3], v[222:225], v[206:209], v[0:3]
	s_setprio 0
	v_lshl_add_u64 v[130:131], v[130:131], 0, s[60:61]
	s_cmp_lt_u32 s66, s65
	s_barrier
	s_cbranch_scc1 .LBB0_274
	s_lshl_b32 s65, s86, 5
	s_lshl_b32 s66, s86, 8
	s_and_b32 s65, s65, 0x1800
	s_and_b32 s66, s66, 0x700
	s_or_b32 s97, s66, s65
	s_lshl_b32 s65, s97, 6
	s_add_u32 s65, s68, s65
	s_addc_u32 s86, s69, 0
	s_add_i32 s20, s20, -1
	s_lshl_b64 s[66:67], s[20:21], 20
	v_add_u32_e32 v128, v156, v157
	s_add_u32 s66, s65, s66
	v_or_b32_e32 v128, v128, v155
	s_addc_u32 s67, s86, s67
	v_lshl_add_u64 v[156:157], s[66:67], 0, v[128:129]
	v_readfirstlane_b32 s20, v160
	v_lshl_add_u64 v[206:207], v[156:157], 0, s[4:5]
	s_mov_b32 m0, s20
	v_readfirstlane_b32 s20, v159
	ds_read_b128 v[130:133], v161
	ds_read_b128 v[162:165], v161 offset:1024
	ds_read_b128 v[166:169], v161 offset:2048
	ds_read_b128 v[170:173], v161 offset:3072
	ds_read_b128 v[174:177], v152
	ds_read_b128 v[178:181], v152 offset:1024
	ds_read_b128 v[182:185], v151
	ds_read_b128 v[186:189], v151 offset:1024
	ds_read_b128 v[190:193], v150
	ds_read_b128 v[194:197], v150 offset:1024
	ds_read_b128 v[198:201], v149
	ds_read_b128 v[202:205], v149 offset:1024
	global_load_lds_dwordx4 v[206:207], off
	v_lshl_add_u64 v[156:157], v[156:157], 0, s[6:7]
	s_mov_b32 m0, s20
	s_nop 0
	global_load_lds_dwordx4 v[156:157], off
	s_waitcnt vmcnt(10)
	s_barrier
	s_waitcnt lgkmcnt(0)
	s_setprio 1
	s_waitcnt lgkmcnt(0)
	v_mfma_f32_16x16x32_bf16 v[124:127], v[130:133], v[174:177], v[124:127]
	v_mfma_f32_16x16x32_bf16 v[120:123], v[166:169], v[174:177], v[120:123]
	v_mfma_f32_16x16x32_bf16 v[116:119], v[130:133], v[182:185], v[116:119]
	v_mfma_f32_16x16x32_bf16 v[112:115], v[166:169], v[182:185], v[112:115]
	v_mfma_f32_16x16x32_bf16 v[108:111], v[130:133], v[190:193], v[108:111]
	v_mfma_f32_16x16x32_bf16 v[104:107], v[166:169], v[190:193], v[104:107]
	v_mfma_f32_16x16x32_bf16 v[100:103], v[130:133], v[198:201], v[100:103]
	v_mfma_f32_16x16x32_bf16 v[96:99], v[166:169], v[198:201], v[96:99]
	v_mfma_f32_16x16x32_bf16 v[124:127], v[162:165], v[178:181], v[124:127]
	v_mfma_f32_16x16x32_bf16 v[120:123], v[170:173], v[178:181], v[120:123]
	v_mfma_f32_16x16x32_bf16 v[116:119], v[162:165], v[186:189], v[116:119]
	v_mfma_f32_16x16x32_bf16 v[112:115], v[170:173], v[186:189], v[112:115]
	v_mfma_f32_16x16x32_bf16 v[108:111], v[162:165], v[194:197], v[108:111]
	v_mfma_f32_16x16x32_bf16 v[104:107], v[170:173], v[194:197], v[104:107]
	v_mfma_f32_16x16x32_bf16 v[100:103], v[162:165], v[202:205], v[100:103]
	v_mfma_f32_16x16x32_bf16 v[96:99], v[170:173], v[202:205], v[96:99]
	s_setprio 0
	s_barrier
	ds_read_b128 v[206:209], v158
	ds_read_b128 v[210:213], v158 offset:1024
	ds_read_b128 v[214:217], v158 offset:2048
	ds_read_b128 v[156:159], v158 offset:3072
	s_barrier
	s_waitcnt lgkmcnt(0)
	s_setprio 1
	s_waitcnt lgkmcnt(0)
	v_mfma_f32_16x16x32_bf16 v[92:95], v[206:209], v[174:177], v[92:95]
	v_mfma_f32_16x16x32_bf16 v[88:91], v[214:217], v[174:177], v[88:91]
	v_mfma_f32_16x16x32_bf16 v[84:87], v[206:209], v[182:185], v[84:87]
	v_mfma_f32_16x16x32_bf16 v[80:83], v[214:217], v[182:185], v[80:83]
	v_mfma_f32_16x16x32_bf16 v[76:79], v[206:209], v[190:193], v[76:79]
	v_mfma_f32_16x16x32_bf16 v[72:75], v[214:217], v[190:193], v[72:75]
	v_mfma_f32_16x16x32_bf16 v[68:71], v[206:209], v[198:201], v[68:71]
	v_mfma_f32_16x16x32_bf16 v[64:67], v[214:217], v[198:201], v[64:67]
	v_mfma_f32_16x16x32_bf16 v[174:177], v[210:213], v[178:181], v[92:95]
	v_mfma_f32_16x16x32_bf16 v[178:181], v[156:159], v[178:181], v[88:91]
	v_mfma_f32_16x16x32_bf16 v[182:185], v[210:213], v[186:189], v[84:87]
	v_mfma_f32_16x16x32_bf16 v[186:189], v[156:159], v[186:189], v[80:83]
	v_mfma_f32_16x16x32_bf16 v[190:193], v[210:213], v[194:197], v[76:79]
	v_mfma_f32_16x16x32_bf16 v[194:197], v[156:159], v[194:197], v[72:75]
	v_mfma_f32_16x16x32_bf16 v[198:201], v[210:213], v[202:205], v[68:71]
	v_mfma_f32_16x16x32_bf16 v[202:205], v[156:159], v[202:205], v[64:67]
	s_setprio 0
	s_barrier
	s_nop 0
	ds_read_b128 v[64:67], v152 offset:16384
	ds_read_b128 v[68:71], v152 offset:17408
	ds_read_b128 v[72:75], v151 offset:16384
	ds_read_b128 v[76:79], v151 offset:17408
	ds_read_b128 v[80:83], v150 offset:16384
	ds_read_b128 v[84:87], v150 offset:17408
	ds_read_b128 v[88:91], v149 offset:16384
	ds_read_b128 v[92:95], v149 offset:17408
	s_waitcnt vmcnt(4)
	s_barrier
	s_waitcnt lgkmcnt(0)
	s_setprio 1
	s_waitcnt lgkmcnt(0)
	v_mfma_f32_16x16x32_bf16 v[60:63], v[130:133], v[64:67], v[60:63]
	v_mfma_f32_16x16x32_bf16 v[56:59], v[166:169], v[64:67], v[56:59]
	v_mfma_f32_16x16x32_bf16 v[52:55], v[130:133], v[72:75], v[52:55]
	v_mfma_f32_16x16x32_bf16 v[48:51], v[166:169], v[72:75], v[48:51]
	v_mfma_f32_16x16x32_bf16 v[218:221], v[130:133], v[80:83], v[44:47]
	v_mfma_f32_16x16x32_bf16 v[222:225], v[166:169], v[80:83], v[40:43]
	v_mfma_f32_16x16x32_bf16 v[130:133], v[130:133], v[88:91], v[36:39]
	v_mfma_f32_16x16x32_bf16 v[166:169], v[166:169], v[88:91], v[32:35]
	v_mfma_f32_16x16x32_bf16 v[32:35], v[162:165], v[68:71], v[60:63]
	v_mfma_f32_16x16x32_bf16 v[36:39], v[170:173], v[68:71], v[56:59]
	v_mfma_f32_16x16x32_bf16 v[40:43], v[162:165], v[76:79], v[52:55]
	v_mfma_f32_16x16x32_bf16 v[44:47], v[170:173], v[76:79], v[48:51]
	v_mfma_f32_16x16x32_bf16 v[48:51], v[162:165], v[84:87], v[218:221]
	v_mfma_f32_16x16x32_bf16 v[52:55], v[170:173], v[84:87], v[222:225]
	v_mfma_f32_16x16x32_bf16 v[56:59], v[162:165], v[92:95], v[130:133]
	v_mfma_f32_16x16x32_bf16 v[60:63], v[170:173], v[92:95], v[166:169]
	s_setprio 0
	s_setprio 1
	v_mfma_f32_16x16x32_bf16 v[28:31], v[206:209], v[64:67], v[28:31]
	v_mfma_f32_16x16x32_bf16 v[24:27], v[214:217], v[64:67], v[24:27]
	v_mfma_f32_16x16x32_bf16 v[20:23], v[206:209], v[72:75], v[20:23]
	v_mfma_f32_16x16x32_bf16 v[64:67], v[214:217], v[72:75], v[16:19]
	v_mfma_f32_16x16x32_bf16 v[72:75], v[206:209], v[80:83], v[12:15]
	v_mfma_f32_16x16x32_bf16 v[8:11], v[214:217], v[80:83], v[8:11]
	v_mfma_f32_16x16x32_bf16 v[80:83], v[206:209], v[88:91], v[4:7]
	v_mfma_f32_16x16x32_bf16 v[0:3], v[214:217], v[88:91], v[0:3]
	v_mfma_f32_16x16x32_bf16 v[4:7], v[210:213], v[68:71], v[28:31]
	v_mfma_f32_16x16x32_bf16 v[12:15], v[156:159], v[68:71], v[24:27]
	v_mfma_f32_16x16x32_bf16 v[16:19], v[210:213], v[76:79], v[20:23]
	v_mfma_f32_16x16x32_bf16 v[20:23], v[156:159], v[76:79], v[64:67]
	v_mfma_f32_16x16x32_bf16 v[24:27], v[210:213], v[84:87], v[72:75]
	v_mfma_f32_16x16x32_bf16 v[28:31], v[156:159], v[84:87], v[8:11]
	v_mfma_f32_16x16x32_bf16 v[64:67], v[210:213], v[92:95], v[80:83]
	v_mfma_f32_16x16x32_bf16 v[68:71], v[156:159], v[92:95], v[0:3]
	s_setprio 0
	s_barrier
	ds_read_b128 v[8:11], v154
	ds_read_b128 v[0:3], v154 offset:1024
	ds_read_b128 v[76:79], v154 offset:2048
	ds_read_b128 v[72:75], v154 offset:3072
	ds_read_b128 v[130:133], v152 offset:32768
	ds_read_b128 v[154:157], v152 offset:33792
	ds_read_b128 v[158:161], v151 offset:32768
	ds_read_b128 v[162:165], v151 offset:33792
	ds_read_b128 v[166:169], v150 offset:32768
	ds_read_b128 v[170:173], v150 offset:33792
	ds_read_b128 v[206:209], v149 offset:32768
	ds_read_b128 v[210:213], v149 offset:33792
	s_waitcnt vmcnt(2)
	s_barrier
	s_waitcnt lgkmcnt(0)
	s_setprio 1
	s_waitcnt lgkmcnt(0)
	v_mfma_f32_16x16x32_bf16 v[80:83], v[8:11], v[130:133], v[124:127]
	v_mfma_f32_16x16x32_bf16 v[84:87], v[76:79], v[130:133], v[120:123]
	v_mfma_f32_16x16x32_bf16 v[88:91], v[8:11], v[158:161], v[116:119]
	v_mfma_f32_16x16x32_bf16 v[92:95], v[76:79], v[158:161], v[112:115]
	v_mfma_f32_16x16x32_bf16 v[108:111], v[8:11], v[166:169], v[108:111]
	v_mfma_f32_16x16x32_bf16 v[104:107], v[76:79], v[166:169], v[104:107]
	v_mfma_f32_16x16x32_bf16 v[100:103], v[8:11], v[206:209], v[100:103]
	v_mfma_f32_16x16x32_bf16 v[96:99], v[76:79], v[206:209], v[96:99]
	v_mfma_f32_16x16x32_bf16 v[112:115], v[0:3], v[154:157], v[80:83]
	v_mfma_f32_16x16x32_bf16 v[116:119], v[72:75], v[154:157], v[84:87]
	v_mfma_f32_16x16x32_bf16 v[120:123], v[0:3], v[162:165], v[88:91]
	v_mfma_f32_16x16x32_bf16 v[124:127], v[72:75], v[162:165], v[92:95]
	v_mfma_f32_16x16x32_bf16 v[108:111], v[0:3], v[170:173], v[108:111]
	v_mfma_f32_16x16x32_bf16 v[104:107], v[72:75], v[170:173], v[104:107]
	v_mfma_f32_16x16x32_bf16 v[100:103], v[0:3], v[210:213], v[100:103]
	v_mfma_f32_16x16x32_bf16 v[96:99], v[72:75], v[210:213], v[96:99]
	s_setprio 0
	s_barrier
	ds_read_b128 v[88:91], v153
	ds_read_b128 v[80:83], v153 offset:1024
	ds_read_b128 v[92:95], v153 offset:2048
	ds_read_b128 v[84:87], v153 offset:3072
	s_waitcnt vmcnt(0)
	s_barrier
	s_waitcnt lgkmcnt(0)
	s_setprio 1
	s_waitcnt lgkmcnt(0)
	v_mfma_f32_16x16x32_bf16 v[174:177], v[88:91], v[130:133], v[174:177]
	v_mfma_f32_16x16x32_bf16 v[130:133], v[92:95], v[130:133], v[178:181]
	v_mfma_f32_16x16x32_bf16 v[178:181], v[88:91], v[158:161], v[182:185]
	v_mfma_f32_16x16x32_bf16 v[158:161], v[92:95], v[158:161], v[186:189]
	v_mfma_f32_16x16x32_bf16 v[182:185], v[88:91], v[166:169], v[190:193]
	v_mfma_f32_16x16x32_bf16 v[166:169], v[92:95], v[166:169], v[194:197]
	v_mfma_f32_16x16x32_bf16 v[186:189], v[88:91], v[206:209], v[198:201]
	v_mfma_f32_16x16x32_bf16 v[190:193], v[92:95], v[206:209], v[202:205]
	v_mfma_f32_16x16x32_bf16 v[174:177], v[80:83], v[154:157], v[174:177]
	v_mfma_f32_16x16x32_bf16 v[130:133], v[84:87], v[154:157], v[130:133]
	v_mfma_f32_16x16x32_bf16 v[154:157], v[80:83], v[162:165], v[178:181]
	v_mfma_f32_16x16x32_bf16 v[158:161], v[84:87], v[162:165], v[158:161]
	v_mfma_f32_16x16x32_bf16 v[162:165], v[80:83], v[170:173], v[182:185]
	v_mfma_f32_16x16x32_bf16 v[166:169], v[84:87], v[170:173], v[166:169]
	v_mfma_f32_16x16x32_bf16 v[170:173], v[80:83], v[210:213], v[186:189]
	v_mfma_f32_16x16x32_bf16 v[178:181], v[84:87], v[210:213], v[190:193]
	s_setprio 0
	s_barrier
	v_mbcnt_lo_u32_b32 v128, -1, 0
	v_mbcnt_hi_u32_b32 v128, -1, v128
	v_cvt_pk_bf16_f32 v112, v112, v113
	v_cvt_pk_bf16_f32 v113, v114, v115
	v_cvt_pk_bf16_f32 v114, v116, v117
	v_cvt_pk_bf16_f32 v115, v118, v119
	s_lshl_b32 s89, s64, 9
	v_add_u32_e32 v153, s72, v128
	v_ashrrev_i32_e32 v182, 6, v153
	v_and_b32_e32 v183, 15, v128
	v_and_b32_e32 v184, 48, v128
	v_mul_lo_u32 v185, v182, s77
	v_bfe_u32 v186, v128, 3, 3
	v_lshlrev_b32_e32 v128, 4, v128
	v_add_u32_e32 v185, 0x20000, v185
	v_lshrrev_b32_e32 v153, 2, v153
	v_and_b32_e32 v128, 0x70, v128
	v_mul_u32_u24_e32 v183, 0x90, v183
	v_and_b32_e32 v153, 64, v153
	v_add3_u32 v183, v185, v183, v184
	v_or_b32_e32 v184, v185, v128
	v_or3_b32 v153, s97, v153, v186
	v_mad_u32_u24 v184, v186, s79, v184
	ds_write_b128 v183, v[112:115]
	v_cvt_pk_bf16_f32 v112, v174, v175
	v_cvt_pk_bf16_f32 v113, v176, v177
	v_cvt_pk_bf16_f32 v114, v130, v131
	v_cvt_pk_bf16_f32 v115, v132, v133
	ds_write_b128 v183, v[112:115] offset:64
	v_lshlrev_b32_e32 v182, 7, v182
	ds_read_b128 v[112:115], v184
	v_lshlrev_b32_e32 v116, 12, v153
	v_and_or_b32 v116, v182, s80, v116
	v_or3_b32 v128, v116, s89, v128
	ds_read_b128 v[116:119], v184 offset:1152
	v_lshl_add_u64 v[130:131], s[0:1], 0, v[128:129]
	s_mov_b32 s20, 0x8000
	s_waitcnt lgkmcnt(0)
	global_store_dwordx4 v128, v[112:115], s[0:1]
	v_cvt_pk_bf16_f32 v108, v108, v109
	v_cvt_pk_bf16_f32 v109, v110, v111
	v_cvt_pk_bf16_f32 v110, v104, v105
	v_cvt_pk_bf16_f32 v111, v106, v107
	v_cvt_pk_bf16_f32 v104, v162, v163
	s_nop 1
	v_add_co_u32_e32 v112, vcc, s20, v130
	v_cvt_pk_bf16_f32 v114, v124, v125
	v_cvt_pk_bf16_f32 v115, v126, v127
	v_cvt_pk_bf16_f32 v105, v164, v165
	v_cvt_pk_bf16_f32 v106, v166, v167
	s_nop 1
	v_addc_co_u32_e32 v113, vcc, 0, v131, vcc
	global_store_dwordx4 v[112:113], v[116:119], off
	v_cvt_pk_bf16_f32 v112, v120, v121
	v_cvt_pk_bf16_f32 v113, v122, v123
	ds_write_b128 v183, v[112:115]
	v_cvt_pk_bf16_f32 v112, v154, v155
	v_cvt_pk_bf16_f32 v113, v156, v157
	v_cvt_pk_bf16_f32 v114, v158, v159
	v_cvt_pk_bf16_f32 v115, v160, v161
	ds_write_b128 v183, v[112:115] offset:64
	ds_read_b128 v[112:115], v184
	ds_read_b128 v[116:119], v184 offset:1152
	v_add_co_u32_e32 v120, vcc, s74, v130
	ds_write_b128 v183, v[108:111]
	v_cvt_pk_bf16_f32 v107, v168, v169
	ds_write_b128 v183, v[104:107] offset:64
	v_addc_co_u32_e32 v121, vcc, 0, v131, vcc
	ds_read_b128 v[104:107], v184
	ds_read_b128 v[108:111], v184 offset:1152
	s_waitcnt lgkmcnt(0)
	global_store_dwordx4 v[120:121], v[112:115], off
	v_cvt_pk_bf16_f32 v100, v100, v101
	v_cvt_pk_bf16_f32 v101, v102, v103
	v_cvt_pk_bf16_f32 v102, v96, v97
	v_cvt_pk_bf16_f32 v103, v98, v99
	ds_write_b128 v183, v[100:103]
	s_nop 0
	v_add_co_u32_e32 v112, vcc, s75, v130
	v_cvt_pk_bf16_f32 v96, v170, v171
	v_cvt_pk_bf16_f32 v97, v172, v173
	v_cvt_pk_bf16_f32 v98, v178, v179
	v_cvt_pk_bf16_f32 v99, v180, v181
	s_nop 1
	v_addc_co_u32_e32 v113, vcc, 0, v131, vcc
	global_store_dwordx4 v[112:113], v[116:119], off
	v_add_co_u32_e32 v112, vcc, s78, v130
	ds_write_b128 v183, v[96:99] offset:64
	s_nop 0
	v_addc_co_u32_e32 v113, vcc, 0, v131, vcc
	ds_read_b128 v[96:99], v184
	ds_read_b128 v[100:103], v184 offset:1152
	global_store_dwordx4 v[112:113], v[104:107], off
	s_nop 1
	v_add_co_u32_e32 v104, vcc, s81, v130
	s_nop 1
	v_addc_co_u32_e32 v105, vcc, 0, v131, vcc
	global_store_dwordx4 v[104:105], v[108:111], off
	v_add_co_u32_e32 v104, vcc, s82, v130
	s_nop 1
	v_addc_co_u32_e32 v105, vcc, 0, v131, vcc
	s_waitcnt lgkmcnt(0)
	global_store_dwordx4 v[104:105], v[96:99], off
	s_nop 1
	v_add_co_u32_e32 v96, vcc, s83, v130
	s_nop 1
	v_addc_co_u32_e32 v97, vcc, 0, v131, vcc
	global_store_dwordx4 v[96:97], v[100:103], off
	ds_read_b128 v[96:99], v152 offset:49152
	ds_read_b128 v[100:103], v152 offset:50176
	ds_read_b128 v[104:107], v151 offset:49152
	ds_read_b128 v[108:111], v151 offset:50176
	ds_read_b128 v[112:115], v150 offset:49152
	ds_read_b128 v[116:119], v150 offset:50176
	ds_read_b128 v[120:123], v149 offset:49152
	ds_read_b128 v[124:127], v149 offset:50176
	s_barrier
	s_waitcnt lgkmcnt(0)
	s_setprio 1
	s_waitcnt lgkmcnt(0)
	v_mfma_f32_16x16x32_bf16 v[32:35], v[8:11], v[96:99], v[32:35]
	v_mfma_f32_16x16x32_bf16 v[36:39], v[76:79], v[96:99], v[36:39]
	v_mfma_f32_16x16x32_bf16 v[40:43], v[8:11], v[104:107], v[40:43]
	v_mfma_f32_16x16x32_bf16 v[130:133], v[76:79], v[104:107], v[44:47]
	v_mfma_f32_16x16x32_bf16 v[150:153], v[8:11], v[112:115], v[48:51]
	v_mfma_f32_16x16x32_bf16 v[52:55], v[76:79], v[112:115], v[52:55]
	v_mfma_f32_16x16x32_bf16 v[8:11], v[8:11], v[120:123], v[56:59]
	v_mfma_f32_16x16x32_bf16 v[60:63], v[76:79], v[120:123], v[60:63]
	v_mfma_f32_16x16x32_bf16 v[56:59], v[0:3], v[100:103], v[32:35]
	v_mfma_f32_16x16x32_bf16 v[48:51], v[72:75], v[100:103], v[36:39]
	v_mfma_f32_16x16x32_bf16 v[44:47], v[0:3], v[108:111], v[40:43]
	v_mfma_f32_16x16x32_bf16 v[40:43], v[72:75], v[108:111], v[130:133]
	v_mfma_f32_16x16x32_bf16 v[36:39], v[0:3], v[116:119], v[150:153]
	v_mfma_f32_16x16x32_bf16 v[32:35], v[72:75], v[116:119], v[52:55]
	v_mfma_f32_16x16x32_bf16 v[8:11], v[0:3], v[124:127], v[8:11]
	v_mfma_f32_16x16x32_bf16 v[0:3], v[72:75], v[124:127], v[60:63]
	s_setprio 0
	s_setprio 1
	v_mfma_f32_16x16x32_bf16 v[4:7], v[88:91], v[96:99], v[4:7]
	v_mfma_f32_16x16x32_bf16 v[12:15], v[92:95], v[96:99], v[12:15]
	v_mfma_f32_16x16x32_bf16 v[16:19], v[88:91], v[104:107], v[16:19]
	v_mfma_f32_16x16x32_bf16 v[20:23], v[92:95], v[104:107], v[20:23]
	v_mfma_f32_16x16x32_bf16 v[72:75], v[88:91], v[112:115], v[24:27]
	v_mfma_f32_16x16x32_bf16 v[76:79], v[92:95], v[112:115], v[28:31]
	v_mfma_f32_16x16x32_bf16 v[64:67], v[88:91], v[120:123], v[64:67]
	v_mfma_f32_16x16x32_bf16 v[68:71], v[92:95], v[120:123], v[68:71]
	v_mfma_f32_16x16x32_bf16 v[60:63], v[80:83], v[100:103], v[4:7]
	v_mfma_f32_16x16x32_bf16 v[52:55], v[84:87], v[100:103], v[12:15]
	v_mfma_f32_16x16x32_bf16 v[28:31], v[80:83], v[108:111], v[16:19]
	v_mfma_f32_16x16x32_bf16 v[24:27], v[84:87], v[108:111], v[20:23]
	v_mfma_f32_16x16x32_bf16 v[20:23], v[80:83], v[116:119], v[72:75]
	v_mfma_f32_16x16x32_bf16 v[16:19], v[84:87], v[116:119], v[76:79]
	v_mfma_f32_16x16x32_bf16 v[12:15], v[80:83], v[124:127], v[64:67]
	v_mfma_f32_16x16x32_bf16 v[4:7], v[84:87], v[124:127], v[68:71]
	s_setprio 0
	v_cmp_gt_u32_e32 vcc, s85, v135
	s_barrier
	s_and_saveexec_b64 s[64:65], vcc
	s_cbranch_execz .LBB0_277
	s_barrier

.LBB0_355:
	s_lshl_b32 s14, s70, 3
	v_cvt_f32_u32_e32 v2, s14
	s_sub_i32 s17, 0, s14
	s_abs_i32 s16, s69
	s_ashr_i32 s15, s69, 31
	v_rcp_iflag_f32_e32 v2, v2
	v_and_b32_e32 v3, 15, v0
	v_lshlrev_b32_e32 v3, 6, v3
	v_lshlrev_b32_e32 v6, 2, v0
	v_mul_f32_e32 v2, 0x4f7ffffe, v2
	v_cvt_u32_f32_e32 v2, v2
	v_lshlrev_b32_e32 v4, 6, v183
	v_and_b32_e32 v6, 32, v6
	v_lshlrev_b32_e32 v1, 13, v1
	v_readfirstlane_b32 s24, v2
	s_mul_i32 s17, s17, s24
	s_mul_hi_u32 s17, s24, s17
	s_add_i32 s24, s24, s17
	s_mul_hi_u32 s17, s16, s24
	s_mul_i32 s24, s17, s14
	s_sub_i32 s16, s16, s24
	s_add_i32 s25, s17, 1
	s_sub_i32 s24, s16, s14
	s_cmp_ge_u32 s16, s14
	s_cselect_b32 s17, s25, s17
	s_cselect_b32 s16, s24, s16
	s_add_i32 s24, s17, 1
	s_cmp_ge_u32 s16, s14
	s_cselect_b32 s16, s24, s17
	s_xor_b32 s16, s16, s15
	s_sub_i32 s67, s16, s15
	s_mul_i32 s14, s67, s14
	s_sub_i32 s14, s69, s14
	s_lshl_b32 s15, s67, 3
	s_and_b32 s16, s14, 7
	s_ashr_i32 s66, s14, 3
	s_or_b32 s68, s16, s15
	s_lshl_b32 s16, s66, 8
	s_lshl_b32 s14, s68, 8
	s_and_b64 s[24:25], s[22:23], exec
	s_cselect_b32 s24, s45, 0x40000
	s_cselect_b32 s36, 32, 0x80
	s_cselect_b32 s25, s46, 0x1000
	s_or_b32 s26, s14, 0x80
	s_ashr_i32 s27, s26, 31
	s_and_b64 s[28:29], s[22:23], exec
	s_cselect_b32 s37, 6, 12
	s_lshl_b64 s[26:27], s[26:27], s37
	s_add_u32 s26, s18, s26
	s_addc_u32 s27, s19, s27
	s_and_b64 s[28:29], s[22:23], exec
	s_cselect_b32 s28, 18, 7
	s_ashr_i32 s17, s16, 31
	s_and_b64 s[30:31], s[22:23], exec
	s_cselect_b32 s69, 12, 6
	s_lshl_b64 s[30:31], s[16:17], s69
	s_add_u32 s17, s20, s30
	s_addc_u32 s29, s21, s31
	s_ashr_i32 s15, s14, 31
	s_lshl_b64 s[30:31], s[14:15], s37
	s_add_u32 s15, s18, s30
	s_addc_u32 s30, s19, s31
	s_or_b32 s18, s16, s36
	s_ashr_i32 s19, s18, 31
	s_lshl_b64 s[18:19], s[18:19], s69
	v_and_b32_e32 v2, 48, v0
	s_add_u32 s20, s20, s18
	v_lshlrev_b32_e32 v0, 6, v0
	v_or_b32_e32 v5, v3, v2
	s_addc_u32 s21, s21, s19
	v_and_b32_e32 v0, 0x3c0, v0
	v_and_b32_e32 v4, 0x3000, v4
	v_bitop3_b32 v3, v3, v6, v2 bitop3:0x36
	v_bitop3_b32 v7, v5, s56, v6 bitop3:0xde
	v_bitop3_b32 v8, v5, s57, v6 bitop3:0xde
	v_bitop3_b32 v9, v5, s58, v6 bitop3:0xde
	v_bitop3_b32 v5, v5, s59, v6 bitop3:0xde
	v_bitop3_b32 v2, v0, v6, v2 bitop3:0x36
	v_or_b32_e32 v6, 0x800, v1
	v_or_b32_e32 v10, 0x1000, v1
	v_or_b32_e32 v11, 0x1800, v1
	s_and_b64 s[18:19], s[22:23], exec
	v_mov_b32_e32 v0, 0
	v_mov_b32_e32 v129, v165
	s_cselect_b32 s22, 7, 18
	s_mov_b64 s[18:19], 1
	v_add_u32_e32 v134, v7, v4
	v_add_u32_e32 v187, v3, v1
	v_add_u32_e32 v186, v2, v6
	v_add_u32_e32 v185, v2, v10
	v_add_u32_e32 v184, v2, v11
	v_add_u32_e32 v133, 0xc000, v169
	v_add_u32_e32 v132, 0xe000, v169
	v_add_u32_e32 v131, v8, v4
	v_add_u32_e32 v182, 0x10000, v169
	v_add_u32_e32 v181, 0x12000, v169
	v_add_u32_e32 v180, 0x2000, v169
	v_add_u32_e32 v179, 0x14000, v169
	v_add_u32_e32 v178, 0x16000, v169
	v_add_u32_e32 v130, v9, v4
	v_add_u32_e32 v177, 0x4000, v169
	v_add_u32_e32 v176, 0x6000, v169
	v_add_u32_e32 v136, v5, v4
	v_add_u32_e32 v175, 0x18000, v169
	v_add_u32_e32 v174, 0x1a000, v169
	v_add_u32_e32 v173, 0x8000, v169
	v_add_u32_e32 v172, 0xa000, v169
	v_add_u32_e32 v171, 0x1c000, v169
	v_add_u32_e32 v170, 0x1e000, v169
	v_mov_b32_e32 v1, v0
	v_mov_b32_e32 v2, v0
	v_mov_b32_e32 v3, v0
	v_mov_b32_e32 v4, v0
	v_mov_b32_e32 v5, v0
	v_mov_b32_e32 v6, v0
	v_mov_b32_e32 v7, v0
	v_mov_b32_e32 v8, v0
	v_mov_b32_e32 v9, v0
	v_mov_b32_e32 v10, v0
	v_mov_b32_e32 v11, v0
	v_mov_b32_e32 v12, v0
	v_mov_b32_e32 v13, v0
	v_mov_b32_e32 v14, v0
	v_mov_b32_e32 v15, v0
	v_mov_b32_e32 v16, v0
	v_mov_b32_e32 v17, v0
	v_mov_b32_e32 v18, v0
	v_mov_b32_e32 v19, v0
	v_mov_b32_e32 v20, v0
	v_mov_b32_e32 v21, v0
	v_mov_b32_e32 v22, v0
	v_mov_b32_e32 v23, v0
	v_mov_b32_e32 v24, v0
	v_mov_b32_e32 v25, v0
	v_mov_b32_e32 v26, v0
	v_mov_b32_e32 v27, v0
	v_mov_b32_e32 v28, v0
	v_mov_b32_e32 v29, v0
	v_mov_b32_e32 v30, v0
	v_mov_b32_e32 v31, v0
	v_mov_b32_e32 v32, v0
	v_mov_b32_e32 v33, v0
	v_mov_b32_e32 v34, v0
	v_mov_b32_e32 v35, v0
	v_mov_b32_e32 v36, v0
	v_mov_b32_e32 v37, v0
	v_mov_b32_e32 v38, v0
	v_mov_b32_e32 v39, v0
	v_mov_b32_e32 v40, v0
	v_mov_b32_e32 v41, v0
	v_mov_b32_e32 v42, v0
	v_mov_b32_e32 v43, v0
	v_mov_b32_e32 v44, v0
	v_mov_b32_e32 v45, v0
	v_mov_b32_e32 v46, v0
	v_mov_b32_e32 v47, v0
	v_mov_b32_e32 v48, v0
	v_mov_b32_e32 v49, v0
	v_mov_b32_e32 v50, v0
	v_mov_b32_e32 v51, v0
	v_mov_b32_e32 v52, v0
	v_mov_b32_e32 v53, v0
	v_mov_b32_e32 v54, v0
	v_mov_b32_e32 v55, v0
	v_mov_b32_e32 v56, v0
	v_mov_b32_e32 v57, v0
	v_mov_b32_e32 v58, v0
	v_mov_b32_e32 v59, v0
	v_mov_b32_e32 v60, v0
	v_mov_b32_e32 v61, v0
	v_mov_b32_e32 v62, v0
	v_mov_b32_e32 v63, v0
	v_mov_b32_e32 v64, v0
	v_mov_b32_e32 v65, v0
	v_mov_b32_e32 v66, v0
	v_mov_b32_e32 v67, v0
	v_mov_b32_e32 v68, v0
	v_mov_b32_e32 v69, v0
	v_mov_b32_e32 v70, v0
	v_mov_b32_e32 v71, v0
	v_mov_b32_e32 v72, v0
	v_mov_b32_e32 v73, v0
	v_mov_b32_e32 v74, v0
	v_mov_b32_e32 v75, v0
	v_mov_b32_e32 v76, v0
	v_mov_b32_e32 v77, v0
	v_mov_b32_e32 v78, v0
	v_mov_b32_e32 v79, v0
	v_mov_b32_e32 v80, v0
	v_mov_b32_e32 v81, v0
	v_mov_b32_e32 v82, v0
	v_mov_b32_e32 v83, v0
	v_mov_b32_e32 v84, v0
	v_mov_b32_e32 v85, v0
	v_mov_b32_e32 v86, v0
	v_mov_b32_e32 v87, v0
	v_mov_b32_e32 v88, v0
	v_mov_b32_e32 v89, v0
	v_mov_b32_e32 v90, v0
	v_mov_b32_e32 v91, v0
	v_mov_b32_e32 v92, v0
	v_mov_b32_e32 v93, v0
	v_mov_b32_e32 v94, v0
	v_mov_b32_e32 v95, v0
	v_mov_b32_e32 v96, v0
	v_mov_b32_e32 v97, v0
	v_mov_b32_e32 v98, v0
	v_mov_b32_e32 v99, v0
	v_mov_b32_e32 v100, v0
	v_mov_b32_e32 v101, v0
	v_mov_b32_e32 v102, v0
	v_mov_b32_e32 v103, v0
	v_mov_b32_e32 v104, v0
	v_mov_b32_e32 v105, v0
	v_mov_b32_e32 v106, v0
	v_mov_b32_e32 v107, v0
	v_mov_b32_e32 v108, v0
	v_mov_b32_e32 v109, v0
	v_mov_b32_e32 v110, v0
	v_mov_b32_e32 v111, v0
	v_mov_b32_e32 v112, v0
	v_mov_b32_e32 v113, v0
	v_mov_b32_e32 v114, v0
	v_mov_b32_e32 v115, v0
	v_mov_b32_e32 v116, v0
	v_mov_b32_e32 v117, v0
	v_mov_b32_e32 v118, v0
	v_mov_b32_e32 v119, v0
	v_mov_b32_e32 v120, v0
	v_mov_b32_e32 v121, v0
	v_mov_b32_e32 v122, v0
	v_mov_b32_e32 v123, v0
	v_mov_b32_e32 v124, v0
	v_mov_b32_e32 v125, v0
	v_mov_b32_e32 v126, v0
	v_mov_b32_e32 v127, v0
	s_barrier
	s_lshl_b64 s[70:71], s[18:19], s28
	s_add_u32 s70, s26, s70
	s_addc_u32 s71, s27, s71
	v_lshl_add_u64 v[162:163], s[70:71], 0, v[164:165]
	v_readfirstlane_b32 s23, v133
	s_add_u32 s70, s70, s24
	s_mov_b32 m0, s23
	s_addc_u32 s71, s71, 0
	v_readfirstlane_b32 s23, v132
	global_load_lds_dwordx4 v[162:163], off
	v_lshl_add_u64 v[162:163], s[70:71], 0, v[164:165]
	s_mov_b32 m0, s23
	s_nop 0
	global_load_lds_dwordx4 v[162:163], off
.LBB0_356:
	ds_read_b128 v[138:141], v134
	ds_read_b128 v[142:145], v134 offset:1024
	ds_read_b128 v[146:149], v134 offset:2048
	ds_read_b128 v[150:153], v134 offset:3072
	ds_read_b128 v[154:157], v187
	ds_read_b128 v[158:161], v187 offset:1024
	ds_read_b128 v[188:191], v186
	ds_read_b128 v[192:195], v186 offset:1024
	ds_read_b128 v[196:199], v185
	ds_read_b128 v[200:203], v185 offset:1024
	ds_read_b128 v[204:207], v184
	ds_read_b128 v[208:211], v184 offset:1024
	s_waitcnt lgkmcnt(8)
	s_waitcnt vmcnt(10)
	s_barrier
	s_waitcnt lgkmcnt(0)
	s_setprio 1
	s_waitcnt lgkmcnt(0)
	v_mfma_f32_16x16x32_bf16 v[124:127], v[138:141], v[154:157], v[124:127]
	v_mfma_f32_16x16x32_bf16 v[120:123], v[146:149], v[154:157], v[120:123]
	v_mfma_f32_16x16x32_bf16 v[116:119], v[138:141], v[188:191], v[116:119]
	v_mfma_f32_16x16x32_bf16 v[112:115], v[146:149], v[188:191], v[112:115]
	v_mfma_f32_16x16x32_bf16 v[108:111], v[138:141], v[196:199], v[108:111]
	v_mfma_f32_16x16x32_bf16 v[104:107], v[146:149], v[196:199], v[104:107]
	v_mfma_f32_16x16x32_bf16 v[100:103], v[138:141], v[204:207], v[100:103]
	v_mfma_f32_16x16x32_bf16 v[96:99], v[146:149], v[204:207], v[96:99]
	v_mfma_f32_16x16x32_bf16 v[124:127], v[142:145], v[158:161], v[124:127]
	v_mfma_f32_16x16x32_bf16 v[120:123], v[150:153], v[158:161], v[120:123]
	v_mfma_f32_16x16x32_bf16 v[116:119], v[142:145], v[192:195], v[116:119]
	v_mfma_f32_16x16x32_bf16 v[112:115], v[150:153], v[192:195], v[112:115]
	v_mfma_f32_16x16x32_bf16 v[108:111], v[142:145], v[200:203], v[108:111]
	v_mfma_f32_16x16x32_bf16 v[104:107], v[150:153], v[200:203], v[104:107]
	v_mfma_f32_16x16x32_bf16 v[100:103], v[142:145], v[208:211], v[100:103]
	v_mfma_f32_16x16x32_bf16 v[96:99], v[150:153], v[208:211], v[96:99]
	s_setprio 0
	s_barrier
	s_add_u32 s70, s18, 1
	s_addc_u32 s71, s19, 0
	s_lshl_b64 s[72:73], s[70:71], s22
	s_add_u32 s74, s17, s72
	s_addc_u32 s75, s29, s73
	v_lshl_add_u64 v[162:163], s[74:75], 0, v[128:129]
	v_readfirstlane_b32 s23, v182
	s_add_u32 s74, s74, s25
	s_mov_b32 m0, s23
	s_addc_u32 s75, s75, 0
	v_readfirstlane_b32 s23, v181
	ds_read_b128 v[212:215], v131
	ds_read_b128 v[216:219], v131 offset:1024
	ds_read_b128 v[220:223], v131 offset:2048
	ds_read_b128 v[224:227], v131 offset:3072
	global_load_lds_dwordx4 v[162:163], off
	v_lshl_add_u64 v[162:163], s[74:75], 0, v[128:129]
	s_mov_b32 m0, s23
	s_nop 0
	global_load_lds_dwordx4 v[162:163], off
	s_waitcnt vmcnt(10)
	s_barrier
	s_waitcnt lgkmcnt(0)
	s_setprio 1
	s_waitcnt lgkmcnt(0)
	v_mfma_f32_16x16x32_bf16 v[92:95], v[212:215], v[154:157], v[92:95]
	v_mfma_f32_16x16x32_bf16 v[88:91], v[220:223], v[154:157], v[88:91]
	v_mfma_f32_16x16x32_bf16 v[84:87], v[212:215], v[188:191], v[84:87]
	v_mfma_f32_16x16x32_bf16 v[80:83], v[220:223], v[188:191], v[80:83]
	v_mfma_f32_16x16x32_bf16 v[76:79], v[212:215], v[196:199], v[76:79]
	v_mfma_f32_16x16x32_bf16 v[72:75], v[220:223], v[196:199], v[72:75]
	v_mfma_f32_16x16x32_bf16 v[68:71], v[212:215], v[204:207], v[68:71]
	v_mfma_f32_16x16x32_bf16 v[64:67], v[220:223], v[204:207], v[64:67]
	v_mfma_f32_16x16x32_bf16 v[92:95], v[216:219], v[158:161], v[92:95]
	v_mfma_f32_16x16x32_bf16 v[88:91], v[224:227], v[158:161], v[88:91]
	v_mfma_f32_16x16x32_bf16 v[84:87], v[216:219], v[192:195], v[84:87]
	v_mfma_f32_16x16x32_bf16 v[80:83], v[224:227], v[192:195], v[80:83]
	v_mfma_f32_16x16x32_bf16 v[76:79], v[216:219], v[200:203], v[76:79]
	v_mfma_f32_16x16x32_bf16 v[72:75], v[224:227], v[200:203], v[72:75]
	v_mfma_f32_16x16x32_bf16 v[68:71], v[216:219], v[208:211], v[68:71]
	v_mfma_f32_16x16x32_bf16 v[64:67], v[224:227], v[208:211], v[64:67]
	s_setprio 0
	s_lshl_b64 s[70:71], s[70:71], s28
	s_add_u32 s74, s15, s70
	s_addc_u32 s75, s30, s71
	v_lshl_add_u64 v[162:163], s[74:75], 0, v[164:165]
	v_readfirstlane_b32 s23, v169
	s_add_u32 s74, s74, s24
	s_mov_b32 m0, s23
	s_addc_u32 s75, s75, 0
	v_readfirstlane_b32 s23, v180
	s_barrier
	ds_read_b128 v[154:157], v187 offset:16384
	ds_read_b128 v[158:161], v187 offset:17408
	ds_read_b128 v[188:191], v186 offset:16384
	ds_read_b128 v[192:195], v186 offset:17408
	ds_read_b128 v[196:199], v185 offset:16384
	ds_read_b128 v[200:203], v185 offset:17408
	ds_read_b128 v[204:207], v184 offset:16384
	ds_read_b128 v[208:211], v184 offset:17408
	global_load_lds_dwordx4 v[162:163], off
	v_lshl_add_u64 v[162:163], s[74:75], 0, v[164:165]
	s_mov_b32 m0, s23
	s_nop 0
	global_load_lds_dwordx4 v[162:163], off
	s_barrier
	s_waitcnt lgkmcnt(0)
	s_setprio 1
	s_waitcnt lgkmcnt(0)
	v_mfma_f32_16x16x32_bf16 v[60:63], v[138:141], v[154:157], v[60:63]
	v_mfma_f32_16x16x32_bf16 v[56:59], v[146:149], v[154:157], v[56:59]
	v_mfma_f32_16x16x32_bf16 v[52:55], v[138:141], v[188:191], v[52:55]
	v_mfma_f32_16x16x32_bf16 v[48:51], v[146:149], v[188:191], v[48:51]
	v_mfma_f32_16x16x32_bf16 v[44:47], v[138:141], v[196:199], v[44:47]
	v_mfma_f32_16x16x32_bf16 v[40:43], v[146:149], v[196:199], v[40:43]
	v_mfma_f32_16x16x32_bf16 v[36:39], v[138:141], v[204:207], v[36:39]
	v_mfma_f32_16x16x32_bf16 v[32:35], v[146:149], v[204:207], v[32:35]
	v_mfma_f32_16x16x32_bf16 v[60:63], v[142:145], v[158:161], v[60:63]
	v_mfma_f32_16x16x32_bf16 v[56:59], v[150:153], v[158:161], v[56:59]
	v_mfma_f32_16x16x32_bf16 v[52:55], v[142:145], v[192:195], v[52:55]
	v_mfma_f32_16x16x32_bf16 v[48:51], v[150:153], v[192:195], v[48:51]
	v_mfma_f32_16x16x32_bf16 v[44:47], v[142:145], v[200:203], v[44:47]
	v_mfma_f32_16x16x32_bf16 v[40:43], v[150:153], v[200:203], v[40:43]
	v_mfma_f32_16x16x32_bf16 v[36:39], v[142:145], v[208:211], v[36:39]
	v_mfma_f32_16x16x32_bf16 v[32:35], v[150:153], v[208:211], v[32:35]
	s_setprio 0
	s_barrier
	s_add_u32 s72, s20, s72
	s_addc_u32 s73, s21, s73
	v_lshl_add_u64 v[138:139], s[72:73], 0, v[128:129]
	v_readfirstlane_b32 s23, v179
	s_add_u32 s72, s72, s25
	s_mov_b32 m0, s23
	s_addc_u32 s73, s73, 0
	v_readfirstlane_b32 s23, v178
	global_load_lds_dwordx4 v[138:139], off
	v_lshl_add_u64 v[138:139], s[72:73], 0, v[128:129]
	s_mov_b32 m0, s23
	s_nop 0
	global_load_lds_dwordx4 v[138:139], off
	s_add_u32 s70, s26, s70
	s_addc_u32 s71, s27, s71
	v_lshl_add_u64 v[162:163], s[70:71], 0, v[164:165]
	v_readfirstlane_b32 s23, v177
	s_add_u32 s70, s70, s24
	s_mov_b32 m0, s23
	s_addc_u32 s71, s71, 0
	v_readfirstlane_b32 s23, v176
	global_load_lds_dwordx4 v[162:163], off
	v_lshl_add_u64 v[162:163], s[70:71], 0, v[164:165]
	s_mov_b32 m0, s23
	s_nop 0
	global_load_lds_dwordx4 v[162:163], off
	s_waitcnt vmcnt(12)
	s_barrier
	s_setprio 1
	v_mfma_f32_16x16x32_bf16 v[28:31], v[212:215], v[154:157], v[28:31]
	v_mfma_f32_16x16x32_bf16 v[24:27], v[220:223], v[154:157], v[24:27]
	v_mfma_f32_16x16x32_bf16 v[20:23], v[212:215], v[188:191], v[20:23]
	v_mfma_f32_16x16x32_bf16 v[16:19], v[220:223], v[188:191], v[16:19]
	v_mfma_f32_16x16x32_bf16 v[12:15], v[212:215], v[196:199], v[12:15]
	v_mfma_f32_16x16x32_bf16 v[8:11], v[220:223], v[196:199], v[8:11]
	v_mfma_f32_16x16x32_bf16 v[4:7], v[212:215], v[204:207], v[4:7]
	v_mfma_f32_16x16x32_bf16 v[0:3], v[220:223], v[204:207], v[0:3]
	v_mfma_f32_16x16x32_bf16 v[28:31], v[216:219], v[158:161], v[28:31]
	v_mfma_f32_16x16x32_bf16 v[24:27], v[224:227], v[158:161], v[24:27]
	v_mfma_f32_16x16x32_bf16 v[20:23], v[216:219], v[192:195], v[20:23]
	v_mfma_f32_16x16x32_bf16 v[16:19], v[224:227], v[192:195], v[16:19]
	v_mfma_f32_16x16x32_bf16 v[12:15], v[216:219], v[200:203], v[12:15]
	v_mfma_f32_16x16x32_bf16 v[8:11], v[224:227], v[200:203], v[8:11]
	v_mfma_f32_16x16x32_bf16 v[4:7], v[216:219], v[208:211], v[4:7]
	v_mfma_f32_16x16x32_bf16 v[0:3], v[224:227], v[208:211], v[0:3]
	s_setprio 0
	s_barrier
	ds_read_b128 v[138:141], v130
	ds_read_b128 v[142:145], v130 offset:1024
	ds_read_b128 v[146:149], v130 offset:2048
	ds_read_b128 v[150:153], v130 offset:3072
	ds_read_b128 v[154:157], v187 offset:32768
	ds_read_b128 v[158:161], v187 offset:33792
	ds_read_b128 v[188:191], v186 offset:32768
	ds_read_b128 v[192:195], v186 offset:33792
	ds_read_b128 v[196:199], v185 offset:32768
	ds_read_b128 v[200:203], v185 offset:33792
	ds_read_b128 v[204:207], v184 offset:32768
	ds_read_b128 v[208:211], v184 offset:33792
	s_waitcnt lgkmcnt(8)
	s_waitcnt vmcnt(10)
	s_barrier
	s_waitcnt lgkmcnt(0)
	s_setprio 1
	s_waitcnt lgkmcnt(0)
	v_mfma_f32_16x16x32_bf16 v[124:127], v[138:141], v[154:157], v[124:127]
	v_mfma_f32_16x16x32_bf16 v[120:123], v[146:149], v[154:157], v[120:123]
	v_mfma_f32_16x16x32_bf16 v[116:119], v[138:141], v[188:191], v[116:119]
	v_mfma_f32_16x16x32_bf16 v[112:115], v[146:149], v[188:191], v[112:115]
	v_mfma_f32_16x16x32_bf16 v[108:111], v[138:141], v[196:199], v[108:111]
	v_mfma_f32_16x16x32_bf16 v[104:107], v[146:149], v[196:199], v[104:107]
	v_mfma_f32_16x16x32_bf16 v[100:103], v[138:141], v[204:207], v[100:103]
	v_mfma_f32_16x16x32_bf16 v[96:99], v[146:149], v[204:207], v[96:99]
	v_mfma_f32_16x16x32_bf16 v[124:127], v[142:145], v[158:161], v[124:127]
	v_mfma_f32_16x16x32_bf16 v[120:123], v[150:153], v[158:161], v[120:123]
	v_mfma_f32_16x16x32_bf16 v[116:119], v[142:145], v[192:195], v[116:119]
	v_mfma_f32_16x16x32_bf16 v[112:115], v[150:153], v[192:195], v[112:115]
	v_mfma_f32_16x16x32_bf16 v[108:111], v[142:145], v[200:203], v[108:111]
	v_mfma_f32_16x16x32_bf16 v[104:107], v[150:153], v[200:203], v[104:107]
	v_mfma_f32_16x16x32_bf16 v[100:103], v[142:145], v[208:211], v[100:103]
	v_mfma_f32_16x16x32_bf16 v[96:99], v[150:153], v[208:211], v[96:99]
	s_setprio 0
	s_barrier
	s_add_u32 s18, s18, 2
	s_addc_u32 s19, s19, 0
	s_lshl_b64 s[70:71], s[18:19], s22
	s_add_u32 s72, s17, s70
	s_addc_u32 s73, s29, s71
	v_lshl_add_u64 v[162:163], s[72:73], 0, v[128:129]
	v_readfirstlane_b32 s23, v175
	s_add_u32 s72, s72, s25
	s_mov_b32 m0, s23
	s_addc_u32 s73, s73, 0
	v_readfirstlane_b32 s23, v174
	ds_read_b128 v[212:215], v136
	ds_read_b128 v[216:219], v136 offset:1024
	ds_read_b128 v[220:223], v136 offset:2048
	ds_read_b128 v[224:227], v136 offset:3072
	global_load_lds_dwordx4 v[162:163], off
	v_lshl_add_u64 v[162:163], s[72:73], 0, v[128:129]
	s_mov_b32 m0, s23
	s_nop 0
	global_load_lds_dwordx4 v[162:163], off
	s_waitcnt vmcnt(10)
	s_barrier
	s_waitcnt lgkmcnt(0)
	s_setprio 1
	s_waitcnt lgkmcnt(0)
	v_mfma_f32_16x16x32_bf16 v[92:95], v[212:215], v[154:157], v[92:95]
	v_mfma_f32_16x16x32_bf16 v[88:91], v[220:223], v[154:157], v[88:91]
	v_mfma_f32_16x16x32_bf16 v[84:87], v[212:215], v[188:191], v[84:87]
	v_mfma_f32_16x16x32_bf16 v[80:83], v[220:223], v[188:191], v[80:83]
	v_mfma_f32_16x16x32_bf16 v[76:79], v[212:215], v[196:199], v[76:79]
	v_mfma_f32_16x16x32_bf16 v[72:75], v[220:223], v[196:199], v[72:75]
	v_mfma_f32_16x16x32_bf16 v[68:71], v[212:215], v[204:207], v[68:71]
	v_mfma_f32_16x16x32_bf16 v[64:67], v[220:223], v[204:207], v[64:67]
	v_mfma_f32_16x16x32_bf16 v[92:95], v[216:219], v[158:161], v[92:95]
	v_mfma_f32_16x16x32_bf16 v[88:91], v[224:227], v[158:161], v[88:91]
	v_mfma_f32_16x16x32_bf16 v[84:87], v[216:219], v[192:195], v[84:87]
	v_mfma_f32_16x16x32_bf16 v[80:83], v[224:227], v[192:195], v[80:83]
	v_mfma_f32_16x16x32_bf16 v[76:79], v[216:219], v[200:203], v[76:79]
	v_mfma_f32_16x16x32_bf16 v[72:75], v[224:227], v[200:203], v[72:75]
	v_mfma_f32_16x16x32_bf16 v[68:71], v[216:219], v[208:211], v[68:71]
	v_mfma_f32_16x16x32_bf16 v[64:67], v[224:227], v[208:211], v[64:67]
	s_setprio 0
	s_lshl_b64 s[72:73], s[18:19], s28
	s_add_u32 s72, s15, s72
	s_addc_u32 s73, s30, s73
	v_lshl_add_u64 v[162:163], s[72:73], 0, v[164:165]
	v_readfirstlane_b32 s23, v173
	s_add_u32 s72, s72, s24
	s_mov_b32 m0, s23
	s_addc_u32 s73, s73, 0
	v_readfirstlane_b32 s23, v172
	s_barrier
	ds_read_b128 v[154:157], v187 offset:49152
	ds_read_b128 v[158:161], v187 offset:50176
	ds_read_b128 v[188:191], v186 offset:49152
	ds_read_b128 v[192:195], v186 offset:50176
	ds_read_b128 v[196:199], v185 offset:49152
	ds_read_b128 v[200:203], v185 offset:50176
	ds_read_b128 v[204:207], v184 offset:49152
	ds_read_b128 v[208:211], v184 offset:50176
	global_load_lds_dwordx4 v[162:163], off
	v_lshl_add_u64 v[162:163], s[72:73], 0, v[164:165]
	s_mov_b32 m0, s23
	s_nop 0
	global_load_lds_dwordx4 v[162:163], off
	s_barrier
	s_waitcnt lgkmcnt(0)
	s_setprio 1
	s_waitcnt lgkmcnt(0)
	v_mfma_f32_16x16x32_bf16 v[60:63], v[138:141], v[154:157], v[60:63]
	v_mfma_f32_16x16x32_bf16 v[56:59], v[146:149], v[154:157], v[56:59]
	v_mfma_f32_16x16x32_bf16 v[52:55], v[138:141], v[188:191], v[52:55]
	v_mfma_f32_16x16x32_bf16 v[48:51], v[146:149], v[188:191], v[48:51]
	v_mfma_f32_16x16x32_bf16 v[44:47], v[138:141], v[196:199], v[44:47]
	v_mfma_f32_16x16x32_bf16 v[40:43], v[146:149], v[196:199], v[40:43]
	v_mfma_f32_16x16x32_bf16 v[36:39], v[138:141], v[204:207], v[36:39]
	v_mfma_f32_16x16x32_bf16 v[32:35], v[146:149], v[204:207], v[32:35]
	v_mfma_f32_16x16x32_bf16 v[60:63], v[142:145], v[158:161], v[60:63]
	v_mfma_f32_16x16x32_bf16 v[56:59], v[150:153], v[158:161], v[56:59]
	v_mfma_f32_16x16x32_bf16 v[52:55], v[142:145], v[192:195], v[52:55]
	v_mfma_f32_16x16x32_bf16 v[48:51], v[150:153], v[192:195], v[48:51]
	v_mfma_f32_16x16x32_bf16 v[44:47], v[142:145], v[200:203], v[44:47]
	v_mfma_f32_16x16x32_bf16 v[40:43], v[150:153], v[200:203], v[40:43]
	v_mfma_f32_16x16x32_bf16 v[36:39], v[142:145], v[208:211], v[36:39]
	v_mfma_f32_16x16x32_bf16 v[32:35], v[150:153], v[208:211], v[32:35]
	s_setprio 0
	s_barrier
	s_add_u32 s70, s20, s70
	s_addc_u32 s71, s21, s71
	v_lshl_add_u64 v[138:139], s[70:71], 0, v[128:129]
	v_readfirstlane_b32 s23, v171
	s_add_u32 s70, s70, s25
	s_mov_b32 m0, s23
	s_addc_u32 s71, s71, 0
	v_readfirstlane_b32 s23, v170
	global_load_lds_dwordx4 v[138:139], off
	v_lshl_add_u64 v[138:139], s[70:71], 0, v[128:129]
	s_mov_b32 m0, s23
	s_nop 0
	global_load_lds_dwordx4 v[138:139], off
	s_lshl_b64 s[70:71], s[18:19], s28
	s_add_u32 s70, s26, s70
	s_addc_u32 s71, s27, s71
	v_lshl_add_u64 v[162:163], s[70:71], 0, v[164:165]
	v_readfirstlane_b32 s23, v133
	s_add_u32 s70, s70, s24
	s_mov_b32 m0, s23
	s_addc_u32 s71, s71, 0
	v_readfirstlane_b32 s23, v132
	global_load_lds_dwordx4 v[162:163], off
	v_lshl_add_u64 v[162:163], s[70:71], 0, v[164:165]
	s_mov_b32 m0, s23
	s_nop 0
	global_load_lds_dwordx4 v[162:163], off
	s_waitcnt vmcnt(12)
	s_barrier
	s_setprio 1
	v_mfma_f32_16x16x32_bf16 v[28:31], v[212:215], v[154:157], v[28:31]
	v_mfma_f32_16x16x32_bf16 v[24:27], v[220:223], v[154:157], v[24:27]
	v_mfma_f32_16x16x32_bf16 v[20:23], v[212:215], v[188:191], v[20:23]
	v_mfma_f32_16x16x32_bf16 v[16:19], v[220:223], v[188:191], v[16:19]
	v_mfma_f32_16x16x32_bf16 v[12:15], v[212:215], v[196:199], v[12:15]
	v_mfma_f32_16x16x32_bf16 v[8:11], v[220:223], v[196:199], v[8:11]
	v_mfma_f32_16x16x32_bf16 v[4:7], v[212:215], v[204:207], v[4:7]
	v_mfma_f32_16x16x32_bf16 v[0:3], v[220:223], v[204:207], v[0:3]
	v_mfma_f32_16x16x32_bf16 v[28:31], v[216:219], v[158:161], v[28:31]
	v_mfma_f32_16x16x32_bf16 v[24:27], v[224:227], v[158:161], v[24:27]
	v_mfma_f32_16x16x32_bf16 v[20:23], v[216:219], v[192:195], v[20:23]
	v_mfma_f32_16x16x32_bf16 v[16:19], v[224:227], v[192:195], v[16:19]
	v_mfma_f32_16x16x32_bf16 v[12:15], v[216:219], v[200:203], v[12:15]
	v_mfma_f32_16x16x32_bf16 v[8:11], v[224:227], v[200:203], v[8:11]
	v_mfma_f32_16x16x32_bf16 v[4:7], v[216:219], v[208:211], v[4:7]
	v_mfma_f32_16x16x32_bf16 v[0:3], v[224:227], v[208:211], v[0:3]
	s_setprio 0
	s_add_i32 s23, s18, -3
	s_cmp_lt_u32 s23, 28
	s_barrier
	s_cbranch_scc1 .LBB0_356
	s_lshl_b64 s[18:19], 31, s28
	s_add_u32 s18, s26, s18
	s_addc_u32 s19, s27, s19
	v_lshl_add_u64 v[128:129], s[18:19], 0, v[164:165]
	v_readfirstlane_b32 s15, v133
	s_add_u32 s18, s18, s24
	s_mov_b32 m0, s15
	s_addc_u32 s19, s19, 0
	v_readfirstlane_b32 s15, v132
	ds_read_b128 v[138:141], v134
	ds_read_b128 v[142:145], v134 offset:1024
	ds_read_b128 v[146:149], v134 offset:2048
	ds_read_b128 v[150:153], v134 offset:3072
	ds_read_b128 v[154:157], v187
	ds_read_b128 v[158:161], v187 offset:1024
	ds_read_b128 v[188:191], v186
	ds_read_b128 v[192:195], v186 offset:1024
	ds_read_b128 v[196:199], v185
	ds_read_b128 v[200:203], v185 offset:1024
	ds_read_b128 v[204:207], v184
	ds_read_b128 v[208:211], v184 offset:1024
	global_load_lds_dwordx4 v[128:129], off
	v_lshl_add_u64 v[128:129], s[18:19], 0, v[164:165]
	s_mov_b32 m0, s15
	s_nop 0
	global_load_lds_dwordx4 v[128:129], off
	s_waitcnt vmcnt(10)
	s_barrier
	s_waitcnt lgkmcnt(0)
	s_setprio 1
	s_waitcnt lgkmcnt(0)
	v_mfma_f32_16x16x32_bf16 v[124:127], v[138:141], v[154:157], v[124:127]
	v_mfma_f32_16x16x32_bf16 v[120:123], v[146:149], v[154:157], v[120:123]
	v_mfma_f32_16x16x32_bf16 v[116:119], v[138:141], v[188:191], v[116:119]
	v_mfma_f32_16x16x32_bf16 v[112:115], v[146:149], v[188:191], v[112:115]
	v_mfma_f32_16x16x32_bf16 v[108:111], v[138:141], v[196:199], v[108:111]
	v_mfma_f32_16x16x32_bf16 v[104:107], v[146:149], v[196:199], v[104:107]
	v_mfma_f32_16x16x32_bf16 v[100:103], v[138:141], v[204:207], v[100:103]
	v_mfma_f32_16x16x32_bf16 v[96:99], v[146:149], v[204:207], v[96:99]
	v_mfma_f32_16x16x32_bf16 v[124:127], v[142:145], v[158:161], v[124:127]
	v_mfma_f32_16x16x32_bf16 v[120:123], v[150:153], v[158:161], v[120:123]
	v_mfma_f32_16x16x32_bf16 v[116:119], v[142:145], v[192:195], v[116:119]
	v_mfma_f32_16x16x32_bf16 v[112:115], v[150:153], v[192:195], v[112:115]
	v_mfma_f32_16x16x32_bf16 v[108:111], v[142:145], v[200:203], v[108:111]
	v_mfma_f32_16x16x32_bf16 v[104:107], v[150:153], v[200:203], v[104:107]
	v_mfma_f32_16x16x32_bf16 v[100:103], v[142:145], v[208:211], v[100:103]
	v_mfma_f32_16x16x32_bf16 v[96:99], v[150:153], v[208:211], v[96:99]
	s_setprio 0
	s_barrier
	ds_read_b128 v[132:135], v131
	ds_read_b128 v[212:215], v131 offset:1024
	ds_read_b128 v[216:219], v131 offset:2048
	ds_read_b128 v[220:223], v131 offset:3072
	s_barrier
	s_waitcnt lgkmcnt(0)
	s_setprio 1
	s_waitcnt lgkmcnt(0)
	v_mfma_f32_16x16x32_bf16 v[92:95], v[132:135], v[154:157], v[92:95]
	v_mfma_f32_16x16x32_bf16 v[88:91], v[216:219], v[154:157], v[88:91]
	v_mfma_f32_16x16x32_bf16 v[84:87], v[132:135], v[188:191], v[84:87]
	v_mfma_f32_16x16x32_bf16 v[80:83], v[216:219], v[188:191], v[80:83]
	v_mfma_f32_16x16x32_bf16 v[76:79], v[132:135], v[196:199], v[76:79]
	v_mfma_f32_16x16x32_bf16 v[72:75], v[216:219], v[196:199], v[72:75]
	v_mfma_f32_16x16x32_bf16 v[68:71], v[132:135], v[204:207], v[68:71]
	v_mfma_f32_16x16x32_bf16 v[64:67], v[216:219], v[204:207], v[64:67]
	v_mfma_f32_16x16x32_bf16 v[154:157], v[212:215], v[158:161], v[92:95]
	v_mfma_f32_16x16x32_bf16 v[158:161], v[220:223], v[158:161], v[88:91]
	v_mfma_f32_16x16x32_bf16 v[188:191], v[212:215], v[192:195], v[84:87]
	v_mfma_f32_16x16x32_bf16 v[192:195], v[220:223], v[192:195], v[80:83]
	v_mfma_f32_16x16x32_bf16 v[196:199], v[212:215], v[200:203], v[76:79]
	v_mfma_f32_16x16x32_bf16 v[200:203], v[220:223], v[200:203], v[72:75]
	v_mfma_f32_16x16x32_bf16 v[204:207], v[212:215], v[208:211], v[68:71]
	v_mfma_f32_16x16x32_bf16 v[208:211], v[220:223], v[208:211], v[64:67]
	s_setprio 0
	s_barrier
	s_nop 0
	ds_read_b128 v[64:67], v187 offset:16384
	ds_read_b128 v[68:71], v187 offset:17408
	ds_read_b128 v[72:75], v186 offset:16384
	ds_read_b128 v[76:79], v186 offset:17408
	ds_read_b128 v[80:83], v185 offset:16384
	ds_read_b128 v[84:87], v185 offset:17408
	ds_read_b128 v[88:91], v184 offset:16384
	ds_read_b128 v[92:95], v184 offset:17408
	s_waitcnt vmcnt(4)
	s_barrier
	s_waitcnt lgkmcnt(0)
	s_setprio 1
	s_waitcnt lgkmcnt(0)
	v_mfma_f32_16x16x32_bf16 v[60:63], v[138:141], v[64:67], v[60:63]
	v_mfma_f32_16x16x32_bf16 v[56:59], v[146:149], v[64:67], v[56:59]
	v_mfma_f32_16x16x32_bf16 v[52:55], v[138:141], v[72:75], v[52:55]
	v_mfma_f32_16x16x32_bf16 v[48:51], v[146:149], v[72:75], v[48:51]
	v_mfma_f32_16x16x32_bf16 v[224:227], v[138:141], v[80:83], v[44:47]
	v_mfma_f32_16x16x32_bf16 v[228:231], v[146:149], v[80:83], v[40:43]
	v_mfma_f32_16x16x32_bf16 v[138:141], v[138:141], v[88:91], v[36:39]
	v_mfma_f32_16x16x32_bf16 v[146:149], v[146:149], v[88:91], v[32:35]
	v_mfma_f32_16x16x32_bf16 v[32:35], v[142:145], v[68:71], v[60:63]
	v_mfma_f32_16x16x32_bf16 v[36:39], v[150:153], v[68:71], v[56:59]
	v_mfma_f32_16x16x32_bf16 v[40:43], v[142:145], v[76:79], v[52:55]
	v_mfma_f32_16x16x32_bf16 v[44:47], v[150:153], v[76:79], v[48:51]
	v_mfma_f32_16x16x32_bf16 v[48:51], v[142:145], v[84:87], v[224:227]
	v_mfma_f32_16x16x32_bf16 v[52:55], v[150:153], v[84:87], v[228:231]
	v_mfma_f32_16x16x32_bf16 v[56:59], v[142:145], v[92:95], v[138:141]
	v_mfma_f32_16x16x32_bf16 v[60:63], v[150:153], v[92:95], v[146:149]
	s_setprio 0
	s_setprio 1
	v_mfma_f32_16x16x32_bf16 v[28:31], v[132:135], v[64:67], v[28:31]
	v_mfma_f32_16x16x32_bf16 v[24:27], v[216:219], v[64:67], v[24:27]
	v_mfma_f32_16x16x32_bf16 v[20:23], v[132:135], v[72:75], v[20:23]
	v_mfma_f32_16x16x32_bf16 v[16:19], v[216:219], v[72:75], v[16:19]
	v_mfma_f32_16x16x32_bf16 v[64:67], v[132:135], v[80:83], v[12:15]
	v_mfma_f32_16x16x32_bf16 v[8:11], v[216:219], v[80:83], v[8:11]
	v_mfma_f32_16x16x32_bf16 v[72:75], v[132:135], v[88:91], v[4:7]
	v_mfma_f32_16x16x32_bf16 v[0:3], v[216:219], v[88:91], v[0:3]
	v_mfma_f32_16x16x32_bf16 v[4:7], v[212:215], v[68:71], v[28:31]
	v_mfma_f32_16x16x32_bf16 v[12:15], v[220:223], v[68:71], v[24:27]
	v_mfma_f32_16x16x32_bf16 v[20:23], v[212:215], v[76:79], v[20:23]
	v_mfma_f32_16x16x32_bf16 v[28:31], v[220:223], v[76:79], v[16:19]
	v_mfma_f32_16x16x32_bf16 v[64:67], v[212:215], v[84:87], v[64:67]
	v_mfma_f32_16x16x32_bf16 v[68:71], v[220:223], v[84:87], v[8:11]
	v_mfma_f32_16x16x32_bf16 v[72:75], v[212:215], v[92:95], v[72:75]
	v_mfma_f32_16x16x32_bf16 v[76:79], v[220:223], v[92:95], v[0:3]
	s_setprio 0
	s_barrier
	ds_read_b128 v[8:11], v130
	ds_read_b128 v[0:3], v130 offset:1024
	ds_read_b128 v[16:19], v130 offset:2048
	ds_read_b128 v[80:83], v130 offset:3072
	ds_read_b128 v[138:141], v187 offset:32768
	ds_read_b128 v[212:215], v187 offset:33792
	ds_read_b128 v[216:219], v186 offset:32768
	ds_read_b128 v[220:223], v186 offset:33792
	ds_read_b128 v[224:227], v185 offset:32768
	ds_read_b128 v[228:231], v185 offset:33792
	ds_read_b128 v[232:235], v184 offset:32768
	ds_read_b128 v[236:239], v184 offset:33792
	s_waitcnt vmcnt(2)
	s_barrier
	s_waitcnt lgkmcnt(0)
	s_setprio 1
	s_waitcnt lgkmcnt(0)
	v_mfma_f32_16x16x32_bf16 v[24:27], v[8:11], v[138:141], v[124:127]
	v_mfma_f32_16x16x32_bf16 v[84:87], v[16:19], v[138:141], v[120:123]
	v_mfma_f32_16x16x32_bf16 v[88:91], v[8:11], v[216:219], v[116:119]
	v_mfma_f32_16x16x32_bf16 v[92:95], v[16:19], v[216:219], v[112:115]
	v_mfma_f32_16x16x32_bf16 v[108:111], v[8:11], v[224:227], v[108:111]
	v_mfma_f32_16x16x32_bf16 v[104:107], v[16:19], v[224:227], v[104:107]
	v_mfma_f32_16x16x32_bf16 v[100:103], v[8:11], v[232:235], v[100:103]
	v_mfma_f32_16x16x32_bf16 v[96:99], v[16:19], v[232:235], v[96:99]
	v_mfma_f32_16x16x32_bf16 v[148:151], v[0:3], v[212:215], v[24:27]
	v_mfma_f32_16x16x32_bf16 v[144:147], v[80:83], v[212:215], v[84:87]
	v_mfma_f32_16x16x32_bf16 v[132:135], v[0:3], v[220:223], v[88:91]
	v_mfma_f32_16x16x32_bf16 v[128:131], v[80:83], v[220:223], v[92:95]
	v_mfma_f32_16x16x32_bf16 v[116:119], v[0:3], v[228:231], v[108:111]
	v_mfma_f32_16x16x32_bf16 v[112:115], v[80:83], v[228:231], v[104:107]
	v_mfma_f32_16x16x32_bf16 v[100:103], v[0:3], v[236:239], v[100:103]
	v_mfma_f32_16x16x32_bf16 v[24:27], v[80:83], v[236:239], v[96:99]
	s_setprio 0
	s_barrier
	ds_read_b128 v[92:95], v136
	ds_read_b128 v[84:87], v136 offset:1024
	ds_read_b128 v[96:99], v136 offset:2048
	ds_read_b128 v[88:91], v136 offset:3072
	s_waitcnt vmcnt(0)
	s_barrier
	s_waitcnt lgkmcnt(0)
	s_setprio 1
	s_waitcnt lgkmcnt(0)
	v_mfma_f32_16x16x32_bf16 v[104:107], v[92:95], v[138:141], v[154:157]
	v_mfma_f32_16x16x32_bf16 v[108:111], v[96:99], v[138:141], v[158:161]
	v_mfma_f32_16x16x32_bf16 v[120:123], v[92:95], v[216:219], v[188:191]
	v_mfma_f32_16x16x32_bf16 v[124:127], v[96:99], v[216:219], v[192:195]
	v_mfma_f32_16x16x32_bf16 v[160:163], v[92:95], v[224:227], v[196:199]
	v_mfma_f32_16x16x32_bf16 v[188:191], v[96:99], v[224:227], v[200:203]
	v_mfma_f32_16x16x32_bf16 v[192:195], v[92:95], v[232:235], v[204:207]
	v_mfma_f32_16x16x32_bf16 v[196:199], v[96:99], v[232:235], v[208:211]
	v_mfma_f32_16x16x32_bf16 v[156:159], v[84:87], v[212:215], v[104:107]
	v_mfma_f32_16x16x32_bf16 v[152:155], v[88:91], v[212:215], v[108:111]
	v_mfma_f32_16x16x32_bf16 v[140:143], v[84:87], v[220:223], v[120:123]
	v_mfma_f32_16x16x32_bf16 v[136:139], v[88:91], v[220:223], v[124:127]
	v_mfma_f32_16x16x32_bf16 v[124:127], v[84:87], v[228:231], v[160:163]
	v_mfma_f32_16x16x32_bf16 v[120:123], v[88:91], v[228:231], v[188:191]
	v_mfma_f32_16x16x32_bf16 v[108:111], v[84:87], v[236:239], v[192:195]
	v_mfma_f32_16x16x32_bf16 v[104:107], v[88:91], v[236:239], v[196:199]
	s_setprio 0
	s_barrier
	v_mbcnt_lo_u32_b32 v164, -1, 0
	v_mbcnt_hi_u32_b32 v164, -1, v164
	s_cmp_lt_i32 s64, 3
	v_add_u32_e32 v160, s34, v164
	v_ashrrev_i32_e32 v192, 6, v160
	v_bfe_u32 v190, v160, 8, 1
	v_and_b32_e32 v191, 3, v192
	v_and_b32_e32 v188, 15, v164
	v_bfe_u32 v189, v160, 4, 2
	s_mov_b64 s[18:19], 0
	s_cbranch_scc1 .LBB0_362
	v_lshrrev_b32_e32 v160, 4, v160
	v_lshlrev_b32_e32 v162, 9, v189
	v_lshlrev_b32_e32 v163, 9, v160
	s_mov_b64 s[20:21], -1
	s_cmp_gt_i32 s64, 3
	v_lshlrev_b32_e32 v161, 4, v188
	v_and_b32_e32 v160, 0x400, v162
	v_and_b32_e32 v162, 0x200, v163
	s_cbranch_scc0 .LBB0_360
	s_lshl_b32 s15, s66, 20
	s_lshl_b32 s20, s66, 16
	s_and_b32 s15, s15, 0xff000000
	s_and_b32 s20, s20, 0xf0000
	s_lshl_b32 s17, s68, 21
	s_or_b32 s15, s20, s15
	v_lshlrev_b32_e32 v163, 14, v191
	s_add_i32 s15, s15, s17
	v_lshlrev_b32_e32 v166, 12, v190
	v_or3_b32 v163, s15, v161, v163
	v_or3_b32 v163, v163, v166, v162
	v_add_u32_e32 v166, v163, v160
	s_mov_b64 s[20:21], 0

.LBB0_465:
	ds_read_b128 v[164:167], v162
	ds_read_b128 v[168:171], v162 offset:1024
	ds_read_b128 v[172:175], v162 offset:2048
	ds_read_b128 v[176:179], v162 offset:3072
	ds_read_b128 v[180:183], v153
	ds_read_b128 v[184:187], v153 offset:1024
	ds_read_b128 v[188:191], v152
	ds_read_b128 v[192:195], v152 offset:1024
	ds_read_b128 v[196:199], v151
	ds_read_b128 v[200:203], v151 offset:1024
	ds_read_b128 v[204:207], v150
	ds_read_b128 v[208:211], v150 offset:1024
	s_waitcnt lgkmcnt(8)
	s_waitcnt vmcnt(10)
	s_barrier
	s_waitcnt lgkmcnt(0)
	s_setprio 1
	s_waitcnt lgkmcnt(0)
	v_mfma_f32_16x16x32_bf16 v[124:127], v[164:167], v[180:183], v[124:127]
	v_mfma_f32_16x16x32_bf16 v[120:123], v[172:175], v[180:183], v[120:123]
	v_mfma_f32_16x16x32_bf16 v[116:119], v[164:167], v[188:191], v[116:119]
	v_mfma_f32_16x16x32_bf16 v[112:115], v[172:175], v[188:191], v[112:115]
	v_mfma_f32_16x16x32_bf16 v[108:111], v[164:167], v[196:199], v[108:111]
	v_mfma_f32_16x16x32_bf16 v[104:107], v[172:175], v[196:199], v[104:107]
	v_mfma_f32_16x16x32_bf16 v[100:103], v[164:167], v[204:207], v[100:103]
	v_mfma_f32_16x16x32_bf16 v[96:99], v[172:175], v[204:207], v[96:99]
	v_mfma_f32_16x16x32_bf16 v[124:127], v[168:171], v[184:187], v[124:127]
	v_mfma_f32_16x16x32_bf16 v[120:123], v[176:179], v[184:187], v[120:123]
	v_mfma_f32_16x16x32_bf16 v[116:119], v[168:171], v[192:195], v[116:119]
	v_mfma_f32_16x16x32_bf16 v[112:115], v[176:179], v[192:195], v[112:115]
	v_mfma_f32_16x16x32_bf16 v[108:111], v[168:171], v[200:203], v[108:111]
	v_mfma_f32_16x16x32_bf16 v[104:107], v[176:179], v[200:203], v[104:107]
	v_mfma_f32_16x16x32_bf16 v[100:103], v[168:171], v[208:211], v[100:103]
	v_mfma_f32_16x16x32_bf16 v[96:99], v[176:179], v[208:211], v[96:99]
	s_setprio 0
	s_barrier
	v_lshl_add_u64 v[230:231], s[50:51], 0, v[130:131]
	s_mov_b64 s[68:69], 0x3880000
	v_readfirstlane_b32 s36, v149
	v_lshl_add_u64 v[232:233], v[230:231], 0, s[68:69]
	s_mov_b32 m0, s36
	s_mov_b64 s[68:69], 0x3881000
	v_readfirstlane_b32 s36, v148
	ds_read_b128 v[212:215], v159
	ds_read_b128 v[216:219], v159 offset:1024
	ds_read_b128 v[220:223], v159 offset:2048
	ds_read_b128 v[224:227], v159 offset:3072
	global_load_lds_dwordx4 v[232:233], off
	v_lshl_add_u64 v[232:233], v[230:231], 0, s[68:69]
	s_mov_b32 m0, s36
	s_nop 0
	global_load_lds_dwordx4 v[232:233], off
	s_waitcnt vmcnt(10)
	s_barrier
	s_waitcnt lgkmcnt(0)
	s_setprio 1
	s_waitcnt lgkmcnt(0)
	v_mfma_f32_16x16x32_bf16 v[92:95], v[212:215], v[180:183], v[92:95]
	v_mfma_f32_16x16x32_bf16 v[88:91], v[220:223], v[180:183], v[88:91]
	v_mfma_f32_16x16x32_bf16 v[84:87], v[212:215], v[188:191], v[84:87]
	v_mfma_f32_16x16x32_bf16 v[80:83], v[220:223], v[188:191], v[80:83]
	v_mfma_f32_16x16x32_bf16 v[76:79], v[212:215], v[196:199], v[76:79]
	v_mfma_f32_16x16x32_bf16 v[72:75], v[220:223], v[196:199], v[72:75]
	v_mfma_f32_16x16x32_bf16 v[68:71], v[212:215], v[204:207], v[68:71]
	v_mfma_f32_16x16x32_bf16 v[64:67], v[220:223], v[204:207], v[64:67]
	v_mfma_f32_16x16x32_bf16 v[92:95], v[216:219], v[184:187], v[92:95]
	v_mfma_f32_16x16x32_bf16 v[88:91], v[224:227], v[184:187], v[88:91]
	v_mfma_f32_16x16x32_bf16 v[84:87], v[216:219], v[192:195], v[84:87]
	v_mfma_f32_16x16x32_bf16 v[80:83], v[224:227], v[192:195], v[80:83]
	v_mfma_f32_16x16x32_bf16 v[76:79], v[216:219], v[200:203], v[76:79]
	v_mfma_f32_16x16x32_bf16 v[72:75], v[224:227], v[200:203], v[72:75]
	v_mfma_f32_16x16x32_bf16 v[68:71], v[216:219], v[208:211], v[68:71]
	v_mfma_f32_16x16x32_bf16 v[64:67], v[224:227], v[208:211], v[64:67]
	s_setprio 0
	s_mov_b64 s[68:69], 0xe000100
	v_readfirstlane_b32 s36, v135
	v_lshl_add_u64 v[232:233], v[228:229], 0, s[68:69]
	s_mov_b32 m0, s36
	s_mov_b64 s[68:69], 0xe040100
	v_readfirstlane_b32 s36, v147
	s_barrier
	ds_read_b128 v[180:183], v153 offset:16384
	ds_read_b128 v[184:187], v153 offset:17408
	ds_read_b128 v[188:191], v152 offset:16384
	ds_read_b128 v[192:195], v152 offset:17408
	ds_read_b128 v[196:199], v151 offset:16384
	ds_read_b128 v[200:203], v151 offset:17408
	ds_read_b128 v[204:207], v150 offset:16384
	ds_read_b128 v[208:211], v150 offset:17408
	global_load_lds_dwordx4 v[232:233], off
	v_lshl_add_u64 v[232:233], v[228:229], 0, s[68:69]
	s_mov_b32 m0, s36
	s_nop 0
	global_load_lds_dwordx4 v[232:233], off
	s_barrier
	s_waitcnt lgkmcnt(0)
	s_setprio 1
	s_waitcnt lgkmcnt(0)
	v_mfma_f32_16x16x32_bf16 v[60:63], v[164:167], v[180:183], v[60:63]
	v_mfma_f32_16x16x32_bf16 v[56:59], v[172:175], v[180:183], v[56:59]
	v_mfma_f32_16x16x32_bf16 v[52:55], v[164:167], v[188:191], v[52:55]
	v_mfma_f32_16x16x32_bf16 v[48:51], v[172:175], v[188:191], v[48:51]
	v_mfma_f32_16x16x32_bf16 v[44:47], v[164:167], v[196:199], v[44:47]
	v_mfma_f32_16x16x32_bf16 v[40:43], v[172:175], v[196:199], v[40:43]
	v_mfma_f32_16x16x32_bf16 v[36:39], v[164:167], v[204:207], v[36:39]
	v_mfma_f32_16x16x32_bf16 v[32:35], v[172:175], v[204:207], v[32:35]
	v_mfma_f32_16x16x32_bf16 v[60:63], v[168:171], v[184:187], v[60:63]
	v_mfma_f32_16x16x32_bf16 v[56:59], v[176:179], v[184:187], v[56:59]
	v_mfma_f32_16x16x32_bf16 v[52:55], v[168:171], v[192:195], v[52:55]
	v_mfma_f32_16x16x32_bf16 v[48:51], v[176:179], v[192:195], v[48:51]
	v_mfma_f32_16x16x32_bf16 v[44:47], v[168:171], v[200:203], v[44:47]
	v_mfma_f32_16x16x32_bf16 v[40:43], v[176:179], v[200:203], v[40:43]
	v_mfma_f32_16x16x32_bf16 v[36:39], v[168:171], v[208:211], v[36:39]
	v_mfma_f32_16x16x32_bf16 v[32:35], v[176:179], v[208:211], v[32:35]
	s_setprio 0
	s_barrier
	s_mov_b64 s[68:69], 0x3882000
	v_readfirstlane_b32 s36, v146
	v_lshl_add_u64 v[164:165], v[230:231], 0, s[68:69]
	s_mov_b32 m0, s36
	s_mov_b64 s[68:69], 0x3883000
	v_readfirstlane_b32 s36, v145
	global_load_lds_dwordx4 v[164:165], off
	v_lshl_add_u64 v[164:165], v[230:231], 0, s[68:69]
	s_mov_b32 m0, s36
	s_nop 0
	global_load_lds_dwordx4 v[164:165], off
	v_readfirstlane_b32 s36, v144
	v_lshl_add_u64 v[166:167], v[228:229], 0, s[26:27]
	s_mov_b32 m0, s36
	v_readfirstlane_b32 s36, v143
	global_load_lds_dwordx4 v[166:167], off
	v_lshl_add_u64 v[166:167], v[228:229], 0, s[28:29]
	s_mov_b32 m0, s36
	s_nop 0
	global_load_lds_dwordx4 v[166:167], off
	s_waitcnt vmcnt(12)
	s_barrier
	s_setprio 1
	v_mfma_f32_16x16x32_bf16 v[28:31], v[212:215], v[180:183], v[28:31]
	v_mfma_f32_16x16x32_bf16 v[24:27], v[220:223], v[180:183], v[24:27]
	v_mfma_f32_16x16x32_bf16 v[20:23], v[212:215], v[188:191], v[20:23]
	v_mfma_f32_16x16x32_bf16 v[16:19], v[220:223], v[188:191], v[16:19]
	v_mfma_f32_16x16x32_bf16 v[12:15], v[212:215], v[196:199], v[12:15]
	v_mfma_f32_16x16x32_bf16 v[8:11], v[220:223], v[196:199], v[8:11]
	v_mfma_f32_16x16x32_bf16 v[4:7], v[212:215], v[204:207], v[4:7]
	v_mfma_f32_16x16x32_bf16 v[0:3], v[220:223], v[204:207], v[0:3]
	v_mfma_f32_16x16x32_bf16 v[28:31], v[216:219], v[184:187], v[28:31]
	v_mfma_f32_16x16x32_bf16 v[24:27], v[224:227], v[184:187], v[24:27]
	v_mfma_f32_16x16x32_bf16 v[20:23], v[216:219], v[192:195], v[20:23]
	v_mfma_f32_16x16x32_bf16 v[16:19], v[224:227], v[192:195], v[16:19]
	v_mfma_f32_16x16x32_bf16 v[12:15], v[216:219], v[200:203], v[12:15]
	v_mfma_f32_16x16x32_bf16 v[8:11], v[224:227], v[200:203], v[8:11]
	v_mfma_f32_16x16x32_bf16 v[4:7], v[216:219], v[208:211], v[4:7]
	v_mfma_f32_16x16x32_bf16 v[0:3], v[224:227], v[208:211], v[0:3]
	s_setprio 0
	s_barrier
	ds_read_b128 v[164:167], v155
	ds_read_b128 v[168:171], v155 offset:1024
	ds_read_b128 v[172:175], v155 offset:2048
	ds_read_b128 v[176:179], v155 offset:3072
	ds_read_b128 v[180:183], v153 offset:32768
	ds_read_b128 v[184:187], v153 offset:33792
	ds_read_b128 v[188:191], v152 offset:32768
	ds_read_b128 v[192:195], v152 offset:33792
	ds_read_b128 v[196:199], v151 offset:32768
	ds_read_b128 v[200:203], v151 offset:33792
	ds_read_b128 v[204:207], v150 offset:32768
	ds_read_b128 v[208:211], v150 offset:33792
	s_waitcnt lgkmcnt(8)
	s_waitcnt vmcnt(10)
	s_barrier
	s_waitcnt lgkmcnt(0)
	s_setprio 1
	s_waitcnt lgkmcnt(0)
	v_mfma_f32_16x16x32_bf16 v[124:127], v[164:167], v[180:183], v[124:127]
	v_mfma_f32_16x16x32_bf16 v[120:123], v[172:175], v[180:183], v[120:123]
	v_mfma_f32_16x16x32_bf16 v[116:119], v[164:167], v[188:191], v[116:119]
	v_mfma_f32_16x16x32_bf16 v[112:115], v[172:175], v[188:191], v[112:115]
	v_mfma_f32_16x16x32_bf16 v[108:111], v[164:167], v[196:199], v[108:111]
	v_mfma_f32_16x16x32_bf16 v[104:107], v[172:175], v[196:199], v[104:107]
	v_mfma_f32_16x16x32_bf16 v[100:103], v[164:167], v[204:207], v[100:103]
	v_mfma_f32_16x16x32_bf16 v[96:99], v[172:175], v[204:207], v[96:99]
	v_mfma_f32_16x16x32_bf16 v[124:127], v[168:171], v[184:187], v[124:127]
	v_mfma_f32_16x16x32_bf16 v[120:123], v[176:179], v[184:187], v[120:123]
	v_mfma_f32_16x16x32_bf16 v[116:119], v[168:171], v[192:195], v[116:119]
	v_mfma_f32_16x16x32_bf16 v[112:115], v[176:179], v[192:195], v[112:115]
	v_mfma_f32_16x16x32_bf16 v[108:111], v[168:171], v[200:203], v[108:111]
	v_mfma_f32_16x16x32_bf16 v[104:107], v[176:179], v[200:203], v[104:107]
	v_mfma_f32_16x16x32_bf16 v[100:103], v[168:171], v[208:211], v[100:103]
	v_mfma_f32_16x16x32_bf16 v[96:99], v[176:179], v[208:211], v[96:99]
	s_setprio 0
	s_barrier
	v_readfirstlane_b32 s36, v142
	v_lshl_add_u64 v[232:233], v[230:231], 0, s[30:31]
	s_mov_b32 m0, s36
	v_readfirstlane_b32 s36, v141
	ds_read_b128 v[212:215], v154
	ds_read_b128 v[216:219], v154 offset:1024
	ds_read_b128 v[220:223], v154 offset:2048
	ds_read_b128 v[224:227], v154 offset:3072
	global_load_lds_dwordx4 v[232:233], off
	v_lshl_add_u64 v[232:233], v[230:231], 0, s[34:35]
	s_mov_b32 m0, s36
	s_nop 0
	global_load_lds_dwordx4 v[232:233], off
	s_waitcnt vmcnt(10)
	s_barrier
	s_waitcnt lgkmcnt(0)
	s_setprio 1
	s_waitcnt lgkmcnt(0)
	v_mfma_f32_16x16x32_bf16 v[92:95], v[212:215], v[180:183], v[92:95]
	v_mfma_f32_16x16x32_bf16 v[88:91], v[220:223], v[180:183], v[88:91]
	v_mfma_f32_16x16x32_bf16 v[84:87], v[212:215], v[188:191], v[84:87]
	v_mfma_f32_16x16x32_bf16 v[80:83], v[220:223], v[188:191], v[80:83]
	v_mfma_f32_16x16x32_bf16 v[76:79], v[212:215], v[196:199], v[76:79]
	v_mfma_f32_16x16x32_bf16 v[72:75], v[220:223], v[196:199], v[72:75]
	v_mfma_f32_16x16x32_bf16 v[68:71], v[212:215], v[204:207], v[68:71]
	v_mfma_f32_16x16x32_bf16 v[64:67], v[220:223], v[204:207], v[64:67]
	v_mfma_f32_16x16x32_bf16 v[92:95], v[216:219], v[184:187], v[92:95]
	v_mfma_f32_16x16x32_bf16 v[88:91], v[224:227], v[184:187], v[88:91]
	v_mfma_f32_16x16x32_bf16 v[84:87], v[216:219], v[192:195], v[84:87]
	v_mfma_f32_16x16x32_bf16 v[80:83], v[224:227], v[192:195], v[80:83]
	v_mfma_f32_16x16x32_bf16 v[76:79], v[216:219], v[200:203], v[76:79]
	v_mfma_f32_16x16x32_bf16 v[72:75], v[224:227], v[200:203], v[72:75]
	v_mfma_f32_16x16x32_bf16 v[68:71], v[216:219], v[208:211], v[68:71]
	v_mfma_f32_16x16x32_bf16 v[64:67], v[224:227], v[208:211], v[64:67]
	s_setprio 0
	v_readfirstlane_b32 s36, v140
	v_lshl_add_u64 v[232:233], v[228:229], 0, s[44:45]
	s_mov_b32 m0, s36
	v_readfirstlane_b32 s36, v139
	s_barrier
	ds_read_b128 v[180:183], v153 offset:49152
	ds_read_b128 v[184:187], v153 offset:50176
	ds_read_b128 v[188:191], v152 offset:49152
	ds_read_b128 v[192:195], v152 offset:50176
	ds_read_b128 v[196:199], v151 offset:49152
	ds_read_b128 v[200:203], v151 offset:50176
	ds_read_b128 v[204:207], v150 offset:49152
	ds_read_b128 v[208:211], v150 offset:50176
	global_load_lds_dwordx4 v[232:233], off
	v_lshl_add_u64 v[228:229], v[228:229], 0, s[46:47]
	s_mov_b32 m0, s36
	s_nop 0
	global_load_lds_dwordx4 v[228:229], off
	s_barrier
	s_waitcnt lgkmcnt(0)
	s_setprio 1
	s_waitcnt lgkmcnt(0)
	v_mfma_f32_16x16x32_bf16 v[60:63], v[164:167], v[180:183], v[60:63]
	v_mfma_f32_16x16x32_bf16 v[56:59], v[172:175], v[180:183], v[56:59]
	v_mfma_f32_16x16x32_bf16 v[52:55], v[164:167], v[188:191], v[52:55]
	v_mfma_f32_16x16x32_bf16 v[48:51], v[172:175], v[188:191], v[48:51]
	v_mfma_f32_16x16x32_bf16 v[44:47], v[164:167], v[196:199], v[44:47]
	v_mfma_f32_16x16x32_bf16 v[40:43], v[172:175], v[196:199], v[40:43]
	v_mfma_f32_16x16x32_bf16 v[36:39], v[164:167], v[204:207], v[36:39]
	v_mfma_f32_16x16x32_bf16 v[32:35], v[172:175], v[204:207], v[32:35]
	v_mfma_f32_16x16x32_bf16 v[60:63], v[168:171], v[184:187], v[60:63]
	v_mfma_f32_16x16x32_bf16 v[56:59], v[176:179], v[184:187], v[56:59]
	v_mfma_f32_16x16x32_bf16 v[52:55], v[168:171], v[192:195], v[52:55]
	v_mfma_f32_16x16x32_bf16 v[48:51], v[176:179], v[192:195], v[48:51]
	v_mfma_f32_16x16x32_bf16 v[44:47], v[168:171], v[200:203], v[44:47]
	v_mfma_f32_16x16x32_bf16 v[40:43], v[176:179], v[200:203], v[40:43]
	v_mfma_f32_16x16x32_bf16 v[36:39], v[168:171], v[208:211], v[36:39]
	v_mfma_f32_16x16x32_bf16 v[32:35], v[176:179], v[208:211], v[32:35]
	s_setprio 0
	s_barrier
	v_readfirstlane_b32 s36, v138
	v_lshl_add_u64 v[164:165], v[230:231], 0, s[56:57]
	s_mov_b32 m0, s36
	v_readfirstlane_b32 s36, v137
	global_load_lds_dwordx4 v[164:165], off
	v_lshl_add_u64 v[164:165], v[230:231], 0, s[58:59]
	s_mov_b32 m0, s36
	s_nop 0
	global_load_lds_dwordx4 v[164:165], off
	v_lshl_add_u64 v[132:133], v[132:133], 0, s[60:61]
	v_lshl_add_u64 v[228:229], s[50:51], 0, v[132:133]
	s_mov_b64 s[68:69], 0xe080080
	v_readfirstlane_b32 s36, v161
	v_lshl_add_u64 v[166:167], v[228:229], 0, s[68:69]
	s_mov_b32 m0, s36
	s_mov_b64 s[68:69], 0xe0c0080
	v_readfirstlane_b32 s36, v160
	global_load_lds_dwordx4 v[166:167], off
	v_lshl_add_u64 v[166:167], v[228:229], 0, s[68:69]
	s_mov_b32 m0, s36
	s_nop 0
	global_load_lds_dwordx4 v[166:167], off
	s_waitcnt vmcnt(12)
	s_barrier
	s_setprio 1
	v_mfma_f32_16x16x32_bf16 v[28:31], v[212:215], v[180:183], v[28:31]
	v_mfma_f32_16x16x32_bf16 v[24:27], v[220:223], v[180:183], v[24:27]
	v_mfma_f32_16x16x32_bf16 v[20:23], v[212:215], v[188:191], v[20:23]
	v_mfma_f32_16x16x32_bf16 v[16:19], v[220:223], v[188:191], v[16:19]
	v_mfma_f32_16x16x32_bf16 v[12:15], v[212:215], v[196:199], v[12:15]
	v_mfma_f32_16x16x32_bf16 v[8:11], v[220:223], v[196:199], v[8:11]
	v_mfma_f32_16x16x32_bf16 v[4:7], v[212:215], v[204:207], v[4:7]
	v_mfma_f32_16x16x32_bf16 v[0:3], v[220:223], v[204:207], v[0:3]
	v_mfma_f32_16x16x32_bf16 v[28:31], v[216:219], v[184:187], v[28:31]
	v_mfma_f32_16x16x32_bf16 v[24:27], v[224:227], v[184:187], v[24:27]
	v_mfma_f32_16x16x32_bf16 v[20:23], v[216:219], v[192:195], v[20:23]
	v_mfma_f32_16x16x32_bf16 v[16:19], v[224:227], v[192:195], v[16:19]
	v_mfma_f32_16x16x32_bf16 v[12:15], v[216:219], v[200:203], v[12:15]
	v_mfma_f32_16x16x32_bf16 v[8:11], v[224:227], v[200:203], v[8:11]
	v_mfma_f32_16x16x32_bf16 v[4:7], v[216:219], v[208:211], v[4:7]
	v_mfma_f32_16x16x32_bf16 v[0:3], v[224:227], v[208:211], v[0:3]
	s_setprio 0
	s_add_i32 s24, s24, 2
	v_lshl_add_u64 v[130:131], v[130:131], 0, s[10:11]
	s_cmp_lt_u32 s24, 28
	s_barrier
	s_cbranch_scc1 .LBB0_465
	s_lshl_b32 s24, s86, 5
	s_lshl_b32 s36, s86, 8
	s_and_b32 s24, s24, 0x1800
	s_and_b32 s36, s36, 0x700
	s_or_b32 s24, s36, s24
	v_lshlrev_b32_e32 v128, 3, v156
	v_lshlrev_b32_e32 v130, 5, v156
	v_and_b32_e32 v128, 0xffff0, v128
	v_and_b32_e32 v130, 32, v130
	s_lshl_b32 s36, s24, 12
	v_add_u32_e32 v130, v130, v158
	v_add_lshl_u32 v128, v157, v128, 12
	s_add_u32 s68, s70, s36
	v_lshl_add_u32 v128, v130, 1, v128
	s_addc_u32 s69, s71, 0
	v_lshl_add_u64 v[156:157], s[68:69], 0, v[128:129]
	v_readfirstlane_b32 s36, v161
	ds_read_b128 v[130:133], v162
	ds_read_b128 v[164:167], v162 offset:1024
	ds_read_b128 v[168:171], v162 offset:2048
	ds_read_b128 v[172:175], v162 offset:3072
	ds_read_b128 v[176:179], v153
	ds_read_b128 v[180:183], v153 offset:1024
	ds_read_b128 v[184:187], v152
	ds_read_b128 v[188:191], v152 offset:1024
	ds_read_b128 v[192:195], v151
	ds_read_b128 v[196:199], v151 offset:1024
	ds_read_b128 v[200:203], v150
	ds_read_b128 v[204:207], v150 offset:1024
	v_lshl_add_u64 v[162:163], v[156:157], 0, s[62:63]
	s_mov_b32 m0, s36
	v_readfirstlane_b32 s36, v160
	global_load_lds_dwordx4 v[162:163], off
	v_lshl_add_u64 v[156:157], v[156:157], 0, s[64:65]
	s_mov_b32 m0, s36
	s_nop 0
	global_load_lds_dwordx4 v[156:157], off
	s_waitcnt vmcnt(10)
	s_barrier
	s_waitcnt lgkmcnt(0)
	s_setprio 1
	s_waitcnt lgkmcnt(0)
	v_mfma_f32_16x16x32_bf16 v[124:127], v[130:133], v[176:179], v[124:127]
	v_mfma_f32_16x16x32_bf16 v[120:123], v[168:171], v[176:179], v[120:123]
	v_mfma_f32_16x16x32_bf16 v[116:119], v[130:133], v[184:187], v[116:119]
	v_mfma_f32_16x16x32_bf16 v[112:115], v[168:171], v[184:187], v[112:115]
	v_mfma_f32_16x16x32_bf16 v[108:111], v[130:133], v[192:195], v[108:111]
	v_mfma_f32_16x16x32_bf16 v[104:107], v[168:171], v[192:195], v[104:107]
	v_mfma_f32_16x16x32_bf16 v[100:103], v[130:133], v[200:203], v[100:103]
	v_mfma_f32_16x16x32_bf16 v[96:99], v[168:171], v[200:203], v[96:99]
	v_mfma_f32_16x16x32_bf16 v[124:127], v[164:167], v[180:183], v[124:127]
	v_mfma_f32_16x16x32_bf16 v[120:123], v[172:175], v[180:183], v[120:123]
	v_mfma_f32_16x16x32_bf16 v[116:119], v[164:167], v[188:191], v[116:119]
	v_mfma_f32_16x16x32_bf16 v[112:115], v[172:175], v[188:191], v[112:115]
	v_mfma_f32_16x16x32_bf16 v[108:111], v[164:167], v[196:199], v[108:111]
	v_mfma_f32_16x16x32_bf16 v[104:107], v[172:175], v[196:199], v[104:107]
	v_mfma_f32_16x16x32_bf16 v[100:103], v[164:167], v[204:207], v[100:103]
	v_mfma_f32_16x16x32_bf16 v[96:99], v[172:175], v[204:207], v[96:99]
	s_setprio 0
	s_barrier
	ds_read_b128 v[160:163], v159
	ds_read_b128 v[208:211], v159 offset:1024
	ds_read_b128 v[212:215], v159 offset:2048
	ds_read_b128 v[156:159], v159 offset:3072
	s_barrier
	s_waitcnt lgkmcnt(0)
	s_setprio 1
	s_waitcnt lgkmcnt(0)
	v_mfma_f32_16x16x32_bf16 v[92:95], v[160:163], v[176:179], v[92:95]
	v_mfma_f32_16x16x32_bf16 v[88:91], v[212:215], v[176:179], v[88:91]
	v_mfma_f32_16x16x32_bf16 v[84:87], v[160:163], v[184:187], v[84:87]
	v_mfma_f32_16x16x32_bf16 v[80:83], v[212:215], v[184:187], v[80:83]
	v_mfma_f32_16x16x32_bf16 v[76:79], v[160:163], v[192:195], v[76:79]
	v_mfma_f32_16x16x32_bf16 v[72:75], v[212:215], v[192:195], v[72:75]
	v_mfma_f32_16x16x32_bf16 v[68:71], v[160:163], v[200:203], v[68:71]
	v_mfma_f32_16x16x32_bf16 v[64:67], v[212:215], v[200:203], v[64:67]
	v_mfma_f32_16x16x32_bf16 v[176:179], v[208:211], v[180:183], v[92:95]
	v_mfma_f32_16x16x32_bf16 v[180:183], v[156:159], v[180:183], v[88:91]
	v_mfma_f32_16x16x32_bf16 v[184:187], v[208:211], v[188:191], v[84:87]
	v_mfma_f32_16x16x32_bf16 v[188:191], v[156:159], v[188:191], v[80:83]
	v_mfma_f32_16x16x32_bf16 v[192:195], v[208:211], v[196:199], v[76:79]
	v_mfma_f32_16x16x32_bf16 v[196:199], v[156:159], v[196:199], v[72:75]
	v_mfma_f32_16x16x32_bf16 v[200:203], v[208:211], v[204:207], v[68:71]
	v_mfma_f32_16x16x32_bf16 v[204:207], v[156:159], v[204:207], v[64:67]
	s_setprio 0
	s_barrier
	s_nop 0
	ds_read_b128 v[64:67], v153 offset:16384
	ds_read_b128 v[68:71], v153 offset:17408
	ds_read_b128 v[72:75], v152 offset:16384
	ds_read_b128 v[76:79], v152 offset:17408
	ds_read_b128 v[80:83], v151 offset:16384
	ds_read_b128 v[84:87], v151 offset:17408
	ds_read_b128 v[88:91], v150 offset:16384
	ds_read_b128 v[92:95], v150 offset:17408
	s_waitcnt vmcnt(4)
	s_barrier
	s_waitcnt lgkmcnt(0)
	s_setprio 1
	s_waitcnt lgkmcnt(0)
	v_mfma_f32_16x16x32_bf16 v[60:63], v[130:133], v[64:67], v[60:63]
	v_mfma_f32_16x16x32_bf16 v[56:59], v[168:171], v[64:67], v[56:59]
	v_mfma_f32_16x16x32_bf16 v[52:55], v[130:133], v[72:75], v[52:55]
	v_mfma_f32_16x16x32_bf16 v[48:51], v[168:171], v[72:75], v[48:51]
	v_mfma_f32_16x16x32_bf16 v[216:219], v[130:133], v[80:83], v[44:47]
	v_mfma_f32_16x16x32_bf16 v[220:223], v[168:171], v[80:83], v[40:43]
	v_mfma_f32_16x16x32_bf16 v[130:133], v[130:133], v[88:91], v[36:39]
	v_mfma_f32_16x16x32_bf16 v[168:171], v[168:171], v[88:91], v[32:35]
	v_mfma_f32_16x16x32_bf16 v[32:35], v[164:167], v[68:71], v[60:63]
	v_mfma_f32_16x16x32_bf16 v[36:39], v[172:175], v[68:71], v[56:59]
	v_mfma_f32_16x16x32_bf16 v[40:43], v[164:167], v[76:79], v[52:55]
	v_mfma_f32_16x16x32_bf16 v[44:47], v[172:175], v[76:79], v[48:51]
	v_mfma_f32_16x16x32_bf16 v[48:51], v[164:167], v[84:87], v[216:219]
	v_mfma_f32_16x16x32_bf16 v[52:55], v[172:175], v[84:87], v[220:223]
	v_mfma_f32_16x16x32_bf16 v[56:59], v[164:167], v[92:95], v[130:133]
	v_mfma_f32_16x16x32_bf16 v[60:63], v[172:175], v[92:95], v[168:171]
	s_setprio 0
	s_setprio 1
	v_mfma_f32_16x16x32_bf16 v[28:31], v[160:163], v[64:67], v[28:31]
	v_mfma_f32_16x16x32_bf16 v[24:27], v[212:215], v[64:67], v[24:27]
	v_mfma_f32_16x16x32_bf16 v[20:23], v[160:163], v[72:75], v[20:23]
	v_mfma_f32_16x16x32_bf16 v[64:67], v[212:215], v[72:75], v[16:19]
	v_mfma_f32_16x16x32_bf16 v[72:75], v[160:163], v[80:83], v[12:15]
	v_mfma_f32_16x16x32_bf16 v[8:11], v[212:215], v[80:83], v[8:11]
	v_mfma_f32_16x16x32_bf16 v[80:83], v[160:163], v[88:91], v[4:7]
	v_mfma_f32_16x16x32_bf16 v[0:3], v[212:215], v[88:91], v[0:3]
	v_mfma_f32_16x16x32_bf16 v[4:7], v[208:211], v[68:71], v[28:31]
	v_mfma_f32_16x16x32_bf16 v[12:15], v[156:159], v[68:71], v[24:27]
	v_mfma_f32_16x16x32_bf16 v[16:19], v[208:211], v[76:79], v[20:23]
	v_mfma_f32_16x16x32_bf16 v[20:23], v[156:159], v[76:79], v[64:67]
	v_mfma_f32_16x16x32_bf16 v[24:27], v[208:211], v[84:87], v[72:75]
	v_mfma_f32_16x16x32_bf16 v[28:31], v[156:159], v[84:87], v[8:11]
	v_mfma_f32_16x16x32_bf16 v[64:67], v[208:211], v[92:95], v[80:83]
	v_mfma_f32_16x16x32_bf16 v[68:71], v[156:159], v[92:95], v[0:3]
	s_setprio 0
	s_barrier
	ds_read_b128 v[8:11], v155
	ds_read_b128 v[0:3], v155 offset:1024
	ds_read_b128 v[76:79], v155 offset:2048
	ds_read_b128 v[72:75], v155 offset:3072
	ds_read_b128 v[130:133], v153 offset:32768
	ds_read_b128 v[156:159], v153 offset:33792
	ds_read_b128 v[160:163], v152 offset:32768
	ds_read_b128 v[164:167], v152 offset:33792
	ds_read_b128 v[168:171], v151 offset:32768
	ds_read_b128 v[172:175], v151 offset:33792
	ds_read_b128 v[208:211], v150 offset:32768
	ds_read_b128 v[212:215], v150 offset:33792
	s_waitcnt vmcnt(2)
	s_barrier
	s_waitcnt lgkmcnt(0)
	s_setprio 1
	s_waitcnt lgkmcnt(0)
	v_mfma_f32_16x16x32_bf16 v[80:83], v[8:11], v[130:133], v[124:127]
	v_mfma_f32_16x16x32_bf16 v[84:87], v[76:79], v[130:133], v[120:123]
	v_mfma_f32_16x16x32_bf16 v[88:91], v[8:11], v[160:163], v[116:119]
	v_mfma_f32_16x16x32_bf16 v[92:95], v[76:79], v[160:163], v[112:115]
	v_mfma_f32_16x16x32_bf16 v[108:111], v[8:11], v[168:171], v[108:111]
	v_mfma_f32_16x16x32_bf16 v[104:107], v[76:79], v[168:171], v[104:107]
	v_mfma_f32_16x16x32_bf16 v[100:103], v[8:11], v[208:211], v[100:103]
	v_mfma_f32_16x16x32_bf16 v[96:99], v[76:79], v[208:211], v[96:99]
	v_mfma_f32_16x16x32_bf16 v[112:115], v[0:3], v[156:159], v[80:83]
	v_mfma_f32_16x16x32_bf16 v[116:119], v[72:75], v[156:159], v[84:87]
	v_mfma_f32_16x16x32_bf16 v[120:123], v[0:3], v[164:167], v[88:91]
	v_mfma_f32_16x16x32_bf16 v[124:127], v[72:75], v[164:167], v[92:95]
	v_mfma_f32_16x16x32_bf16 v[108:111], v[0:3], v[172:175], v[108:111]
	v_mfma_f32_16x16x32_bf16 v[104:107], v[72:75], v[172:175], v[104:107]
	v_mfma_f32_16x16x32_bf16 v[100:103], v[0:3], v[212:215], v[100:103]
	v_mfma_f32_16x16x32_bf16 v[96:99], v[72:75], v[212:215], v[96:99]
	s_setprio 0
	s_barrier
	ds_read_b128 v[88:91], v154
	ds_read_b128 v[80:83], v154 offset:1024
	ds_read_b128 v[92:95], v154 offset:2048
	ds_read_b128 v[84:87], v154 offset:3072
	s_waitcnt vmcnt(0)
	s_barrier
	s_waitcnt lgkmcnt(0)
	s_setprio 1
	s_waitcnt lgkmcnt(0)
	v_mfma_f32_16x16x32_bf16 v[176:179], v[88:91], v[130:133], v[176:179]
	v_mfma_f32_16x16x32_bf16 v[130:133], v[92:95], v[130:133], v[180:183]
	v_mfma_f32_16x16x32_bf16 v[180:183], v[88:91], v[160:163], v[184:187]
	v_mfma_f32_16x16x32_bf16 v[160:163], v[92:95], v[160:163], v[188:191]
	v_mfma_f32_16x16x32_bf16 v[184:187], v[88:91], v[168:171], v[192:195]
	v_mfma_f32_16x16x32_bf16 v[168:171], v[92:95], v[168:171], v[196:199]
	v_mfma_f32_16x16x32_bf16 v[188:191], v[88:91], v[208:211], v[200:203]
	v_mfma_f32_16x16x32_bf16 v[192:195], v[92:95], v[208:211], v[204:207]
	v_mfma_f32_16x16x32_bf16 v[176:179], v[80:83], v[156:159], v[176:179]
	v_mfma_f32_16x16x32_bf16 v[130:133], v[84:87], v[156:159], v[130:133]
	v_mfma_f32_16x16x32_bf16 v[154:157], v[80:83], v[164:167], v[180:183]
	v_mfma_f32_16x16x32_bf16 v[158:161], v[84:87], v[164:167], v[160:163]
	v_mfma_f32_16x16x32_bf16 v[162:165], v[80:83], v[172:175], v[184:187]
	v_mfma_f32_16x16x32_bf16 v[166:169], v[84:87], v[172:175], v[168:171]
	v_mfma_f32_16x16x32_bf16 v[170:173], v[80:83], v[212:215], v[188:191]
	v_mfma_f32_16x16x32_bf16 v[180:183], v[84:87], v[212:215], v[192:195]
	s_setprio 0
	s_barrier
	v_mbcnt_lo_u32_b32 v128, -1, 0
	v_mbcnt_hi_u32_b32 v128, -1, v128
	v_cvt_pk_bf16_f32 v112, v112, v113
	v_cvt_pk_bf16_f32 v113, v114, v115
	v_cvt_pk_bf16_f32 v114, v116, v117
	v_cvt_pk_bf16_f32 v115, v118, v119
	s_lshl_b32 s68, s66, 9
	v_add_u32_e32 v174, s74, v128
	v_ashrrev_i32_e32 v175, 6, v174
	v_and_b32_e32 v184, 15, v128
	v_and_b32_e32 v185, 48, v128
	v_mul_lo_u32 v186, v175, s79
	v_bfe_u32 v187, v128, 3, 3
	v_lshlrev_b32_e32 v128, 4, v128
	v_add_u32_e32 v186, 0x20000, v186
	v_lshrrev_b32_e32 v174, 2, v174
	v_and_b32_e32 v128, 0x70, v128
	v_mul_u32_u24_e32 v184, 0x90, v184
	v_and_b32_e32 v174, 64, v174
	v_add3_u32 v184, v186, v184, v185
	v_or_b32_e32 v185, v186, v128
	v_or3_b32 v174, s24, v174, v187
	v_mad_u32_u24 v185, v187, s80, v185
	ds_write_b128 v184, v[112:115]
	v_cvt_pk_bf16_f32 v112, v176, v177
	v_cvt_pk_bf16_f32 v113, v178, v179
	v_cvt_pk_bf16_f32 v114, v130, v131
	v_cvt_pk_bf16_f32 v115, v132, v133
	ds_write_b128 v184, v[112:115] offset:64
	v_lshlrev_b32_e32 v175, 7, v175
	ds_read_b128 v[112:115], v185
	v_lshlrev_b32_e32 v116, 12, v174
	v_and_or_b32 v116, v175, s81, v116
	v_or3_b32 v128, v116, s68, v128
	ds_read_b128 v[116:119], v185 offset:1152
	v_lshl_add_u64 v[130:131], s[0:1], 0, v[128:129]
	s_mov_b32 s36, 0x8000
	s_waitcnt lgkmcnt(0)
	global_store_dwordx4 v128, v[112:115], s[0:1]
	v_cvt_pk_bf16_f32 v108, v108, v109
	v_cvt_pk_bf16_f32 v109, v110, v111
	v_cvt_pk_bf16_f32 v110, v104, v105
	v_cvt_pk_bf16_f32 v111, v106, v107
	v_cvt_pk_bf16_f32 v104, v162, v163
	s_nop 1
	v_add_co_u32_e32 v112, vcc, s36, v130
	v_cvt_pk_bf16_f32 v114, v124, v125
	v_cvt_pk_bf16_f32 v115, v126, v127
	v_cvt_pk_bf16_f32 v105, v164, v165
	v_cvt_pk_bf16_f32 v106, v166, v167
	s_nop 1
	v_addc_co_u32_e32 v113, vcc, 0, v131, vcc
	global_store_dwordx4 v[112:113], v[116:119], off
	v_cvt_pk_bf16_f32 v112, v120, v121
	v_cvt_pk_bf16_f32 v113, v122, v123
	ds_write_b128 v184, v[112:115]
	v_cvt_pk_bf16_f32 v112, v154, v155
	v_cvt_pk_bf16_f32 v113, v156, v157
	v_cvt_pk_bf16_f32 v114, v158, v159
	v_cvt_pk_bf16_f32 v115, v160, v161
	ds_write_b128 v184, v[112:115] offset:64
	ds_read_b128 v[112:115], v185
	ds_read_b128 v[116:119], v185 offset:1152
	v_add_co_u32_e32 v120, vcc, s76, v130
	ds_write_b128 v184, v[108:111]
	v_cvt_pk_bf16_f32 v107, v168, v169
	ds_write_b128 v184, v[104:107] offset:64
	v_addc_co_u32_e32 v121, vcc, 0, v131, vcc
	ds_read_b128 v[104:107], v185
	ds_read_b128 v[108:111], v185 offset:1152
	s_waitcnt lgkmcnt(0)
	global_store_dwordx4 v[120:121], v[112:115], off
	v_cvt_pk_bf16_f32 v100, v100, v101
	v_cvt_pk_bf16_f32 v101, v102, v103
	v_cvt_pk_bf16_f32 v102, v96, v97
	v_cvt_pk_bf16_f32 v103, v98, v99
	ds_write_b128 v184, v[100:103]
	s_nop 0
	v_add_co_u32_e32 v112, vcc, s77, v130
	v_cvt_pk_bf16_f32 v96, v170, v171
	v_cvt_pk_bf16_f32 v97, v172, v173
	v_cvt_pk_bf16_f32 v98, v180, v181
	v_cvt_pk_bf16_f32 v99, v182, v183
	s_nop 1
	v_addc_co_u32_e32 v113, vcc, 0, v131, vcc
	global_store_dwordx4 v[112:113], v[116:119], off
	v_add_co_u32_e32 v112, vcc, s78, v130
	ds_write_b128 v184, v[96:99] offset:64
	s_nop 0
	v_addc_co_u32_e32 v113, vcc, 0, v131, vcc
	ds_read_b128 v[96:99], v185
	ds_read_b128 v[100:103], v185 offset:1152
	global_store_dwordx4 v[112:113], v[104:107], off
	s_nop 1
	v_add_co_u32_e32 v104, vcc, s82, v130
	s_nop 1
	v_addc_co_u32_e32 v105, vcc, 0, v131, vcc
	global_store_dwordx4 v[104:105], v[108:111], off
	v_add_co_u32_e32 v104, vcc, s83, v130
	s_nop 1
	v_addc_co_u32_e32 v105, vcc, 0, v131, vcc
	s_waitcnt lgkmcnt(0)
	global_store_dwordx4 v[104:105], v[96:99], off
	s_nop 1
	v_add_co_u32_e32 v96, vcc, s91, v130
	s_nop 1
	v_addc_co_u32_e32 v97, vcc, 0, v131, vcc
	global_store_dwordx4 v[96:97], v[100:103], off
	ds_read_b128 v[96:99], v153 offset:49152
	ds_read_b128 v[100:103], v153 offset:50176
	ds_read_b128 v[104:107], v152 offset:49152
	ds_read_b128 v[108:111], v152 offset:50176
	ds_read_b128 v[112:115], v151 offset:49152
	ds_read_b128 v[116:119], v151 offset:50176
	ds_read_b128 v[120:123], v150 offset:49152
	ds_read_b128 v[124:127], v150 offset:50176
	s_barrier
	s_waitcnt lgkmcnt(0)
	s_setprio 1
	s_waitcnt lgkmcnt(0)
	v_mfma_f32_16x16x32_bf16 v[32:35], v[8:11], v[96:99], v[32:35]
	v_mfma_f32_16x16x32_bf16 v[36:39], v[76:79], v[96:99], v[36:39]
	v_mfma_f32_16x16x32_bf16 v[40:43], v[8:11], v[104:107], v[40:43]
	v_mfma_f32_16x16x32_bf16 v[130:133], v[76:79], v[104:107], v[44:47]
	v_mfma_f32_16x16x32_bf16 v[150:153], v[8:11], v[112:115], v[48:51]
	v_mfma_f32_16x16x32_bf16 v[52:55], v[76:79], v[112:115], v[52:55]
	v_mfma_f32_16x16x32_bf16 v[8:11], v[8:11], v[120:123], v[56:59]
	v_mfma_f32_16x16x32_bf16 v[60:63], v[76:79], v[120:123], v[60:63]
	v_mfma_f32_16x16x32_bf16 v[56:59], v[0:3], v[100:103], v[32:35]
	v_mfma_f32_16x16x32_bf16 v[48:51], v[72:75], v[100:103], v[36:39]
	v_mfma_f32_16x16x32_bf16 v[44:47], v[0:3], v[108:111], v[40:43]
	v_mfma_f32_16x16x32_bf16 v[40:43], v[72:75], v[108:111], v[130:133]
	v_mfma_f32_16x16x32_bf16 v[36:39], v[0:3], v[116:119], v[150:153]
	v_mfma_f32_16x16x32_bf16 v[32:35], v[72:75], v[116:119], v[52:55]
	v_mfma_f32_16x16x32_bf16 v[8:11], v[0:3], v[124:127], v[8:11]
	v_mfma_f32_16x16x32_bf16 v[0:3], v[72:75], v[124:127], v[60:63]
	s_setprio 0
	s_setprio 1
	v_mfma_f32_16x16x32_bf16 v[4:7], v[88:91], v[96:99], v[4:7]
	v_mfma_f32_16x16x32_bf16 v[12:15], v[92:95], v[96:99], v[12:15]
	v_mfma_f32_16x16x32_bf16 v[16:19], v[88:91], v[104:107], v[16:19]
	v_mfma_f32_16x16x32_bf16 v[20:23], v[92:95], v[104:107], v[20:23]
	v_mfma_f32_16x16x32_bf16 v[72:75], v[88:91], v[112:115], v[24:27]
	v_mfma_f32_16x16x32_bf16 v[76:79], v[92:95], v[112:115], v[28:31]
	v_mfma_f32_16x16x32_bf16 v[64:67], v[88:91], v[120:123], v[64:67]
	v_mfma_f32_16x16x32_bf16 v[68:71], v[92:95], v[120:123], v[68:71]
	v_mfma_f32_16x16x32_bf16 v[60:63], v[80:83], v[100:103], v[4:7]
	v_mfma_f32_16x16x32_bf16 v[52:55], v[84:87], v[100:103], v[12:15]
	v_mfma_f32_16x16x32_bf16 v[28:31], v[80:83], v[108:111], v[16:19]
	v_mfma_f32_16x16x32_bf16 v[24:27], v[84:87], v[108:111], v[20:23]
	v_mfma_f32_16x16x32_bf16 v[20:23], v[80:83], v[116:119], v[72:75]
	v_mfma_f32_16x16x32_bf16 v[16:19], v[84:87], v[116:119], v[76:79]
	v_mfma_f32_16x16x32_bf16 v[12:15], v[80:83], v[124:127], v[64:67]
	v_mfma_f32_16x16x32_bf16 v[4:7], v[84:87], v[124:127], v[68:71]
	s_setprio 0
	v_cmp_gt_u32_e32 vcc, s92, v136
	s_barrier
	s_and_saveexec_b64 s[66:67], vcc
	s_cbranch_execz .LBB0_468
	s_barrier

.LBB0_521:
	ds_read_b128 v[140:143], v138
	ds_read_b128 v[144:147], v138 offset:1024
	ds_read_b128 v[148:151], v138 offset:2048
	ds_read_b128 v[152:155], v138 offset:3072
	ds_read_b128 v[156:159], v193
	ds_read_b128 v[160:163], v193 offset:1024
	ds_read_b128 v[194:197], v192
	ds_read_b128 v[198:201], v192 offset:1024
	ds_read_b128 v[202:205], v191
	ds_read_b128 v[206:209], v191 offset:1024
	ds_read_b128 v[210:213], v190
	ds_read_b128 v[214:217], v190 offset:1024
	s_waitcnt lgkmcnt(8)
	s_waitcnt vmcnt(10)
	s_barrier
	s_waitcnt lgkmcnt(0)
	s_setprio 1
	s_waitcnt lgkmcnt(0)
	v_mfma_f32_16x16x32_bf16 v[124:127], v[140:143], v[156:159], v[124:127]
	v_mfma_f32_16x16x32_bf16 v[120:123], v[148:151], v[156:159], v[120:123]
	v_mfma_f32_16x16x32_bf16 v[116:119], v[140:143], v[194:197], v[116:119]
	v_mfma_f32_16x16x32_bf16 v[112:115], v[148:151], v[194:197], v[112:115]
	v_mfma_f32_16x16x32_bf16 v[108:111], v[140:143], v[202:205], v[108:111]
	v_mfma_f32_16x16x32_bf16 v[104:107], v[148:151], v[202:205], v[104:107]
	v_mfma_f32_16x16x32_bf16 v[100:103], v[140:143], v[210:213], v[100:103]
	v_mfma_f32_16x16x32_bf16 v[96:99], v[148:151], v[210:213], v[96:99]
	v_mfma_f32_16x16x32_bf16 v[124:127], v[144:147], v[160:163], v[124:127]
	v_mfma_f32_16x16x32_bf16 v[120:123], v[152:155], v[160:163], v[120:123]
	v_mfma_f32_16x16x32_bf16 v[116:119], v[144:147], v[198:201], v[116:119]
	v_mfma_f32_16x16x32_bf16 v[112:115], v[152:155], v[198:201], v[112:115]
	v_mfma_f32_16x16x32_bf16 v[108:111], v[144:147], v[206:209], v[108:111]
	v_mfma_f32_16x16x32_bf16 v[104:107], v[152:155], v[206:209], v[104:107]
	v_mfma_f32_16x16x32_bf16 v[100:103], v[144:147], v[214:217], v[100:103]
	v_mfma_f32_16x16x32_bf16 v[96:99], v[152:155], v[214:217], v[96:99]
	s_setprio 0
	s_barrier
	v_readfirstlane_b32 s36, v189
	v_lshl_add_u64 v[234:235], s[58:59], 0, v[164:165]
	s_mov_b32 m0, s36
	v_readfirstlane_b32 s36, v188
	ds_read_b128 v[218:221], v135
	ds_read_b128 v[222:225], v135 offset:1024
	ds_read_b128 v[226:229], v135 offset:2048
	ds_read_b128 v[230:233], v135 offset:3072
	global_load_lds_dwordx4 v[234:235], off
	v_lshl_add_u64 v[236:237], v[234:235], 0, s[2:3]
	s_mov_b32 m0, s36
	s_nop 0
	global_load_lds_dwordx4 v[236:237], off
	s_waitcnt vmcnt(10)
	s_barrier
	s_waitcnt lgkmcnt(0)
	s_setprio 1
	s_waitcnt lgkmcnt(0)
	v_mfma_f32_16x16x32_bf16 v[92:95], v[218:221], v[156:159], v[92:95]
	v_mfma_f32_16x16x32_bf16 v[88:91], v[226:229], v[156:159], v[88:91]
	v_mfma_f32_16x16x32_bf16 v[84:87], v[218:221], v[194:197], v[84:87]
	v_mfma_f32_16x16x32_bf16 v[80:83], v[226:229], v[194:197], v[80:83]
	v_mfma_f32_16x16x32_bf16 v[76:79], v[218:221], v[202:205], v[76:79]
	v_mfma_f32_16x16x32_bf16 v[72:75], v[226:229], v[202:205], v[72:75]
	v_mfma_f32_16x16x32_bf16 v[68:71], v[218:221], v[210:213], v[68:71]
	v_mfma_f32_16x16x32_bf16 v[64:67], v[226:229], v[210:213], v[64:67]
	v_mfma_f32_16x16x32_bf16 v[92:95], v[222:225], v[160:163], v[92:95]
	v_mfma_f32_16x16x32_bf16 v[88:91], v[230:233], v[160:163], v[88:91]
	v_mfma_f32_16x16x32_bf16 v[84:87], v[222:225], v[198:201], v[84:87]
	v_mfma_f32_16x16x32_bf16 v[80:83], v[230:233], v[198:201], v[80:83]
	v_mfma_f32_16x16x32_bf16 v[76:79], v[222:225], v[206:209], v[76:79]
	v_mfma_f32_16x16x32_bf16 v[72:75], v[230:233], v[206:209], v[72:75]
	v_mfma_f32_16x16x32_bf16 v[68:71], v[222:225], v[214:217], v[68:71]
	v_mfma_f32_16x16x32_bf16 v[64:67], v[230:233], v[214:217], v[64:67]
	s_setprio 0
	v_readfirstlane_b32 s36, v169
	v_lshl_add_u64 v[236:237], v[128:129], 0, s[22:23]
	s_mov_b32 m0, s36
	v_readfirstlane_b32 s36, v187
	s_barrier
	ds_read_b128 v[156:159], v193 offset:16384
	ds_read_b128 v[160:163], v193 offset:17408
	ds_read_b128 v[194:197], v192 offset:16384
	ds_read_b128 v[198:201], v192 offset:17408
	ds_read_b128 v[202:205], v191 offset:16384
	ds_read_b128 v[206:209], v191 offset:17408
	ds_read_b128 v[210:213], v190 offset:16384
	ds_read_b128 v[214:217], v190 offset:17408
	global_load_lds_dwordx4 v[236:237], off
	v_lshl_add_u64 v[236:237], v[128:129], 0, s[24:25]
	s_mov_b32 m0, s36
	s_nop 0
	global_load_lds_dwordx4 v[236:237], off
	s_barrier
	s_waitcnt lgkmcnt(0)
	s_setprio 1
	s_waitcnt lgkmcnt(0)
	v_mfma_f32_16x16x32_bf16 v[60:63], v[140:143], v[156:159], v[60:63]
	v_mfma_f32_16x16x32_bf16 v[56:59], v[148:151], v[156:159], v[56:59]
	v_mfma_f32_16x16x32_bf16 v[52:55], v[140:143], v[194:197], v[52:55]
	v_mfma_f32_16x16x32_bf16 v[48:51], v[148:151], v[194:197], v[48:51]
	v_mfma_f32_16x16x32_bf16 v[44:47], v[140:143], v[202:205], v[44:47]
	v_mfma_f32_16x16x32_bf16 v[40:43], v[148:151], v[202:205], v[40:43]
	v_mfma_f32_16x16x32_bf16 v[36:39], v[140:143], v[210:213], v[36:39]
	v_mfma_f32_16x16x32_bf16 v[32:35], v[148:151], v[210:213], v[32:35]
	v_mfma_f32_16x16x32_bf16 v[60:63], v[144:147], v[160:163], v[60:63]
	v_mfma_f32_16x16x32_bf16 v[56:59], v[152:155], v[160:163], v[56:59]
	v_mfma_f32_16x16x32_bf16 v[52:55], v[144:147], v[198:201], v[52:55]
	v_mfma_f32_16x16x32_bf16 v[48:51], v[152:155], v[198:201], v[48:51]
	v_mfma_f32_16x16x32_bf16 v[44:47], v[144:147], v[206:209], v[44:47]
	v_mfma_f32_16x16x32_bf16 v[40:43], v[152:155], v[206:209], v[40:43]
	v_mfma_f32_16x16x32_bf16 v[36:39], v[144:147], v[214:217], v[36:39]
	v_mfma_f32_16x16x32_bf16 v[32:35], v[152:155], v[214:217], v[32:35]
	s_setprio 0
	s_barrier
	v_readfirstlane_b32 s36, v186
	v_lshl_add_u64 v[140:141], v[234:235], 0, s[6:7]
	s_mov_b32 m0, s36
	v_readfirstlane_b32 s36, v185
	global_load_lds_dwordx4 v[140:141], off
	v_lshl_add_u64 v[140:141], v[234:235], 0, s[8:9]
	s_mov_b32 m0, s36
	s_nop 0
	global_load_lds_dwordx4 v[140:141], off
	v_readfirstlane_b32 s36, v184
	v_lshl_add_u64 v[142:143], v[128:129], 0, s[26:27]
	s_mov_b32 m0, s36
	v_readfirstlane_b32 s36, v183
	global_load_lds_dwordx4 v[142:143], off
	s_mov_b32 m0, s36
	s_nop 0
	global_load_lds_dwordx4 v[128:129], off
	s_waitcnt vmcnt(12)
	s_barrier
	s_setprio 1
	v_mfma_f32_16x16x32_bf16 v[28:31], v[218:221], v[156:159], v[28:31]
	v_mfma_f32_16x16x32_bf16 v[24:27], v[226:229], v[156:159], v[24:27]
	v_mfma_f32_16x16x32_bf16 v[20:23], v[218:221], v[194:197], v[20:23]
	v_mfma_f32_16x16x32_bf16 v[16:19], v[226:229], v[194:197], v[16:19]
	v_mfma_f32_16x16x32_bf16 v[12:15], v[218:221], v[202:205], v[12:15]
	v_mfma_f32_16x16x32_bf16 v[8:11], v[226:229], v[202:205], v[8:11]
	v_mfma_f32_16x16x32_bf16 v[4:7], v[218:221], v[210:213], v[4:7]
	v_mfma_f32_16x16x32_bf16 v[0:3], v[226:229], v[210:213], v[0:3]
	v_mfma_f32_16x16x32_bf16 v[28:31], v[222:225], v[160:163], v[28:31]
	v_mfma_f32_16x16x32_bf16 v[24:27], v[230:233], v[160:163], v[24:27]
	v_mfma_f32_16x16x32_bf16 v[20:23], v[222:225], v[198:201], v[20:23]
	v_mfma_f32_16x16x32_bf16 v[16:19], v[230:233], v[198:201], v[16:19]
	v_mfma_f32_16x16x32_bf16 v[12:15], v[222:225], v[206:209], v[12:15]
	v_mfma_f32_16x16x32_bf16 v[8:11], v[230:233], v[206:209], v[8:11]
	v_mfma_f32_16x16x32_bf16 v[4:7], v[222:225], v[214:217], v[4:7]
	v_mfma_f32_16x16x32_bf16 v[0:3], v[230:233], v[214:217], v[0:3]
	s_setprio 0
	s_barrier
	ds_read_b128 v[140:143], v130
	ds_read_b128 v[144:147], v130 offset:1024
	ds_read_b128 v[148:151], v130 offset:2048
	ds_read_b128 v[152:155], v130 offset:3072
	ds_read_b128 v[156:159], v193 offset:32768
	ds_read_b128 v[160:163], v193 offset:33792
	ds_read_b128 v[194:197], v192 offset:32768
	ds_read_b128 v[198:201], v192 offset:33792
	ds_read_b128 v[202:205], v191 offset:32768
	ds_read_b128 v[206:209], v191 offset:33792
	ds_read_b128 v[210:213], v190 offset:32768
	ds_read_b128 v[214:217], v190 offset:33792
	s_waitcnt lgkmcnt(8)
	s_waitcnt vmcnt(10)
	s_barrier
	s_waitcnt lgkmcnt(0)
	s_setprio 1
	s_waitcnt lgkmcnt(0)
	v_mfma_f32_16x16x32_bf16 v[124:127], v[140:143], v[156:159], v[124:127]
	v_mfma_f32_16x16x32_bf16 v[120:123], v[148:151], v[156:159], v[120:123]
	v_mfma_f32_16x16x32_bf16 v[116:119], v[140:143], v[194:197], v[116:119]
	v_mfma_f32_16x16x32_bf16 v[112:115], v[148:151], v[194:197], v[112:115]
	v_mfma_f32_16x16x32_bf16 v[108:111], v[140:143], v[202:205], v[108:111]
	v_mfma_f32_16x16x32_bf16 v[104:107], v[148:151], v[202:205], v[104:107]
	v_mfma_f32_16x16x32_bf16 v[100:103], v[140:143], v[210:213], v[100:103]
	v_mfma_f32_16x16x32_bf16 v[96:99], v[148:151], v[210:213], v[96:99]
	v_mfma_f32_16x16x32_bf16 v[124:127], v[144:147], v[160:163], v[124:127]
	v_mfma_f32_16x16x32_bf16 v[120:123], v[152:155], v[160:163], v[120:123]
	v_mfma_f32_16x16x32_bf16 v[116:119], v[144:147], v[198:201], v[116:119]
	v_mfma_f32_16x16x32_bf16 v[112:115], v[152:155], v[198:201], v[112:115]
	v_mfma_f32_16x16x32_bf16 v[108:111], v[144:147], v[206:209], v[108:111]
	v_mfma_f32_16x16x32_bf16 v[104:107], v[152:155], v[206:209], v[104:107]
	v_mfma_f32_16x16x32_bf16 v[100:103], v[144:147], v[214:217], v[100:103]
	v_mfma_f32_16x16x32_bf16 v[96:99], v[152:155], v[214:217], v[96:99]
	s_setprio 0
	s_barrier
	v_readfirstlane_b32 s36, v182
	v_lshl_add_u64 v[234:235], s[46:47], 0, v[164:165]
	s_mov_b32 m0, s36
	v_readfirstlane_b32 s36, v181
	ds_read_b128 v[218:221], v132
	ds_read_b128 v[222:225], v132 offset:1024
	ds_read_b128 v[226:229], v132 offset:2048
	ds_read_b128 v[230:233], v132 offset:3072
	global_load_lds_dwordx4 v[234:235], off
	v_lshl_add_u64 v[236:237], v[234:235], 0, s[2:3]
	s_mov_b32 m0, s36
	s_nop 0
	global_load_lds_dwordx4 v[236:237], off
	s_waitcnt vmcnt(10)
	s_barrier
	s_waitcnt lgkmcnt(0)
	s_setprio 1
	s_waitcnt lgkmcnt(0)
	v_mfma_f32_16x16x32_bf16 v[92:95], v[218:221], v[156:159], v[92:95]
	v_mfma_f32_16x16x32_bf16 v[88:91], v[226:229], v[156:159], v[88:91]
	v_mfma_f32_16x16x32_bf16 v[84:87], v[218:221], v[194:197], v[84:87]
	v_mfma_f32_16x16x32_bf16 v[80:83], v[226:229], v[194:197], v[80:83]
	v_mfma_f32_16x16x32_bf16 v[76:79], v[218:221], v[202:205], v[76:79]
	v_mfma_f32_16x16x32_bf16 v[72:75], v[226:229], v[202:205], v[72:75]
	v_mfma_f32_16x16x32_bf16 v[68:71], v[218:221], v[210:213], v[68:71]
	v_mfma_f32_16x16x32_bf16 v[64:67], v[226:229], v[210:213], v[64:67]
	v_mfma_f32_16x16x32_bf16 v[92:95], v[222:225], v[160:163], v[92:95]
	v_mfma_f32_16x16x32_bf16 v[88:91], v[230:233], v[160:163], v[88:91]
	v_mfma_f32_16x16x32_bf16 v[84:87], v[222:225], v[198:201], v[84:87]
	v_mfma_f32_16x16x32_bf16 v[80:83], v[230:233], v[198:201], v[80:83]
	v_mfma_f32_16x16x32_bf16 v[76:79], v[222:225], v[206:209], v[76:79]
	v_mfma_f32_16x16x32_bf16 v[72:75], v[230:233], v[206:209], v[72:75]
	v_mfma_f32_16x16x32_bf16 v[68:71], v[222:225], v[214:217], v[68:71]
	v_mfma_f32_16x16x32_bf16 v[64:67], v[230:233], v[214:217], v[64:67]
	s_setprio 0
	v_readfirstlane_b32 s36, v177
	v_lshl_add_u64 v[236:237], v[128:129], 0, s[28:29]
	s_mov_b32 m0, s36
	v_readfirstlane_b32 s36, v175
	s_barrier
	ds_read_b128 v[156:159], v193 offset:49152
	ds_read_b128 v[160:163], v193 offset:50176
	ds_read_b128 v[194:197], v192 offset:49152
	ds_read_b128 v[198:201], v192 offset:50176
	ds_read_b128 v[202:205], v191 offset:49152
	ds_read_b128 v[206:209], v191 offset:50176
	ds_read_b128 v[210:213], v190 offset:49152
	ds_read_b128 v[214:217], v190 offset:50176
	global_load_lds_dwordx4 v[236:237], off
	v_lshl_add_u64 v[236:237], v[128:129], 0, s[30:31]
	s_mov_b32 m0, s36
	s_nop 0
	global_load_lds_dwordx4 v[236:237], off
	s_barrier
	s_waitcnt lgkmcnt(0)
	s_setprio 1
	s_waitcnt lgkmcnt(0)
	v_mfma_f32_16x16x32_bf16 v[60:63], v[140:143], v[156:159], v[60:63]
	v_mfma_f32_16x16x32_bf16 v[56:59], v[148:151], v[156:159], v[56:59]
	v_mfma_f32_16x16x32_bf16 v[52:55], v[140:143], v[194:197], v[52:55]
	v_mfma_f32_16x16x32_bf16 v[48:51], v[148:151], v[194:197], v[48:51]
	v_mfma_f32_16x16x32_bf16 v[44:47], v[140:143], v[202:205], v[44:47]
	v_mfma_f32_16x16x32_bf16 v[40:43], v[148:151], v[202:205], v[40:43]
	v_mfma_f32_16x16x32_bf16 v[36:39], v[140:143], v[210:213], v[36:39]
	v_mfma_f32_16x16x32_bf16 v[32:35], v[148:151], v[210:213], v[32:35]
	v_mfma_f32_16x16x32_bf16 v[60:63], v[144:147], v[160:163], v[60:63]
	v_mfma_f32_16x16x32_bf16 v[56:59], v[152:155], v[160:163], v[56:59]
	v_mfma_f32_16x16x32_bf16 v[52:55], v[144:147], v[198:201], v[52:55]
	v_mfma_f32_16x16x32_bf16 v[48:51], v[152:155], v[198:201], v[48:51]
	v_mfma_f32_16x16x32_bf16 v[44:47], v[144:147], v[206:209], v[44:47]
	v_mfma_f32_16x16x32_bf16 v[40:43], v[152:155], v[206:209], v[40:43]
	v_mfma_f32_16x16x32_bf16 v[36:39], v[144:147], v[214:217], v[36:39]
	v_mfma_f32_16x16x32_bf16 v[32:35], v[152:155], v[214:217], v[32:35]
	s_setprio 0
	s_barrier
	v_readfirstlane_b32 s36, v173
	v_lshl_add_u64 v[140:141], v[234:235], 0, s[6:7]
	s_mov_b32 m0, s36
	v_readfirstlane_b32 s36, v171
	global_load_lds_dwordx4 v[140:141], off
	v_lshl_add_u64 v[140:141], v[234:235], 0, s[8:9]
	s_mov_b32 m0, s36
	s_nop 0
	global_load_lds_dwordx4 v[140:141], off
	v_lshl_add_u64 v[128:129], v[128:129], 0, s[34:35]
	v_readfirstlane_b32 s36, v137
	v_lshl_add_u64 v[142:143], v[128:129], 0, s[18:19]
	s_mov_b32 m0, s36
	v_readfirstlane_b32 s36, v136
	global_load_lds_dwordx4 v[142:143], off
	v_lshl_add_u64 v[142:143], v[128:129], 0, s[20:21]
	s_mov_b32 m0, s36
	s_nop 0
	global_load_lds_dwordx4 v[142:143], off
	s_waitcnt vmcnt(12)
	s_barrier
	s_setprio 1
	v_mfma_f32_16x16x32_bf16 v[28:31], v[218:221], v[156:159], v[28:31]
	v_mfma_f32_16x16x32_bf16 v[24:27], v[226:229], v[156:159], v[24:27]
	v_mfma_f32_16x16x32_bf16 v[20:23], v[218:221], v[194:197], v[20:23]
	v_mfma_f32_16x16x32_bf16 v[16:19], v[226:229], v[194:197], v[16:19]
	v_mfma_f32_16x16x32_bf16 v[12:15], v[218:221], v[202:205], v[12:15]
	v_mfma_f32_16x16x32_bf16 v[8:11], v[226:229], v[202:205], v[8:11]
	v_mfma_f32_16x16x32_bf16 v[4:7], v[218:221], v[210:213], v[4:7]
	v_mfma_f32_16x16x32_bf16 v[0:3], v[226:229], v[210:213], v[0:3]
	v_mfma_f32_16x16x32_bf16 v[28:31], v[222:225], v[160:163], v[28:31]
	v_mfma_f32_16x16x32_bf16 v[24:27], v[230:233], v[160:163], v[24:27]
	v_mfma_f32_16x16x32_bf16 v[20:23], v[222:225], v[198:201], v[20:23]
	v_mfma_f32_16x16x32_bf16 v[16:19], v[230:233], v[198:201], v[16:19]
	v_mfma_f32_16x16x32_bf16 v[12:15], v[222:225], v[206:209], v[12:15]
	v_mfma_f32_16x16x32_bf16 v[8:11], v[230:233], v[206:209], v[8:11]
	v_mfma_f32_16x16x32_bf16 v[4:7], v[222:225], v[214:217], v[4:7]
	v_mfma_f32_16x16x32_bf16 v[0:3], v[230:233], v[214:217], v[0:3]
	s_setprio 0
	s_add_i32 s14, s14, 2
	s_add_u32 s46, s46, s56
	s_addc_u32 s47, s47, s57
	s_add_u32 s58, s58, s56
	s_addc_u32 s59, s59, s57
	s_cmp_lt_u32 s14, 28
	s_barrier
	s_cbranch_scc1 .LBB0_521
	s_lshl_b32 s14, s60, 3
	s_or_b32 s80, s61, s14
	s_lshl_b32 s46, s80, 8
	v_lshlrev_b32_e32 v128, 3, v131
	v_lshlrev_b32_e32 v129, 5, v131
	s_or_b32 s14, s46, 0x80
	v_and_b32_e32 v128, 0x7fff0, v128
	v_and_b32_e32 v129, 32, v129
	s_lshl_b64 s[56:57], s[14:15], 13
	v_add_u32_e32 v129, v129, v134
	v_add_lshl_u32 v128, v133, v128, 13
	s_add_u32 s56, s40, s56
	v_lshl_add_u32 v164, v129, 1, v128
	s_addc_u32 s57, s41, s57
	v_lshl_add_u64 v[128:129], s[56:57], 0, v[164:165]
	v_readfirstlane_b32 s14, v137
	ds_read_b128 v[140:143], v138
	ds_read_b128 v[144:147], v138 offset:1024
	ds_read_b128 v[148:151], v138 offset:2048
	ds_read_b128 v[152:155], v138 offset:3072
	ds_read_b128 v[156:159], v193
	ds_read_b128 v[160:163], v193 offset:1024
	ds_read_b128 v[194:197], v192
	ds_read_b128 v[198:201], v192 offset:1024
	ds_read_b128 v[202:205], v191
	ds_read_b128 v[206:209], v191 offset:1024
	ds_read_b128 v[210:213], v190
	ds_read_b128 v[214:217], v190 offset:1024
	v_lshl_add_u64 v[138:139], v[128:129], 0, s[38:39]
	s_mov_b32 m0, s14
	v_readfirstlane_b32 s14, v136
	global_load_lds_dwordx4 v[138:139], off
	v_lshl_add_u64 v[128:129], v[128:129], 0, s[44:45]
	s_mov_b32 m0, s14
	s_mov_b32 s47, s15
	global_load_lds_dwordx4 v[128:129], off
	s_waitcnt vmcnt(10)
	s_barrier
	s_waitcnt lgkmcnt(0)
	s_setprio 1
	s_waitcnt lgkmcnt(0)
	v_mfma_f32_16x16x32_bf16 v[124:127], v[140:143], v[156:159], v[124:127]
	v_mfma_f32_16x16x32_bf16 v[120:123], v[148:151], v[156:159], v[120:123]
	v_mfma_f32_16x16x32_bf16 v[116:119], v[140:143], v[194:197], v[116:119]
	v_mfma_f32_16x16x32_bf16 v[112:115], v[148:151], v[194:197], v[112:115]
	v_mfma_f32_16x16x32_bf16 v[108:111], v[140:143], v[202:205], v[108:111]
	v_mfma_f32_16x16x32_bf16 v[104:107], v[148:151], v[202:205], v[104:107]
	v_mfma_f32_16x16x32_bf16 v[100:103], v[140:143], v[210:213], v[100:103]
	v_mfma_f32_16x16x32_bf16 v[96:99], v[148:151], v[210:213], v[96:99]
	v_mfma_f32_16x16x32_bf16 v[124:127], v[144:147], v[160:163], v[124:127]
	v_mfma_f32_16x16x32_bf16 v[120:123], v[152:155], v[160:163], v[120:123]
	v_mfma_f32_16x16x32_bf16 v[116:119], v[144:147], v[198:201], v[116:119]
	v_mfma_f32_16x16x32_bf16 v[112:115], v[152:155], v[198:201], v[112:115]
	v_mfma_f32_16x16x32_bf16 v[108:111], v[144:147], v[206:209], v[108:111]
	v_mfma_f32_16x16x32_bf16 v[104:107], v[152:155], v[206:209], v[104:107]
	v_mfma_f32_16x16x32_bf16 v[100:103], v[144:147], v[214:217], v[100:103]
	v_mfma_f32_16x16x32_bf16 v[96:99], v[152:155], v[214:217], v[96:99]
	s_setprio 0
	s_barrier
	ds_read_b128 v[136:139], v135
	ds_read_b128 v[218:221], v135 offset:1024
	ds_read_b128 v[222:225], v135 offset:2048
	ds_read_b128 v[226:229], v135 offset:3072
	s_barrier
	s_waitcnt lgkmcnt(0)
	s_setprio 1
	s_waitcnt lgkmcnt(0)
	v_mfma_f32_16x16x32_bf16 v[92:95], v[136:139], v[156:159], v[92:95]
	v_mfma_f32_16x16x32_bf16 v[84:87], v[136:139], v[194:197], v[84:87]
	v_mfma_f32_16x16x32_bf16 v[80:83], v[222:225], v[194:197], v[80:83]
	v_mfma_f32_16x16x32_bf16 v[88:91], v[222:225], v[156:159], v[88:91]
	v_mfma_f32_16x16x32_bf16 v[76:79], v[136:139], v[202:205], v[76:79]
	v_mfma_f32_16x16x32_bf16 v[72:75], v[222:225], v[202:205], v[72:75]
	v_mfma_f32_16x16x32_bf16 v[68:71], v[136:139], v[210:213], v[68:71]
	v_mfma_f32_16x16x32_bf16 v[64:67], v[222:225], v[210:213], v[64:67]
	v_mfma_f32_16x16x32_bf16 v[156:159], v[218:221], v[160:163], v[92:95]
	v_mfma_f32_16x16x32_bf16 v[194:197], v[218:221], v[198:201], v[84:87]
	v_mfma_f32_16x16x32_bf16 v[198:201], v[226:229], v[198:201], v[80:83]
	v_mfma_f32_16x16x32_bf16 v[160:163], v[226:229], v[160:163], v[88:91]
	v_mfma_f32_16x16x32_bf16 v[202:205], v[218:221], v[206:209], v[76:79]
	v_mfma_f32_16x16x32_bf16 v[206:209], v[226:229], v[206:209], v[72:75]
	v_mfma_f32_16x16x32_bf16 v[210:213], v[218:221], v[214:217], v[68:71]
	v_mfma_f32_16x16x32_bf16 v[214:217], v[226:229], v[214:217], v[64:67]
	s_setprio 0
	s_barrier
	s_nop 0
	ds_read_b128 v[64:67], v193 offset:16384
	ds_read_b128 v[68:71], v193 offset:17408
	ds_read_b128 v[72:75], v192 offset:16384
	ds_read_b128 v[76:79], v192 offset:17408
	ds_read_b128 v[80:83], v191 offset:16384
	ds_read_b128 v[84:87], v191 offset:17408
	ds_read_b128 v[88:91], v190 offset:16384
	ds_read_b128 v[92:95], v190 offset:17408
	s_waitcnt vmcnt(4)
	s_barrier
	s_waitcnt lgkmcnt(0)
	s_setprio 1
	s_waitcnt lgkmcnt(0)
	v_mfma_f32_16x16x32_bf16 v[60:63], v[140:143], v[64:67], v[60:63]
	v_mfma_f32_16x16x32_bf16 v[56:59], v[148:151], v[64:67], v[56:59]
	v_mfma_f32_16x16x32_bf16 v[52:55], v[140:143], v[72:75], v[52:55]
	v_mfma_f32_16x16x32_bf16 v[48:51], v[148:151], v[72:75], v[48:51]
	v_mfma_f32_16x16x32_bf16 v[230:233], v[140:143], v[80:83], v[44:47]
	v_mfma_f32_16x16x32_bf16 v[234:237], v[148:151], v[80:83], v[40:43]
	v_mfma_f32_16x16x32_bf16 v[140:143], v[140:143], v[88:91], v[36:39]
	v_mfma_f32_16x16x32_bf16 v[148:151], v[148:151], v[88:91], v[32:35]
	v_mfma_f32_16x16x32_bf16 v[32:35], v[144:147], v[68:71], v[60:63]
	v_mfma_f32_16x16x32_bf16 v[36:39], v[152:155], v[68:71], v[56:59]
	v_mfma_f32_16x16x32_bf16 v[40:43], v[144:147], v[76:79], v[52:55]
	v_mfma_f32_16x16x32_bf16 v[44:47], v[152:155], v[76:79], v[48:51]
	v_mfma_f32_16x16x32_bf16 v[48:51], v[144:147], v[84:87], v[230:233]
	v_mfma_f32_16x16x32_bf16 v[52:55], v[152:155], v[84:87], v[234:237]
	v_mfma_f32_16x16x32_bf16 v[56:59], v[144:147], v[92:95], v[140:143]
	v_mfma_f32_16x16x32_bf16 v[60:63], v[152:155], v[92:95], v[148:151]
	s_setprio 0
	s_setprio 1
	v_mfma_f32_16x16x32_bf16 v[28:31], v[136:139], v[64:67], v[28:31]
	v_mfma_f32_16x16x32_bf16 v[24:27], v[222:225], v[64:67], v[24:27]
	v_mfma_f32_16x16x32_bf16 v[20:23], v[136:139], v[72:75], v[20:23]
	v_mfma_f32_16x16x32_bf16 v[64:67], v[222:225], v[72:75], v[16:19]
	v_mfma_f32_16x16x32_bf16 v[12:15], v[136:139], v[80:83], v[12:15]
	v_mfma_f32_16x16x32_bf16 v[8:11], v[222:225], v[80:83], v[8:11]
	v_mfma_f32_16x16x32_bf16 v[72:75], v[136:139], v[88:91], v[4:7]
	v_mfma_f32_16x16x32_bf16 v[80:83], v[222:225], v[88:91], v[0:3]
	v_mfma_f32_16x16x32_bf16 v[0:3], v[218:221], v[68:71], v[28:31]
	v_mfma_f32_16x16x32_bf16 v[4:7], v[226:229], v[68:71], v[24:27]
	v_mfma_f32_16x16x32_bf16 v[16:19], v[218:221], v[76:79], v[20:23]
	v_mfma_f32_16x16x32_bf16 v[20:23], v[226:229], v[76:79], v[64:67]
	v_mfma_f32_16x16x32_bf16 v[24:27], v[218:221], v[84:87], v[12:15]
	v_mfma_f32_16x16x32_bf16 v[28:31], v[226:229], v[84:87], v[8:11]
	v_mfma_f32_16x16x32_bf16 v[64:67], v[218:221], v[92:95], v[72:75]
	v_mfma_f32_16x16x32_bf16 v[68:71], v[226:229], v[92:95], v[80:83]
	s_setprio 0
	s_barrier
	ds_read_b128 v[12:15], v130
	ds_read_b128 v[8:11], v130 offset:1024
	ds_read_b128 v[76:79], v130 offset:2048
	ds_read_b128 v[72:75], v130 offset:3072
	ds_read_b128 v[140:143], v193 offset:32768
	ds_read_b128 v[148:151], v193 offset:33792
	ds_read_b128 v[218:221], v192 offset:32768
	ds_read_b128 v[222:225], v192 offset:33792
	ds_read_b128 v[226:229], v191 offset:32768
	ds_read_b128 v[230:233], v191 offset:33792
	ds_read_b128 v[234:237], v190 offset:32768
	ds_read_b128 v[238:241], v190 offset:33792
	s_waitcnt vmcnt(2)
	s_barrier
	s_waitcnt lgkmcnt(0)
	s_setprio 1
	s_waitcnt lgkmcnt(0)
	v_mfma_f32_16x16x32_bf16 v[80:83], v[12:15], v[140:143], v[124:127]
	v_mfma_f32_16x16x32_bf16 v[84:87], v[76:79], v[140:143], v[120:123]
	v_mfma_f32_16x16x32_bf16 v[88:91], v[12:15], v[218:221], v[116:119]
	v_mfma_f32_16x16x32_bf16 v[92:95], v[76:79], v[218:221], v[112:115]
	v_mfma_f32_16x16x32_bf16 v[108:111], v[12:15], v[226:229], v[108:111]
	v_mfma_f32_16x16x32_bf16 v[104:107], v[76:79], v[226:229], v[104:107]
	v_mfma_f32_16x16x32_bf16 v[100:103], v[12:15], v[234:237], v[100:103]
	v_mfma_f32_16x16x32_bf16 v[96:99], v[76:79], v[234:237], v[96:99]
	v_mfma_f32_16x16x32_bf16 v[152:155], v[8:11], v[148:151], v[80:83]
	v_mfma_f32_16x16x32_bf16 v[144:147], v[72:75], v[148:151], v[84:87]
	v_mfma_f32_16x16x32_bf16 v[136:139], v[8:11], v[222:225], v[88:91]
	v_mfma_f32_16x16x32_bf16 v[128:131], v[72:75], v[222:225], v[92:95]
	v_mfma_f32_16x16x32_bf16 v[120:123], v[8:11], v[230:233], v[108:111]
	v_mfma_f32_16x16x32_bf16 v[112:115], v[72:75], v[230:233], v[104:107]
	v_mfma_f32_16x16x32_bf16 v[104:107], v[8:11], v[238:241], v[100:103]
	v_mfma_f32_16x16x32_bf16 v[96:99], v[72:75], v[238:241], v[96:99]
	s_setprio 0
	s_barrier
	ds_read_b128 v[88:91], v132
	ds_read_b128 v[80:83], v132 offset:1024
	ds_read_b128 v[92:95], v132 offset:2048
	ds_read_b128 v[84:87], v132 offset:3072
	s_waitcnt vmcnt(0)
	s_barrier
	s_waitcnt lgkmcnt(0)
	s_setprio 1
	s_waitcnt lgkmcnt(0)
	v_mfma_f32_16x16x32_bf16 v[100:103], v[88:91], v[140:143], v[156:159]
	v_mfma_f32_16x16x32_bf16 v[108:111], v[92:95], v[140:143], v[160:163]
	v_mfma_f32_16x16x32_bf16 v[116:119], v[88:91], v[218:221], v[194:197]
	v_mfma_f32_16x16x32_bf16 v[124:127], v[92:95], v[218:221], v[198:201]
	v_mfma_f32_16x16x32_bf16 v[160:163], v[88:91], v[226:229], v[202:205]
	v_mfma_f32_16x16x32_bf16 v[194:197], v[92:95], v[226:229], v[206:209]
	v_mfma_f32_16x16x32_bf16 v[198:201], v[88:91], v[234:237], v[210:213]
	v_mfma_f32_16x16x32_bf16 v[202:205], v[92:95], v[234:237], v[214:217]
	v_mfma_f32_16x16x32_bf16 v[156:159], v[80:83], v[148:151], v[100:103]
	v_mfma_f32_16x16x32_bf16 v[148:151], v[84:87], v[148:151], v[108:111]
	v_mfma_f32_16x16x32_bf16 v[140:143], v[80:83], v[222:225], v[116:119]
	v_mfma_f32_16x16x32_bf16 v[132:135], v[84:87], v[222:225], v[124:127]
	v_mfma_f32_16x16x32_bf16 v[124:127], v[80:83], v[230:233], v[160:163]
	v_mfma_f32_16x16x32_bf16 v[116:119], v[84:87], v[230:233], v[194:197]
	v_mfma_f32_16x16x32_bf16 v[108:111], v[80:83], v[238:241], v[198:201]
	v_mfma_f32_16x16x32_bf16 v[100:103], v[84:87], v[238:241], v[202:205]
	s_setprio 0
	s_lshl_b64 s[56:57], s[46:47], 2
	s_barrier
	v_mbcnt_lo_u32_b32 v162, -1, 0
	v_mbcnt_hi_u32_b32 v162, -1, v162
	s_add_u32 s56, s87, s56
	v_add_u32_e32 v160, s64, v162
	s_addc_u32 s57, s88, s57
	v_and_b32_e32 v164, 0x100, v160
	v_and_b32_e32 v162, 15, v162
	v_lshl_add_u64 v[160:161], s[56:57], 0, v[164:165]
	v_lshlrev_b32_e32 v164, 2, v162
	v_lshl_add_u64 v[160:161], v[160:161], 0, v[164:165]
	global_load_dword v180, v[160:161], off
	global_load_dword v178, v[160:161], off offset:64
	global_load_dword v176, v[160:161], off offset:128
	global_load_dword v174, v[160:161], off offset:192
	global_load_dword v172, v[160:161], off offset:512
	global_load_dword v170, v[160:161], off offset:576
	global_load_dword v168, v[160:161], off offset:640
	global_load_dword v166, v[160:161], off offset:704
	v_mbcnt_lo_u32_b32 v194, -1, 0
	v_mbcnt_hi_u32_b32 v194, -1, v194
	s_cmp_lg_u32 s79, 0
	v_add_u32_e32 v160, s64, v194
	v_bfe_u32 v196, v160, 8, 1
	v_ashrrev_i32_e32 v199, 6, v160
	v_bfe_u32 v160, v194, 4, 2
	s_cselect_b64 s[56:57], -1, 0
	v_and_b32_e32 v197, 3, v199
	v_and_b32_e32 v195, 15, v194
	s_and_b64 vcc, exec, s[56:57]
	v_lshlrev_b32_e32 v198, 4, v160
	s_cbranch_vccz .LBB0_533
	s_lshl_b32 s14, s78, 22
	s_lshl_b32 s36, s80, 14
	s_add_i32 s36, s36, s14
	v_lshlrev_b32_e32 v160, 6, v195
	v_or3_b32 v160, s36, v160, v198
	v_lshl_add_u32 v160, v197, 20, v160
	v_lshl_or_b32 v164, v196, 12, v160
	s_waitcnt vmcnt(0)
	v_pk_mul_f32 v[160:161], v[154:155], v[180:181] op_sel_hi:[1,0]
	v_pk_mul_f32 v[200:201], v[146:147], v[180:181] op_sel_hi:[1,0]
	v_max_f32_e32 v160, 0, v160
	v_mul_f32_e32 v204, v160, v160
	v_max_f32_e32 v160, 0, v200
	v_pk_mul_f32 v[162:163], v[152:153], v[180:181] op_sel_hi:[1,0]
	v_mul_f32_e32 v200, v160, v160
	v_max_f32_e32 v160, 0, v161
	v_pk_mul_f32 v[202:203], v[144:145], v[180:181] op_sel_hi:[1,0]
	v_max_f32_e32 v162, 0, v162
	v_max_f32_e32 v163, 0, v163
	v_mul_f32_e32 v161, v160, v160
	v_max_f32_e32 v160, 0, v201
	v_mul_f32_e32 v162, v162, v162
	v_max_f32_e32 v202, 0, v202
	v_mul_f32_e32 v163, v163, v163
	v_max_f32_e32 v203, 0, v203
	v_mul_f32_e32 v201, v160, v160
	v_cvt_pk_bf16_f32 v160, v162, v163
	v_cvt_pk_bf16_f32 v161, v204, v161
	v_mul_f32_e32 v202, v202, v202
	v_mul_f32_e32 v203, v203, v203
	v_cvt_pk_bf16_f32 v162, v202, v203
	v_cvt_pk_bf16_f32 v163, v200, v201
	global_store_dwordx4 v164, v[160:163], s[0:1]
	v_pk_mul_f32 v[202:203], v[150:151], v[180:181] op_sel_hi:[1,0]
	v_lshl_add_u64 v[200:201], s[0:1], 0, v[164:165]
	v_pk_mul_f32 v[160:161], v[158:159], v[180:181] op_sel_hi:[1,0]
	v_pk_mul_f32 v[162:163], v[156:157], v[180:181] op_sel_hi:[1,0]
	v_max_f32_e32 v160, 0, v160
	v_mul_f32_e32 v206, v160, v160
	v_max_f32_e32 v160, 0, v202
	v_mul_f32_e32 v202, v160, v160
	v_max_f32_e32 v160, 0, v161
	v_pk_mul_f32 v[204:205], v[148:149], v[180:181] op_sel_hi:[1,0]
	v_max_f32_e32 v162, 0, v162
	v_max_f32_e32 v163, 0, v163
	v_mul_f32_e32 v161, v160, v160
	v_max_f32_e32 v160, 0, v203
	v_add_co_u32_e32 v200, vcc, s72, v200
	v_mul_f32_e32 v162, v162, v162
	v_max_f32_e32 v204, 0, v204
	v_mul_f32_e32 v163, v163, v163
	v_max_f32_e32 v205, 0, v205
	v_mul_f32_e32 v203, v160, v160
	v_cvt_pk_bf16_f32 v160, v162, v163
	v_cvt_pk_bf16_f32 v161, v206, v161
	v_addc_co_u32_e32 v201, vcc, 0, v201, vcc
	v_mul_f32_e32 v204, v204, v204
	v_mul_f32_e32 v205, v205, v205
	v_cvt_pk_bf16_f32 v162, v204, v205
	v_cvt_pk_bf16_f32 v163, v202, v203
	global_store_dwordx4 v[200:201], v[160:163], off
	v_pk_mul_f32 v[202:203], v[130:131], v[178:179] op_sel_hi:[1,0]
	v_pk_mul_f32 v[204:205], v[128:129], v[178:179] op_sel_hi:[1,0]
	v_pk_mul_f32 v[160:161], v[138:139], v[178:179] op_sel_hi:[1,0]
	v_pk_mul_f32 v[162:163], v[136:137], v[178:179] op_sel_hi:[1,0]
	v_max_f32_e32 v160, 0, v160
	v_mul_f32_e32 v206, v160, v160
	v_max_f32_e32 v160, 0, v202
	v_mul_f32_e32 v202, v160, v160
	v_max_f32_e32 v160, 0, v161
	v_max_f32_e32 v162, 0, v162
	v_max_f32_e32 v163, 0, v163
	v_mul_f32_e32 v161, v160, v160
	v_max_f32_e32 v160, 0, v203
	v_mul_f32_e32 v162, v162, v162
	v_max_f32_e32 v204, 0, v204
	v_mul_f32_e32 v163, v163, v163
	v_max_f32_e32 v205, 0, v205
	v_mul_f32_e32 v203, v160, v160
	v_cvt_pk_bf16_f32 v160, v162, v163
	v_cvt_pk_bf16_f32 v161, v206, v161
	v_mul_f32_e32 v204, v204, v204
	v_mul_f32_e32 v205, v205, v205
	v_cvt_pk_bf16_f32 v162, v204, v205
	v_cvt_pk_bf16_f32 v163, v202, v203
	global_store_dwordx4 v164, v[160:163], s[0:1] offset:1024
	v_pk_mul_f32 v[202:203], v[134:135], v[178:179] op_sel_hi:[1,0]
	v_pk_mul_f32 v[204:205], v[132:133], v[178:179] op_sel_hi:[1,0]
	v_pk_mul_f32 v[160:161], v[142:143], v[178:179] op_sel_hi:[1,0]
	v_pk_mul_f32 v[162:163], v[140:141], v[178:179] op_sel_hi:[1,0]
	v_max_f32_e32 v160, 0, v160
	v_mul_f32_e32 v206, v160, v160
	v_max_f32_e32 v160, 0, v202
	v_mul_f32_e32 v202, v160, v160
	v_max_f32_e32 v160, 0, v161
	v_max_f32_e32 v162, 0, v162
	v_max_f32_e32 v163, 0, v163
	v_mul_f32_e32 v161, v160, v160
	v_max_f32_e32 v160, 0, v203
	v_mul_f32_e32 v162, v162, v162
	v_max_f32_e32 v204, 0, v204
	v_mul_f32_e32 v163, v163, v163
	v_max_f32_e32 v205, 0, v205
	v_mul_f32_e32 v203, v160, v160
	v_cvt_pk_bf16_f32 v160, v162, v163
	v_cvt_pk_bf16_f32 v161, v206, v161
	v_mul_f32_e32 v204, v204, v204
	v_mul_f32_e32 v205, v205, v205
	v_cvt_pk_bf16_f32 v162, v204, v205
	v_cvt_pk_bf16_f32 v163, v202, v203
	global_store_dwordx4 v[200:201], v[160:163], off offset:1024
	v_pk_mul_f32 v[202:203], v[114:115], v[176:177] op_sel_hi:[1,0]
	v_pk_mul_f32 v[204:205], v[112:113], v[176:177] op_sel_hi:[1,0]
	v_pk_mul_f32 v[160:161], v[122:123], v[176:177] op_sel_hi:[1,0]
	v_pk_mul_f32 v[162:163], v[120:121], v[176:177] op_sel_hi:[1,0]
	v_max_f32_e32 v160, 0, v160
	v_mul_f32_e32 v206, v160, v160
	v_max_f32_e32 v160, 0, v202
	v_mul_f32_e32 v202, v160, v160
	v_max_f32_e32 v160, 0, v161
	v_max_f32_e32 v162, 0, v162
	v_max_f32_e32 v163, 0, v163
	v_mul_f32_e32 v161, v160, v160
	v_max_f32_e32 v160, 0, v203
	v_mul_f32_e32 v162, v162, v162
	v_max_f32_e32 v204, 0, v204
	v_mul_f32_e32 v163, v163, v163
	v_max_f32_e32 v205, 0, v205
	v_mul_f32_e32 v203, v160, v160
	v_cvt_pk_bf16_f32 v160, v162, v163
	v_cvt_pk_bf16_f32 v161, v206, v161
	v_mul_f32_e32 v204, v204, v204
	v_mul_f32_e32 v205, v205, v205
	v_cvt_pk_bf16_f32 v162, v204, v205
	v_cvt_pk_bf16_f32 v163, v202, v203
	global_store_dwordx4 v164, v[160:163], s[0:1] offset:2048
	v_pk_mul_f32 v[202:203], v[118:119], v[176:177] op_sel_hi:[1,0]
	v_pk_mul_f32 v[204:205], v[116:117], v[176:177] op_sel_hi:[1,0]
	v_pk_mul_f32 v[160:161], v[126:127], v[176:177] op_sel_hi:[1,0]
	v_pk_mul_f32 v[162:163], v[124:125], v[176:177] op_sel_hi:[1,0]
	v_max_f32_e32 v160, 0, v160
	v_mul_f32_e32 v206, v160, v160
	v_max_f32_e32 v160, 0, v202
	v_mul_f32_e32 v202, v160, v160
	v_max_f32_e32 v160, 0, v161
	v_max_f32_e32 v162, 0, v162
	v_max_f32_e32 v163, 0, v163
	v_mul_f32_e32 v161, v160, v160
	v_max_f32_e32 v160, 0, v203
	v_mul_f32_e32 v162, v162, v162
	v_max_f32_e32 v204, 0, v204
	v_mul_f32_e32 v163, v163, v163
	v_max_f32_e32 v205, 0, v205
	v_mul_f32_e32 v203, v160, v160
	v_cvt_pk_bf16_f32 v160, v162, v163
	v_cvt_pk_bf16_f32 v161, v206, v161
	v_mul_f32_e32 v204, v204, v204
	v_mul_f32_e32 v205, v205, v205
	v_cvt_pk_bf16_f32 v162, v204, v205
	v_cvt_pk_bf16_f32 v163, v202, v203
	global_store_dwordx4 v[200:201], v[160:163], off offset:2048
	v_pk_mul_f32 v[200:201], v[98:99], v[174:175] op_sel_hi:[1,0]
	v_pk_mul_f32 v[202:203], v[96:97], v[174:175] op_sel_hi:[1,0]
	v_pk_mul_f32 v[160:161], v[106:107], v[174:175] op_sel_hi:[1,0]
	v_pk_mul_f32 v[162:163], v[104:105], v[174:175] op_sel_hi:[1,0]
	v_max_f32_e32 v160, 0, v160
	v_mul_f32_e32 v204, v160, v160
	v_max_f32_e32 v160, 0, v200
	v_mul_f32_e32 v200, v160, v160
	v_max_f32_e32 v160, 0, v161
	v_max_f32_e32 v162, 0, v162
	v_max_f32_e32 v163, 0, v163
	v_mul_f32_e32 v161, v160, v160
	v_max_f32_e32 v160, 0, v201
	v_mul_f32_e32 v162, v162, v162
	v_max_f32_e32 v202, 0, v202
	v_mul_f32_e32 v163, v163, v163
	v_max_f32_e32 v203, 0, v203
	v_mul_f32_e32 v201, v160, v160
	v_cvt_pk_bf16_f32 v160, v162, v163
	v_cvt_pk_bf16_f32 v161, v204, v161
	v_mul_f32_e32 v202, v202, v202
	v_mul_f32_e32 v203, v203, v203
	v_cvt_pk_bf16_f32 v162, v202, v203
	v_cvt_pk_bf16_f32 v163, v200, v201
	global_store_dwordx4 v164, v[160:163], s[0:1] offset:3072
	v_pk_mul_f32 v[200:201], v[102:103], v[174:175] op_sel_hi:[1,0]
	v_pk_mul_f32 v[202:203], v[100:101], v[174:175] op_sel_hi:[1,0]
	v_pk_mul_f32 v[160:161], v[110:111], v[174:175] op_sel_hi:[1,0]
	v_pk_mul_f32 v[162:163], v[108:109], v[174:175] op_sel_hi:[1,0]
	v_max_f32_e32 v160, 0, v160
	v_mul_f32_e32 v204, v160, v160
	v_max_f32_e32 v160, 0, v200
	v_max_f32_e32 v162, 0, v162
	v_max_f32_e32 v163, 0, v163
	v_mul_f32_e32 v200, v160, v160
	v_max_f32_e32 v160, 0, v161
	v_mul_f32_e32 v162, v162, v162
	v_max_f32_e32 v202, 0, v202
	v_mul_f32_e32 v163, v163, v163
	v_max_f32_e32 v203, 0, v203
	v_mul_f32_e32 v161, v160, v160
	v_max_f32_e32 v160, 0, v201
	v_mul_f32_e32 v202, v202, v202
	v_mul_f32_e32 v203, v203, v203
	v_mul_f32_e32 v201, v160, v160
	v_cvt_pk_bf16_f32 v160, v162, v163
	v_cvt_pk_bf16_f32 v161, v204, v161
	v_cvt_pk_bf16_f32 v162, v202, v203
	v_cvt_pk_bf16_f32 v163, v200, v201
	v_add_u32_e32 v164, 0x80c00, v164
	s_cbranch_execnz .LBB0_525

.LBB0_561:
	ds_read_b128 v[162:165], v161
	ds_read_b128 v[166:169], v161 offset:1024
	ds_read_b128 v[170:173], v161 offset:2048
	ds_read_b128 v[174:177], v161 offset:3072
	ds_read_b128 v[178:181], v152
	ds_read_b128 v[182:185], v152 offset:1024
	ds_read_b128 v[186:189], v151
	ds_read_b128 v[190:193], v151 offset:1024
	ds_read_b128 v[194:197], v150
	ds_read_b128 v[198:201], v150 offset:1024
	ds_read_b128 v[202:205], v149
	ds_read_b128 v[206:209], v149 offset:1024
	s_waitcnt lgkmcnt(8)
	s_waitcnt vmcnt(10)
	s_barrier
	s_waitcnt lgkmcnt(0)
	s_setprio 1
	s_waitcnt lgkmcnt(0)
	v_mfma_f32_16x16x32_bf16 v[124:127], v[162:165], v[178:181], v[124:127]
	v_mfma_f32_16x16x32_bf16 v[120:123], v[170:173], v[178:181], v[120:123]
	v_mfma_f32_16x16x32_bf16 v[116:119], v[162:165], v[186:189], v[116:119]
	v_mfma_f32_16x16x32_bf16 v[112:115], v[170:173], v[186:189], v[112:115]
	v_mfma_f32_16x16x32_bf16 v[108:111], v[162:165], v[194:197], v[108:111]
	v_mfma_f32_16x16x32_bf16 v[104:107], v[170:173], v[194:197], v[104:107]
	v_mfma_f32_16x16x32_bf16 v[100:103], v[162:165], v[202:205], v[100:103]
	v_mfma_f32_16x16x32_bf16 v[96:99], v[170:173], v[202:205], v[96:99]
	v_mfma_f32_16x16x32_bf16 v[124:127], v[166:169], v[182:185], v[124:127]
	v_mfma_f32_16x16x32_bf16 v[120:123], v[174:177], v[182:185], v[120:123]
	v_mfma_f32_16x16x32_bf16 v[116:119], v[166:169], v[190:193], v[116:119]
	v_mfma_f32_16x16x32_bf16 v[112:115], v[174:177], v[190:193], v[112:115]
	v_mfma_f32_16x16x32_bf16 v[108:111], v[166:169], v[198:201], v[108:111]
	v_mfma_f32_16x16x32_bf16 v[104:107], v[174:177], v[198:201], v[104:107]
	v_mfma_f32_16x16x32_bf16 v[100:103], v[166:169], v[206:209], v[100:103]
	v_mfma_f32_16x16x32_bf16 v[96:99], v[174:177], v[206:209], v[96:99]
	s_setprio 0
	s_barrier
	v_readfirstlane_b32 s36, v148
	v_lshl_add_u64 v[226:227], v[130:131], 0, s[26:27]
	s_mov_b32 m0, s36
	v_readfirstlane_b32 s36, v147
	ds_read_b128 v[210:213], v158
	ds_read_b128 v[214:217], v158 offset:1024
	ds_read_b128 v[218:221], v158 offset:2048
	ds_read_b128 v[222:225], v158 offset:3072
	global_load_lds_dwordx4 v[226:227], off
	v_lshl_add_u64 v[226:227], v[130:131], 0, s[28:29]
	s_mov_b32 m0, s36
	s_add_i32 s68, s68, 2
	global_load_lds_dwordx4 v[226:227], off
	s_waitcnt vmcnt(10)
	s_barrier
	s_waitcnt lgkmcnt(0)
	s_setprio 1
	s_waitcnt lgkmcnt(0)
	v_mfma_f32_16x16x32_bf16 v[92:95], v[210:213], v[178:181], v[92:95]
	v_mfma_f32_16x16x32_bf16 v[88:91], v[218:221], v[178:181], v[88:91]
	v_mfma_f32_16x16x32_bf16 v[84:87], v[210:213], v[186:189], v[84:87]
	v_mfma_f32_16x16x32_bf16 v[80:83], v[218:221], v[186:189], v[80:83]
	v_mfma_f32_16x16x32_bf16 v[76:79], v[210:213], v[194:197], v[76:79]
	v_mfma_f32_16x16x32_bf16 v[72:75], v[218:221], v[194:197], v[72:75]
	v_mfma_f32_16x16x32_bf16 v[68:71], v[210:213], v[202:205], v[68:71]
	v_mfma_f32_16x16x32_bf16 v[64:67], v[218:221], v[202:205], v[64:67]
	v_mfma_f32_16x16x32_bf16 v[92:95], v[214:217], v[182:185], v[92:95]
	v_mfma_f32_16x16x32_bf16 v[88:91], v[222:225], v[182:185], v[88:91]
	v_mfma_f32_16x16x32_bf16 v[84:87], v[214:217], v[190:193], v[84:87]
	v_mfma_f32_16x16x32_bf16 v[80:83], v[222:225], v[190:193], v[80:83]
	v_mfma_f32_16x16x32_bf16 v[76:79], v[214:217], v[198:201], v[76:79]
	v_mfma_f32_16x16x32_bf16 v[72:75], v[222:225], v[198:201], v[72:75]
	v_mfma_f32_16x16x32_bf16 v[68:71], v[214:217], v[206:209], v[68:71]
	v_mfma_f32_16x16x32_bf16 v[64:67], v[222:225], v[206:209], v[64:67]
	s_setprio 0
	v_readfirstlane_b32 s36, v134
	v_lshl_add_u64 v[226:227], v[132:133], 0, s[30:31]
	s_mov_b32 m0, s36
	v_readfirstlane_b32 s36, v146
	s_barrier
	ds_read_b128 v[178:181], v152 offset:16384
	ds_read_b128 v[182:185], v152 offset:17408
	ds_read_b128 v[186:189], v151 offset:16384
	ds_read_b128 v[190:193], v151 offset:17408
	ds_read_b128 v[194:197], v150 offset:16384
	ds_read_b128 v[198:201], v150 offset:17408
	ds_read_b128 v[202:205], v149 offset:16384
	ds_read_b128 v[206:209], v149 offset:17408
	global_load_lds_dwordx4 v[226:227], off
	v_lshl_add_u64 v[226:227], v[132:133], 0, s[34:35]
	s_mov_b32 m0, s36
	s_nop 0
	global_load_lds_dwordx4 v[226:227], off
	s_barrier
	s_waitcnt lgkmcnt(0)
	s_setprio 1
	s_waitcnt lgkmcnt(0)
	v_mfma_f32_16x16x32_bf16 v[60:63], v[162:165], v[178:181], v[60:63]
	v_mfma_f32_16x16x32_bf16 v[56:59], v[170:173], v[178:181], v[56:59]
	v_mfma_f32_16x16x32_bf16 v[52:55], v[162:165], v[186:189], v[52:55]
	v_mfma_f32_16x16x32_bf16 v[48:51], v[170:173], v[186:189], v[48:51]
	v_mfma_f32_16x16x32_bf16 v[44:47], v[162:165], v[194:197], v[44:47]
	v_mfma_f32_16x16x32_bf16 v[40:43], v[170:173], v[194:197], v[40:43]
	v_mfma_f32_16x16x32_bf16 v[36:39], v[162:165], v[202:205], v[36:39]
	v_mfma_f32_16x16x32_bf16 v[32:35], v[170:173], v[202:205], v[32:35]
	v_mfma_f32_16x16x32_bf16 v[60:63], v[166:169], v[182:185], v[60:63]
	v_mfma_f32_16x16x32_bf16 v[56:59], v[174:177], v[182:185], v[56:59]
	v_mfma_f32_16x16x32_bf16 v[52:55], v[166:169], v[190:193], v[52:55]
	v_mfma_f32_16x16x32_bf16 v[48:51], v[174:177], v[190:193], v[48:51]
	v_mfma_f32_16x16x32_bf16 v[44:47], v[166:169], v[198:201], v[44:47]
	v_mfma_f32_16x16x32_bf16 v[40:43], v[174:177], v[198:201], v[40:43]
	v_mfma_f32_16x16x32_bf16 v[36:39], v[166:169], v[206:209], v[36:39]
	v_mfma_f32_16x16x32_bf16 v[32:35], v[174:177], v[206:209], v[32:35]
	s_setprio 0
	s_barrier
	v_readfirstlane_b32 s36, v145
	v_lshl_add_u64 v[162:163], v[130:131], 0, s[38:39]
	s_mov_b32 m0, s36
	v_readfirstlane_b32 s36, v144
	global_load_lds_dwordx4 v[162:163], off
	v_lshl_add_u64 v[162:163], v[130:131], 0, s[44:45]
	s_mov_b32 m0, s36
	s_nop 0
	global_load_lds_dwordx4 v[162:163], off
	v_readfirstlane_b32 s36, v143
	v_lshl_add_u64 v[164:165], v[132:133], 0, s[46:47]
	s_mov_b32 m0, s36
	v_readfirstlane_b32 s36, v142
	global_load_lds_dwordx4 v[164:165], off
	v_lshl_add_u64 v[164:165], v[132:133], 0, s[50:51]
	s_mov_b32 m0, s36
	s_nop 0
	global_load_lds_dwordx4 v[164:165], off
	s_waitcnt vmcnt(12)
	s_barrier
	s_setprio 1
	v_mfma_f32_16x16x32_bf16 v[28:31], v[210:213], v[178:181], v[28:31]
	v_mfma_f32_16x16x32_bf16 v[24:27], v[218:221], v[178:181], v[24:27]
	v_mfma_f32_16x16x32_bf16 v[20:23], v[210:213], v[186:189], v[20:23]
	v_mfma_f32_16x16x32_bf16 v[16:19], v[218:221], v[186:189], v[16:19]
	v_mfma_f32_16x16x32_bf16 v[12:15], v[210:213], v[194:197], v[12:15]
	v_mfma_f32_16x16x32_bf16 v[8:11], v[218:221], v[194:197], v[8:11]
	v_mfma_f32_16x16x32_bf16 v[4:7], v[210:213], v[202:205], v[4:7]
	v_mfma_f32_16x16x32_bf16 v[0:3], v[218:221], v[202:205], v[0:3]
	v_mfma_f32_16x16x32_bf16 v[28:31], v[214:217], v[182:185], v[28:31]
	v_mfma_f32_16x16x32_bf16 v[24:27], v[222:225], v[182:185], v[24:27]
	v_mfma_f32_16x16x32_bf16 v[20:23], v[214:217], v[190:193], v[20:23]
	v_mfma_f32_16x16x32_bf16 v[16:19], v[222:225], v[190:193], v[16:19]
	v_mfma_f32_16x16x32_bf16 v[12:15], v[214:217], v[198:201], v[12:15]
	v_mfma_f32_16x16x32_bf16 v[8:11], v[222:225], v[198:201], v[8:11]
	v_mfma_f32_16x16x32_bf16 v[4:7], v[214:217], v[206:209], v[4:7]
	v_mfma_f32_16x16x32_bf16 v[0:3], v[222:225], v[206:209], v[0:3]
	s_setprio 0
	s_barrier
	ds_read_b128 v[162:165], v154
	ds_read_b128 v[166:169], v154 offset:1024
	ds_read_b128 v[170:173], v154 offset:2048
	ds_read_b128 v[174:177], v154 offset:3072
	ds_read_b128 v[178:181], v152 offset:32768
	ds_read_b128 v[182:185], v152 offset:33792
	ds_read_b128 v[186:189], v151 offset:32768
	ds_read_b128 v[190:193], v151 offset:33792
	ds_read_b128 v[194:197], v150 offset:32768
	ds_read_b128 v[198:201], v150 offset:33792
	ds_read_b128 v[202:205], v149 offset:32768
	ds_read_b128 v[206:209], v149 offset:33792
	s_waitcnt lgkmcnt(8)
	s_waitcnt vmcnt(10)
	s_barrier
	s_waitcnt lgkmcnt(0)
	s_setprio 1
	s_waitcnt lgkmcnt(0)
	v_mfma_f32_16x16x32_bf16 v[124:127], v[162:165], v[178:181], v[124:127]
	v_mfma_f32_16x16x32_bf16 v[120:123], v[170:173], v[178:181], v[120:123]
	v_mfma_f32_16x16x32_bf16 v[116:119], v[162:165], v[186:189], v[116:119]
	v_mfma_f32_16x16x32_bf16 v[112:115], v[170:173], v[186:189], v[112:115]
	v_mfma_f32_16x16x32_bf16 v[108:111], v[162:165], v[194:197], v[108:111]
	v_mfma_f32_16x16x32_bf16 v[104:107], v[170:173], v[194:197], v[104:107]
	v_mfma_f32_16x16x32_bf16 v[100:103], v[162:165], v[202:205], v[100:103]
	v_mfma_f32_16x16x32_bf16 v[96:99], v[170:173], v[202:205], v[96:99]
	v_mfma_f32_16x16x32_bf16 v[124:127], v[166:169], v[182:185], v[124:127]
	v_mfma_f32_16x16x32_bf16 v[120:123], v[174:177], v[182:185], v[120:123]
	v_mfma_f32_16x16x32_bf16 v[116:119], v[166:169], v[190:193], v[116:119]
	v_mfma_f32_16x16x32_bf16 v[112:115], v[174:177], v[190:193], v[112:115]
	v_mfma_f32_16x16x32_bf16 v[108:111], v[166:169], v[198:201], v[108:111]
	v_mfma_f32_16x16x32_bf16 v[104:107], v[174:177], v[198:201], v[104:107]
	v_mfma_f32_16x16x32_bf16 v[100:103], v[166:169], v[206:209], v[100:103]
	v_mfma_f32_16x16x32_bf16 v[96:99], v[174:177], v[206:209], v[96:99]
	s_setprio 0
	s_barrier
	v_readfirstlane_b32 s36, v141
	v_lshl_add_u64 v[226:227], v[130:131], 0, s[56:57]
	s_mov_b32 m0, s36
	v_readfirstlane_b32 s36, v140
	ds_read_b128 v[210:213], v153
	ds_read_b128 v[214:217], v153 offset:1024
	ds_read_b128 v[218:221], v153 offset:2048
	ds_read_b128 v[222:225], v153 offset:3072
	global_load_lds_dwordx4 v[226:227], off
	v_lshl_add_u64 v[226:227], v[130:131], 0, s[58:59]
	s_mov_b32 m0, s36
	s_nop 0
	global_load_lds_dwordx4 v[226:227], off
	s_waitcnt vmcnt(10)
	s_barrier
	s_waitcnt lgkmcnt(0)
	s_setprio 1
	s_waitcnt lgkmcnt(0)
	v_mfma_f32_16x16x32_bf16 v[92:95], v[210:213], v[178:181], v[92:95]
	v_mfma_f32_16x16x32_bf16 v[88:91], v[218:221], v[178:181], v[88:91]
	v_mfma_f32_16x16x32_bf16 v[84:87], v[210:213], v[186:189], v[84:87]
	v_mfma_f32_16x16x32_bf16 v[80:83], v[218:221], v[186:189], v[80:83]
	v_mfma_f32_16x16x32_bf16 v[76:79], v[210:213], v[194:197], v[76:79]
	v_mfma_f32_16x16x32_bf16 v[72:75], v[218:221], v[194:197], v[72:75]
	v_mfma_f32_16x16x32_bf16 v[68:71], v[210:213], v[202:205], v[68:71]
	v_mfma_f32_16x16x32_bf16 v[64:67], v[218:221], v[202:205], v[64:67]
	v_mfma_f32_16x16x32_bf16 v[92:95], v[214:217], v[182:185], v[92:95]
	v_mfma_f32_16x16x32_bf16 v[88:91], v[222:225], v[182:185], v[88:91]
	v_mfma_f32_16x16x32_bf16 v[84:87], v[214:217], v[190:193], v[84:87]
	v_mfma_f32_16x16x32_bf16 v[80:83], v[222:225], v[190:193], v[80:83]
	v_mfma_f32_16x16x32_bf16 v[76:79], v[214:217], v[198:201], v[76:79]
	v_mfma_f32_16x16x32_bf16 v[72:75], v[222:225], v[198:201], v[72:75]
	v_mfma_f32_16x16x32_bf16 v[68:71], v[214:217], v[206:209], v[68:71]
	v_mfma_f32_16x16x32_bf16 v[64:67], v[222:225], v[206:209], v[64:67]
	s_setprio 0
	v_readfirstlane_b32 s36, v139
	v_lshl_add_u64 v[226:227], v[132:133], 0, s[60:61]
	s_mov_b32 m0, s36
	v_readfirstlane_b32 s36, v138
	s_barrier
	ds_read_b128 v[178:181], v152 offset:49152
	ds_read_b128 v[182:185], v152 offset:50176
	ds_read_b128 v[186:189], v151 offset:49152
	ds_read_b128 v[190:193], v151 offset:50176
	ds_read_b128 v[194:197], v150 offset:49152
	ds_read_b128 v[198:201], v150 offset:50176
	ds_read_b128 v[202:205], v149 offset:49152
	ds_read_b128 v[206:209], v149 offset:50176
	global_load_lds_dwordx4 v[226:227], off
	s_mov_b32 m0, s36
	s_nop 0
	global_load_lds_dwordx4 v[132:133], off
	s_barrier
	s_waitcnt lgkmcnt(0)
	s_setprio 1
	s_waitcnt lgkmcnt(0)
	v_mfma_f32_16x16x32_bf16 v[60:63], v[162:165], v[178:181], v[60:63]
	v_mfma_f32_16x16x32_bf16 v[56:59], v[170:173], v[178:181], v[56:59]
	v_mfma_f32_16x16x32_bf16 v[52:55], v[162:165], v[186:189], v[52:55]
	v_mfma_f32_16x16x32_bf16 v[48:51], v[170:173], v[186:189], v[48:51]
	v_mfma_f32_16x16x32_bf16 v[44:47], v[162:165], v[194:197], v[44:47]
	v_mfma_f32_16x16x32_bf16 v[40:43], v[170:173], v[194:197], v[40:43]
	v_mfma_f32_16x16x32_bf16 v[36:39], v[162:165], v[202:205], v[36:39]
	v_mfma_f32_16x16x32_bf16 v[32:35], v[170:173], v[202:205], v[32:35]
	v_mfma_f32_16x16x32_bf16 v[60:63], v[166:169], v[182:185], v[60:63]
	v_mfma_f32_16x16x32_bf16 v[56:59], v[174:177], v[182:185], v[56:59]
	v_mfma_f32_16x16x32_bf16 v[52:55], v[166:169], v[190:193], v[52:55]
	v_mfma_f32_16x16x32_bf16 v[48:51], v[174:177], v[190:193], v[48:51]
	v_mfma_f32_16x16x32_bf16 v[44:47], v[166:169], v[198:201], v[44:47]
	v_mfma_f32_16x16x32_bf16 v[40:43], v[174:177], v[198:201], v[40:43]
	v_mfma_f32_16x16x32_bf16 v[36:39], v[166:169], v[206:209], v[36:39]
	v_mfma_f32_16x16x32_bf16 v[32:35], v[174:177], v[206:209], v[32:35]
	s_setprio 0
	s_barrier
	v_readfirstlane_b32 s36, v137
	v_lshl_add_u64 v[162:163], v[130:131], 0, s[60:61]
	s_mov_b32 m0, s36
	v_readfirstlane_b32 s36, v136
	global_load_lds_dwordx4 v[162:163], off
	s_mov_b32 m0, s36
	s_nop 0
	global_load_lds_dwordx4 v[130:131], off
	v_lshl_add_u64 v[132:133], v[132:133], 0, s[64:65]
	v_readfirstlane_b32 s36, v160
	v_lshl_add_u64 v[164:165], v[132:133], 0, s[22:23]
	s_mov_b32 m0, s36
	v_readfirstlane_b32 s36, v159
	global_load_lds_dwordx4 v[164:165], off
	v_lshl_add_u64 v[164:165], v[132:133], 0, s[24:25]
	s_mov_b32 m0, s36
	s_nop 0
	global_load_lds_dwordx4 v[164:165], off
	s_waitcnt vmcnt(12)
	s_barrier
	s_setprio 1
	v_mfma_f32_16x16x32_bf16 v[28:31], v[210:213], v[178:181], v[28:31]
	v_mfma_f32_16x16x32_bf16 v[24:27], v[218:221], v[178:181], v[24:27]
	v_mfma_f32_16x16x32_bf16 v[20:23], v[210:213], v[186:189], v[20:23]
	v_mfma_f32_16x16x32_bf16 v[16:19], v[218:221], v[186:189], v[16:19]
	v_mfma_f32_16x16x32_bf16 v[12:15], v[210:213], v[194:197], v[12:15]
	v_mfma_f32_16x16x32_bf16 v[8:11], v[218:221], v[194:197], v[8:11]
	v_mfma_f32_16x16x32_bf16 v[4:7], v[210:213], v[202:205], v[4:7]
	v_mfma_f32_16x16x32_bf16 v[0:3], v[218:221], v[202:205], v[0:3]
	v_mfma_f32_16x16x32_bf16 v[28:31], v[214:217], v[182:185], v[28:31]
	v_mfma_f32_16x16x32_bf16 v[24:27], v[222:225], v[182:185], v[24:27]
	v_mfma_f32_16x16x32_bf16 v[20:23], v[214:217], v[190:193], v[20:23]
	v_mfma_f32_16x16x32_bf16 v[16:19], v[222:225], v[190:193], v[16:19]
	v_mfma_f32_16x16x32_bf16 v[12:15], v[214:217], v[198:201], v[12:15]
	v_mfma_f32_16x16x32_bf16 v[8:11], v[222:225], v[198:201], v[8:11]
	v_mfma_f32_16x16x32_bf16 v[4:7], v[214:217], v[206:209], v[4:7]
	v_mfma_f32_16x16x32_bf16 v[0:3], v[222:225], v[206:209], v[0:3]
	s_setprio 0
	v_lshl_add_u64 v[130:131], v[130:131], 0, s[62:63]
	s_cmp_lt_u32 s68, s67
	s_barrier
	s_cbranch_scc1 .LBB0_561
	s_lshl_b32 s36, s86, 5
	s_lshl_b32 s37, s86, 8
	s_and_b32 s36, s36, 0x1800
	s_and_b32 s37, s37, 0x700
	s_or_b32 s96, s37, s36
	s_lshl_b32 s36, s96, 6
	s_add_u32 s36, s70, s36
	s_addc_u32 s37, s71, 0
	s_add_i32 s20, s20, -1
	s_lshl_b64 s[68:69], s[20:21], 20
	v_add_u32_e32 v128, v156, v157
	s_add_u32 s68, s36, s68
	v_or_b32_e32 v128, v128, v155
	s_addc_u32 s69, s37, s69
	v_lshl_add_u64 v[156:157], s[68:69], 0, v[128:129]
	v_readfirstlane_b32 s20, v160
	v_lshl_add_u64 v[206:207], v[156:157], 0, s[4:5]
	s_mov_b32 m0, s20
	v_readfirstlane_b32 s20, v159
	ds_read_b128 v[130:133], v161
	ds_read_b128 v[162:165], v161 offset:1024
	ds_read_b128 v[166:169], v161 offset:2048
	ds_read_b128 v[170:173], v161 offset:3072
	ds_read_b128 v[174:177], v152
	ds_read_b128 v[178:181], v152 offset:1024
	ds_read_b128 v[182:185], v151
	ds_read_b128 v[186:189], v151 offset:1024
	ds_read_b128 v[190:193], v150
	ds_read_b128 v[194:197], v150 offset:1024
	ds_read_b128 v[198:201], v149
	ds_read_b128 v[202:205], v149 offset:1024
	global_load_lds_dwordx4 v[206:207], off
	v_lshl_add_u64 v[156:157], v[156:157], 0, s[6:7]
	s_mov_b32 m0, s20
	s_nop 0
	global_load_lds_dwordx4 v[156:157], off
	s_waitcnt vmcnt(10)
	s_barrier
	s_waitcnt lgkmcnt(0)
	s_setprio 1
	s_waitcnt lgkmcnt(0)
	v_mfma_f32_16x16x32_bf16 v[124:127], v[130:133], v[174:177], v[124:127]
	v_mfma_f32_16x16x32_bf16 v[120:123], v[166:169], v[174:177], v[120:123]
	v_mfma_f32_16x16x32_bf16 v[116:119], v[130:133], v[182:185], v[116:119]
	v_mfma_f32_16x16x32_bf16 v[112:115], v[166:169], v[182:185], v[112:115]
	v_mfma_f32_16x16x32_bf16 v[108:111], v[130:133], v[190:193], v[108:111]
	v_mfma_f32_16x16x32_bf16 v[104:107], v[166:169], v[190:193], v[104:107]
	v_mfma_f32_16x16x32_bf16 v[100:103], v[130:133], v[198:201], v[100:103]
	v_mfma_f32_16x16x32_bf16 v[96:99], v[166:169], v[198:201], v[96:99]
	v_mfma_f32_16x16x32_bf16 v[124:127], v[162:165], v[178:181], v[124:127]
	v_mfma_f32_16x16x32_bf16 v[120:123], v[170:173], v[178:181], v[120:123]
	v_mfma_f32_16x16x32_bf16 v[116:119], v[162:165], v[186:189], v[116:119]
	v_mfma_f32_16x16x32_bf16 v[112:115], v[170:173], v[186:189], v[112:115]
	v_mfma_f32_16x16x32_bf16 v[108:111], v[162:165], v[194:197], v[108:111]
	v_mfma_f32_16x16x32_bf16 v[104:107], v[170:173], v[194:197], v[104:107]
	v_mfma_f32_16x16x32_bf16 v[100:103], v[162:165], v[202:205], v[100:103]
	v_mfma_f32_16x16x32_bf16 v[96:99], v[170:173], v[202:205], v[96:99]
	s_setprio 0
	s_barrier
	ds_read_b128 v[206:209], v158
	ds_read_b128 v[210:213], v158 offset:1024
	ds_read_b128 v[214:217], v158 offset:2048
	ds_read_b128 v[156:159], v158 offset:3072
	s_barrier
	s_waitcnt lgkmcnt(0)
	s_setprio 1
	s_waitcnt lgkmcnt(0)
	v_mfma_f32_16x16x32_bf16 v[92:95], v[206:209], v[174:177], v[92:95]
	v_mfma_f32_16x16x32_bf16 v[88:91], v[214:217], v[174:177], v[88:91]
	v_mfma_f32_16x16x32_bf16 v[84:87], v[206:209], v[182:185], v[84:87]
	v_mfma_f32_16x16x32_bf16 v[80:83], v[214:217], v[182:185], v[80:83]
	v_mfma_f32_16x16x32_bf16 v[76:79], v[206:209], v[190:193], v[76:79]
	v_mfma_f32_16x16x32_bf16 v[72:75], v[214:217], v[190:193], v[72:75]
	v_mfma_f32_16x16x32_bf16 v[68:71], v[206:209], v[198:201], v[68:71]
	v_mfma_f32_16x16x32_bf16 v[64:67], v[214:217], v[198:201], v[64:67]
	v_mfma_f32_16x16x32_bf16 v[174:177], v[210:213], v[178:181], v[92:95]
	v_mfma_f32_16x16x32_bf16 v[178:181], v[156:159], v[178:181], v[88:91]
	v_mfma_f32_16x16x32_bf16 v[182:185], v[210:213], v[186:189], v[84:87]
	v_mfma_f32_16x16x32_bf16 v[186:189], v[156:159], v[186:189], v[80:83]
	v_mfma_f32_16x16x32_bf16 v[190:193], v[210:213], v[194:197], v[76:79]
	v_mfma_f32_16x16x32_bf16 v[194:197], v[156:159], v[194:197], v[72:75]
	v_mfma_f32_16x16x32_bf16 v[198:201], v[210:213], v[202:205], v[68:71]
	v_mfma_f32_16x16x32_bf16 v[202:205], v[156:159], v[202:205], v[64:67]
	s_setprio 0
	s_barrier
	s_nop 0
	ds_read_b128 v[64:67], v152 offset:16384
	ds_read_b128 v[68:71], v152 offset:17408
	ds_read_b128 v[72:75], v151 offset:16384
	ds_read_b128 v[76:79], v151 offset:17408
	ds_read_b128 v[80:83], v150 offset:16384
	ds_read_b128 v[84:87], v150 offset:17408
	ds_read_b128 v[88:91], v149 offset:16384
	ds_read_b128 v[92:95], v149 offset:17408
	s_waitcnt vmcnt(4)
	s_barrier
	s_waitcnt lgkmcnt(0)
	s_setprio 1
	s_waitcnt lgkmcnt(0)
	v_mfma_f32_16x16x32_bf16 v[60:63], v[130:133], v[64:67], v[60:63]
	v_mfma_f32_16x16x32_bf16 v[56:59], v[166:169], v[64:67], v[56:59]
	v_mfma_f32_16x16x32_bf16 v[52:55], v[130:133], v[72:75], v[52:55]
	v_mfma_f32_16x16x32_bf16 v[48:51], v[166:169], v[72:75], v[48:51]
	v_mfma_f32_16x16x32_bf16 v[218:221], v[130:133], v[80:83], v[44:47]
	v_mfma_f32_16x16x32_bf16 v[222:225], v[166:169], v[80:83], v[40:43]
	v_mfma_f32_16x16x32_bf16 v[130:133], v[130:133], v[88:91], v[36:39]
	v_mfma_f32_16x16x32_bf16 v[166:169], v[166:169], v[88:91], v[32:35]
	v_mfma_f32_16x16x32_bf16 v[32:35], v[162:165], v[68:71], v[60:63]
	v_mfma_f32_16x16x32_bf16 v[36:39], v[170:173], v[68:71], v[56:59]
	v_mfma_f32_16x16x32_bf16 v[40:43], v[162:165], v[76:79], v[52:55]
	v_mfma_f32_16x16x32_bf16 v[44:47], v[170:173], v[76:79], v[48:51]
	v_mfma_f32_16x16x32_bf16 v[48:51], v[162:165], v[84:87], v[218:221]
	v_mfma_f32_16x16x32_bf16 v[52:55], v[170:173], v[84:87], v[222:225]
	v_mfma_f32_16x16x32_bf16 v[56:59], v[162:165], v[92:95], v[130:133]
	v_mfma_f32_16x16x32_bf16 v[60:63], v[170:173], v[92:95], v[166:169]
	s_setprio 0
	s_setprio 1
	v_mfma_f32_16x16x32_bf16 v[28:31], v[206:209], v[64:67], v[28:31]
	v_mfma_f32_16x16x32_bf16 v[24:27], v[214:217], v[64:67], v[24:27]
	v_mfma_f32_16x16x32_bf16 v[20:23], v[206:209], v[72:75], v[20:23]
	v_mfma_f32_16x16x32_bf16 v[64:67], v[214:217], v[72:75], v[16:19]
	v_mfma_f32_16x16x32_bf16 v[72:75], v[206:209], v[80:83], v[12:15]
	v_mfma_f32_16x16x32_bf16 v[8:11], v[214:217], v[80:83], v[8:11]
	v_mfma_f32_16x16x32_bf16 v[80:83], v[206:209], v[88:91], v[4:7]
	v_mfma_f32_16x16x32_bf16 v[0:3], v[214:217], v[88:91], v[0:3]
	v_mfma_f32_16x16x32_bf16 v[4:7], v[210:213], v[68:71], v[28:31]
	v_mfma_f32_16x16x32_bf16 v[12:15], v[156:159], v[68:71], v[24:27]
	v_mfma_f32_16x16x32_bf16 v[16:19], v[210:213], v[76:79], v[20:23]
	v_mfma_f32_16x16x32_bf16 v[20:23], v[156:159], v[76:79], v[64:67]
	v_mfma_f32_16x16x32_bf16 v[24:27], v[210:213], v[84:87], v[72:75]
	v_mfma_f32_16x16x32_bf16 v[28:31], v[156:159], v[84:87], v[8:11]
	v_mfma_f32_16x16x32_bf16 v[64:67], v[210:213], v[92:95], v[80:83]
	v_mfma_f32_16x16x32_bf16 v[68:71], v[156:159], v[92:95], v[0:3]
	s_setprio 0
	s_barrier
	ds_read_b128 v[8:11], v154
	ds_read_b128 v[0:3], v154 offset:1024
	ds_read_b128 v[76:79], v154 offset:2048
	ds_read_b128 v[72:75], v154 offset:3072
	ds_read_b128 v[130:133], v152 offset:32768
	ds_read_b128 v[154:157], v152 offset:33792
	ds_read_b128 v[158:161], v151 offset:32768
	ds_read_b128 v[162:165], v151 offset:33792
	ds_read_b128 v[166:169], v150 offset:32768
	ds_read_b128 v[170:173], v150 offset:33792
	ds_read_b128 v[206:209], v149 offset:32768
	ds_read_b128 v[210:213], v149 offset:33792
	s_waitcnt vmcnt(2)
	s_barrier
	s_waitcnt lgkmcnt(0)
	s_setprio 1
	s_waitcnt lgkmcnt(0)
	v_mfma_f32_16x16x32_bf16 v[80:83], v[8:11], v[130:133], v[124:127]
	v_mfma_f32_16x16x32_bf16 v[84:87], v[76:79], v[130:133], v[120:123]
	v_mfma_f32_16x16x32_bf16 v[88:91], v[8:11], v[158:161], v[116:119]
	v_mfma_f32_16x16x32_bf16 v[92:95], v[76:79], v[158:161], v[112:115]
	v_mfma_f32_16x16x32_bf16 v[108:111], v[8:11], v[166:169], v[108:111]
	v_mfma_f32_16x16x32_bf16 v[104:107], v[76:79], v[166:169], v[104:107]
	v_mfma_f32_16x16x32_bf16 v[100:103], v[8:11], v[206:209], v[100:103]
	v_mfma_f32_16x16x32_bf16 v[96:99], v[76:79], v[206:209], v[96:99]
	v_mfma_f32_16x16x32_bf16 v[112:115], v[0:3], v[154:157], v[80:83]
	v_mfma_f32_16x16x32_bf16 v[116:119], v[72:75], v[154:157], v[84:87]
	v_mfma_f32_16x16x32_bf16 v[120:123], v[0:3], v[162:165], v[88:91]
	v_mfma_f32_16x16x32_bf16 v[124:127], v[72:75], v[162:165], v[92:95]
	v_mfma_f32_16x16x32_bf16 v[108:111], v[0:3], v[170:173], v[108:111]
	v_mfma_f32_16x16x32_bf16 v[104:107], v[72:75], v[170:173], v[104:107]
	v_mfma_f32_16x16x32_bf16 v[100:103], v[0:3], v[210:213], v[100:103]
	v_mfma_f32_16x16x32_bf16 v[96:99], v[72:75], v[210:213], v[96:99]
	s_setprio 0
	s_barrier
	ds_read_b128 v[88:91], v153
	ds_read_b128 v[80:83], v153 offset:1024
	ds_read_b128 v[92:95], v153 offset:2048
	ds_read_b128 v[84:87], v153 offset:3072
	s_waitcnt vmcnt(0)
	s_barrier
	s_waitcnt lgkmcnt(0)
	s_setprio 1
	s_waitcnt lgkmcnt(0)
	v_mfma_f32_16x16x32_bf16 v[174:177], v[88:91], v[130:133], v[174:177]
	v_mfma_f32_16x16x32_bf16 v[130:133], v[92:95], v[130:133], v[178:181]
	v_mfma_f32_16x16x32_bf16 v[178:181], v[88:91], v[158:161], v[182:185]
	v_mfma_f32_16x16x32_bf16 v[158:161], v[92:95], v[158:161], v[186:189]
	v_mfma_f32_16x16x32_bf16 v[182:185], v[88:91], v[166:169], v[190:193]
	v_mfma_f32_16x16x32_bf16 v[166:169], v[92:95], v[166:169], v[194:197]
	v_mfma_f32_16x16x32_bf16 v[186:189], v[88:91], v[206:209], v[198:201]
	v_mfma_f32_16x16x32_bf16 v[190:193], v[92:95], v[206:209], v[202:205]
	v_mfma_f32_16x16x32_bf16 v[174:177], v[80:83], v[154:157], v[174:177]
	v_mfma_f32_16x16x32_bf16 v[130:133], v[84:87], v[154:157], v[130:133]
	v_mfma_f32_16x16x32_bf16 v[154:157], v[80:83], v[162:165], v[178:181]
	v_mfma_f32_16x16x32_bf16 v[158:161], v[84:87], v[162:165], v[158:161]
	v_mfma_f32_16x16x32_bf16 v[162:165], v[80:83], v[170:173], v[182:185]
	v_mfma_f32_16x16x32_bf16 v[166:169], v[84:87], v[170:173], v[166:169]
	v_mfma_f32_16x16x32_bf16 v[170:173], v[80:83], v[210:213], v[186:189]
	v_mfma_f32_16x16x32_bf16 v[178:181], v[84:87], v[210:213], v[190:193]
	s_setprio 0
	s_barrier
	v_mbcnt_lo_u32_b32 v128, -1, 0
	v_mbcnt_hi_u32_b32 v128, -1, v128
	v_cvt_pk_bf16_f32 v112, v112, v113
	v_cvt_pk_bf16_f32 v113, v114, v115
	v_cvt_pk_bf16_f32 v114, v116, v117
	v_cvt_pk_bf16_f32 v115, v118, v119
	s_lshl_b32 s89, s66, 9
	v_add_u32_e32 v153, s74, v128
	v_ashrrev_i32_e32 v182, 6, v153
	v_and_b32_e32 v183, 15, v128
	v_and_b32_e32 v184, 48, v128
	v_mul_lo_u32 v185, v182, s79
	v_bfe_u32 v186, v128, 3, 3
	v_lshlrev_b32_e32 v128, 4, v128
	v_add_u32_e32 v185, 0x20000, v185
	v_lshrrev_b32_e32 v153, 2, v153
	v_and_b32_e32 v128, 0x70, v128
	v_mul_u32_u24_e32 v183, 0x90, v183
	v_and_b32_e32 v153, 64, v153
	v_add3_u32 v183, v185, v183, v184
	v_or_b32_e32 v184, v185, v128
	v_or3_b32 v153, s96, v153, v186
	v_mad_u32_u24 v184, v186, s81, v184
	ds_write_b128 v183, v[112:115]
	v_cvt_pk_bf16_f32 v112, v174, v175
	v_cvt_pk_bf16_f32 v113, v176, v177
	v_cvt_pk_bf16_f32 v114, v130, v131
	v_cvt_pk_bf16_f32 v115, v132, v133
	ds_write_b128 v183, v[112:115] offset:64
	v_lshlrev_b32_e32 v182, 7, v182
	ds_read_b128 v[112:115], v184
	v_lshlrev_b32_e32 v116, 12, v153
	v_and_or_b32 v116, v182, s82, v116
	v_or3_b32 v128, v116, s89, v128
	ds_read_b128 v[116:119], v184 offset:1152
	v_lshl_add_u64 v[130:131], s[0:1], 0, v[128:129]
	s_mov_b32 s20, 0x8000
	s_waitcnt lgkmcnt(0)
	global_store_dwordx4 v128, v[112:115], s[0:1]
	v_cvt_pk_bf16_f32 v108, v108, v109
	v_cvt_pk_bf16_f32 v109, v110, v111
	v_cvt_pk_bf16_f32 v110, v104, v105
	v_cvt_pk_bf16_f32 v111, v106, v107
	v_cvt_pk_bf16_f32 v104, v162, v163
	s_nop 1
	v_add_co_u32_e32 v112, vcc, s20, v130
	v_cvt_pk_bf16_f32 v114, v124, v125
	v_cvt_pk_bf16_f32 v115, v126, v127
	v_cvt_pk_bf16_f32 v105, v164, v165
	v_cvt_pk_bf16_f32 v106, v166, v167
	s_nop 1
	v_addc_co_u32_e32 v113, vcc, 0, v131, vcc
	global_store_dwordx4 v[112:113], v[116:119], off
	v_cvt_pk_bf16_f32 v112, v120, v121
	v_cvt_pk_bf16_f32 v113, v122, v123
	ds_write_b128 v183, v[112:115]
	v_cvt_pk_bf16_f32 v112, v154, v155
	v_cvt_pk_bf16_f32 v113, v156, v157
	v_cvt_pk_bf16_f32 v114, v158, v159
	v_cvt_pk_bf16_f32 v115, v160, v161
	ds_write_b128 v183, v[112:115] offset:64
	ds_read_b128 v[112:115], v184
	ds_read_b128 v[116:119], v184 offset:1152
	v_add_co_u32_e32 v120, vcc, s76, v130
	ds_write_b128 v183, v[108:111]
	v_cvt_pk_bf16_f32 v107, v168, v169
	ds_write_b128 v183, v[104:107] offset:64
	v_addc_co_u32_e32 v121, vcc, 0, v131, vcc
	ds_read_b128 v[104:107], v184
	ds_read_b128 v[108:111], v184 offset:1152
	s_waitcnt lgkmcnt(0)
	global_store_dwordx4 v[120:121], v[112:115], off
	v_cvt_pk_bf16_f32 v100, v100, v101
	v_cvt_pk_bf16_f32 v101, v102, v103
	v_cvt_pk_bf16_f32 v102, v96, v97
	v_cvt_pk_bf16_f32 v103, v98, v99
	ds_write_b128 v183, v[100:103]
	s_nop 0
	v_add_co_u32_e32 v112, vcc, s77, v130
	v_cvt_pk_bf16_f32 v96, v170, v171
	v_cvt_pk_bf16_f32 v97, v172, v173
	v_cvt_pk_bf16_f32 v98, v178, v179
	v_cvt_pk_bf16_f32 v99, v180, v181
	s_nop 1
	v_addc_co_u32_e32 v113, vcc, 0, v131, vcc
	global_store_dwordx4 v[112:113], v[116:119], off
	v_add_co_u32_e32 v112, vcc, s80, v130
	ds_write_b128 v183, v[96:99] offset:64
	s_nop 0
	v_addc_co_u32_e32 v113, vcc, 0, v131, vcc
	ds_read_b128 v[96:99], v184
	ds_read_b128 v[100:103], v184 offset:1152
	global_store_dwordx4 v[112:113], v[104:107], off
	s_nop 1
	v_add_co_u32_e32 v104, vcc, s83, v130
	s_nop 1
	v_addc_co_u32_e32 v105, vcc, 0, v131, vcc
	global_store_dwordx4 v[104:105], v[108:111], off
	v_add_co_u32_e32 v104, vcc, s85, v130
	s_nop 1
	v_addc_co_u32_e32 v105, vcc, 0, v131, vcc
	s_waitcnt lgkmcnt(0)
	global_store_dwordx4 v[104:105], v[96:99], off
	s_nop 1
	v_add_co_u32_e32 v96, vcc, s87, v130
	s_nop 1
	v_addc_co_u32_e32 v97, vcc, 0, v131, vcc
	global_store_dwordx4 v[96:97], v[100:103], off
	ds_read_b128 v[96:99], v152 offset:49152
	ds_read_b128 v[100:103], v152 offset:50176
	ds_read_b128 v[104:107], v151 offset:49152
	ds_read_b128 v[108:111], v151 offset:50176
	ds_read_b128 v[112:115], v150 offset:49152
	ds_read_b128 v[116:119], v150 offset:50176
	ds_read_b128 v[120:123], v149 offset:49152
	ds_read_b128 v[124:127], v149 offset:50176
	s_barrier
	s_waitcnt lgkmcnt(0)
	s_setprio 1
	s_waitcnt lgkmcnt(0)
	v_mfma_f32_16x16x32_bf16 v[32:35], v[8:11], v[96:99], v[32:35]
	v_mfma_f32_16x16x32_bf16 v[36:39], v[76:79], v[96:99], v[36:39]
	v_mfma_f32_16x16x32_bf16 v[40:43], v[8:11], v[104:107], v[40:43]
	v_mfma_f32_16x16x32_bf16 v[130:133], v[76:79], v[104:107], v[44:47]
	v_mfma_f32_16x16x32_bf16 v[150:153], v[8:11], v[112:115], v[48:51]
	v_mfma_f32_16x16x32_bf16 v[52:55], v[76:79], v[112:115], v[52:55]
	v_mfma_f32_16x16x32_bf16 v[8:11], v[8:11], v[120:123], v[56:59]
	v_mfma_f32_16x16x32_bf16 v[60:63], v[76:79], v[120:123], v[60:63]
	v_mfma_f32_16x16x32_bf16 v[56:59], v[0:3], v[100:103], v[32:35]
	v_mfma_f32_16x16x32_bf16 v[48:51], v[72:75], v[100:103], v[36:39]
	v_mfma_f32_16x16x32_bf16 v[44:47], v[0:3], v[108:111], v[40:43]
	v_mfma_f32_16x16x32_bf16 v[40:43], v[72:75], v[108:111], v[130:133]
	v_mfma_f32_16x16x32_bf16 v[36:39], v[0:3], v[116:119], v[150:153]
	v_mfma_f32_16x16x32_bf16 v[32:35], v[72:75], v[116:119], v[52:55]
	v_mfma_f32_16x16x32_bf16 v[8:11], v[0:3], v[124:127], v[8:11]
	v_mfma_f32_16x16x32_bf16 v[0:3], v[72:75], v[124:127], v[60:63]
	s_setprio 0
	s_setprio 1
	v_mfma_f32_16x16x32_bf16 v[4:7], v[88:91], v[96:99], v[4:7]
	v_mfma_f32_16x16x32_bf16 v[12:15], v[92:95], v[96:99], v[12:15]
	v_mfma_f32_16x16x32_bf16 v[16:19], v[88:91], v[104:107], v[16:19]
	v_mfma_f32_16x16x32_bf16 v[20:23], v[92:95], v[104:107], v[20:23]
	v_mfma_f32_16x16x32_bf16 v[72:75], v[88:91], v[112:115], v[24:27]
	v_mfma_f32_16x16x32_bf16 v[76:79], v[92:95], v[112:115], v[28:31]
	v_mfma_f32_16x16x32_bf16 v[64:67], v[88:91], v[120:123], v[64:67]
	v_mfma_f32_16x16x32_bf16 v[68:71], v[92:95], v[120:123], v[68:71]
	v_mfma_f32_16x16x32_bf16 v[60:63], v[80:83], v[100:103], v[4:7]
	v_mfma_f32_16x16x32_bf16 v[52:55], v[84:87], v[100:103], v[12:15]
	v_mfma_f32_16x16x32_bf16 v[28:31], v[80:83], v[108:111], v[16:19]
	v_mfma_f32_16x16x32_bf16 v[24:27], v[84:87], v[108:111], v[20:23]
	v_mfma_f32_16x16x32_bf16 v[20:23], v[80:83], v[116:119], v[72:75]
	v_mfma_f32_16x16x32_bf16 v[16:19], v[84:87], v[116:119], v[76:79]
	v_mfma_f32_16x16x32_bf16 v[12:15], v[80:83], v[124:127], v[64:67]
	v_mfma_f32_16x16x32_bf16 v[4:7], v[84:87], v[124:127], v[68:71]
	s_setprio 0
	v_cmp_gt_u32_e32 vcc, s88, v135
	s_barrier
	s_and_saveexec_b64 s[66:67], vcc
	s_cbranch_execz .LBB0_564
	s_barrier
